# cache-policy split test: x/y row loads non-temporal, final out stores back to the default policy (writes absorbed by the memory-side cache)
# speedup vs baseline: 1.0073x; 1.0073x over previous
; __global__ void __launch_bounds__(NWAVES * 64, 2) mk_fwd(Args args) {
;     ...
;         const int per = (ML + F.NGW - 1) / F.NGW, per2 = (per + 1) & ~1, rbeg = F.gw * per2;
;         int rcur = -1; f32x4 PA[8];
;         for (int row0 = rbeg; row0 < rbeg + per2 && row0 < ML; row0 += 2) {
;             f32x4 v[2][8]; u32x2 yw[2][8];
; #pragma unroll
;             for (int q = 0; q < 2; ++q) { const int row = row0 + q; load_row_f32(args.out + (size_t)row * DM, F.lane, v[q]);
;                 const bf16_t* yr = Y + (size_t)row * DM;
; #pragma unroll
;                 for (int j = 0; j < 8; ++j) yw[q][j] = *(const u32x2*)(yr + 4 * F.lane + 256 * j); }
; #pragma unroll
;             for (int q = 0; q < 2; ++q) { const int row = row0 + q; const int r = row / SEQ;
;                 if (r != rcur) { const float* m1 = mod + (size_t)(9 + r) * 6144; rcur = r;
; #pragma unroll
;                     for (int j = 0; j < 8; ++j) { const int col = 4 * F.lane + 256 * j; PA[j] = *(const f32x4*)(m1 + 2 * DM + col) * *(const f32x4*)(post_norm + DM + col); } }
.LBB0_1288:
	s_cmp_gt_i32 s86, 11
	s_cselect_b64 s[2:3], -1, 0
	s_xor_b64 s[0:1], s[0:1], -1
	s_or_b64 s[0:1], s[2:3], s[0:1]
	s_and_b64 vcc, exec, s[0:1]
	s_cbranch_vccnz .LBB0_1296
	s_cmpk_lg_i32 s63, 0x100
	s_cbranch_scc1 .Lp11_generic
	v_and_b32_e32 v194, 63, v198
	v_lshlrev_b32_e32 v192, 4, v194
	v_add_u32_e32 v193, 0x1000, v192
	v_lshlrev_b32_e32 v194, 3, v194
	v_mov_b32_e32 v195, 0x358637bd
	s_lshr_b32 s0, s33, 8
	s_mul_i32 s1, s0, 0x6000
	s_add_u32 s8, s84, s1
	s_addc_u32 s9, s85, 0
	s_add_u32 s8, s8, 0x4000
	s_addc_u32 s9, s9, 0
	s_add_u32 s10, s8, 0x36000
	s_addc_u32 s11, s9, 0
	s_add_u32 s12, s82, 0x2000
	s_addc_u32 s13, s83, 0
	s_lshl_b32 s0, s33, 16
	s_add_u32 s14, s68, s0
	s_addc_u32 s15, s69, 0
	s_add_u32 s18, s94, s0
	s_addc_u32 s19, s95, 0
	s_lshl_b32 s0, s33, 15
	s_add_u32 s16, s84, s0
	s_addc_u32 s17, s85, 0
	s_add_u32 s22, s16, 0x8800000
	s_addc_u32 s23, s17, 0
	s_add_u32 s16, s16, 0x11800000
	s_addc_u32 s17, s17, 0
	global_load_dwordx4 v[128:131], v192, s[8:9] offset:0
	global_load_dwordx4 v[132:135], v192, s[8:9] offset:1024
	global_load_dwordx4 v[136:139], v192, s[8:9] offset:2048
	global_load_dwordx4 v[140:143], v192, s[8:9] offset:3072
	global_load_dwordx4 v[144:147], v193, s[8:9] offset:0
	global_load_dwordx4 v[148:151], v193, s[8:9] offset:1024
	global_load_dwordx4 v[152:155], v193, s[8:9] offset:2048
	global_load_dwordx4 v[156:159], v193, s[8:9] offset:3072
	global_load_dwordx4 v[32:35], v192, s[82:83] offset:0
	global_load_dwordx4 v[36:39], v192, s[82:83] offset:1024
	global_load_dwordx4 v[40:43], v192, s[82:83] offset:2048
	global_load_dwordx4 v[44:47], v192, s[82:83] offset:3072
	global_load_dwordx4 v[48:51], v193, s[82:83] offset:0
	global_load_dwordx4 v[52:55], v193, s[82:83] offset:1024
	global_load_dwordx4 v[56:59], v193, s[82:83] offset:2048
	global_load_dwordx4 v[60:63], v193, s[82:83] offset:3072
	global_load_dwordx4 v[160:163], v192, s[10:11] offset:0
	global_load_dwordx4 v[164:167], v192, s[10:11] offset:1024
	global_load_dwordx4 v[168:171], v192, s[10:11] offset:2048
	global_load_dwordx4 v[172:175], v192, s[10:11] offset:3072
	global_load_dwordx4 v[176:179], v193, s[10:11] offset:0
	global_load_dwordx4 v[180:183], v193, s[10:11] offset:1024
	global_load_dwordx4 v[184:187], v193, s[10:11] offset:2048
	global_load_dwordx4 v[188:191], v193, s[10:11] offset:3072
	global_load_dwordx4 v[96:99], v192, s[12:13] offset:0
	global_load_dwordx4 v[100:103], v192, s[12:13] offset:1024
	global_load_dwordx4 v[104:107], v192, s[12:13] offset:2048
	global_load_dwordx4 v[108:111], v192, s[12:13] offset:3072
	global_load_dwordx4 v[112:115], v193, s[12:13] offset:0
	global_load_dwordx4 v[116:119], v193, s[12:13] offset:1024
	global_load_dwordx4 v[120:123], v193, s[12:13] offset:2048
	global_load_dwordx4 v[124:127], v193, s[12:13] offset:3072
	s_waitcnt vmcnt(0)
	v_mul_f32_e32 v128, v128, v32
	v_mul_f32_e32 v129, v129, v33
	v_mul_f32_e32 v130, v130, v34
	v_mul_f32_e32 v131, v131, v35
	v_mul_f32_e32 v132, v132, v36
	v_mul_f32_e32 v133, v133, v37
	v_mul_f32_e32 v134, v134, v38
	v_mul_f32_e32 v135, v135, v39
	v_mul_f32_e32 v136, v136, v40
	v_mul_f32_e32 v137, v137, v41
	v_mul_f32_e32 v138, v138, v42
	v_mul_f32_e32 v139, v139, v43
	v_mul_f32_e32 v140, v140, v44
	v_mul_f32_e32 v141, v141, v45
	v_mul_f32_e32 v142, v142, v46
	v_mul_f32_e32 v143, v143, v47
	v_mul_f32_e32 v144, v144, v48
	v_mul_f32_e32 v145, v145, v49
	v_mul_f32_e32 v146, v146, v50
	v_mul_f32_e32 v147, v147, v51
	v_mul_f32_e32 v148, v148, v52
	v_mul_f32_e32 v149, v149, v53
	v_mul_f32_e32 v150, v150, v54
	v_mul_f32_e32 v151, v151, v55
	v_mul_f32_e32 v152, v152, v56
	v_mul_f32_e32 v153, v153, v57
	v_mul_f32_e32 v154, v154, v58
	v_mul_f32_e32 v155, v155, v59
	v_mul_f32_e32 v156, v156, v60
	v_mul_f32_e32 v157, v157, v61
	v_mul_f32_e32 v158, v158, v62
	v_mul_f32_e32 v159, v159, v63
	v_mul_f32_e32 v160, v160, v96
	v_mul_f32_e32 v161, v161, v97
	v_mul_f32_e32 v162, v162, v98
	v_mul_f32_e32 v163, v163, v99
	v_mul_f32_e32 v164, v164, v100
	v_mul_f32_e32 v165, v165, v101
	v_mul_f32_e32 v166, v166, v102
	v_mul_f32_e32 v167, v167, v103
	v_mul_f32_e32 v168, v168, v104
	v_mul_f32_e32 v169, v169, v105
	v_mul_f32_e32 v170, v170, v106
	v_mul_f32_e32 v171, v171, v107
	v_mul_f32_e32 v172, v172, v108
	v_mul_f32_e32 v173, v173, v109
	v_mul_f32_e32 v174, v174, v110
	v_mul_f32_e32 v175, v175, v111
	v_mul_f32_e32 v176, v176, v112
	v_mul_f32_e32 v177, v177, v113
	v_mul_f32_e32 v178, v178, v114
	v_mul_f32_e32 v179, v179, v115
	v_mul_f32_e32 v180, v180, v116
	v_mul_f32_e32 v181, v181, v117
	v_mul_f32_e32 v182, v182, v118
	v_mul_f32_e32 v183, v183, v119
	v_mul_f32_e32 v184, v184, v120
	v_mul_f32_e32 v185, v185, v121
	v_mul_f32_e32 v186, v186, v122
	v_mul_f32_e32 v187, v187, v123
	v_mul_f32_e32 v188, v188, v124
	v_mul_f32_e32 v189, v189, v125
	v_mul_f32_e32 v190, v190, v126
	v_mul_f32_e32 v191, v191, v127
	global_load_dwordx4 v[0:3], v192, s[14:15] offset:0 nt
	global_load_dwordx4 v[4:7], v192, s[14:15] offset:1024 nt
	global_load_dwordx4 v[8:11], v192, s[14:15] offset:2048 nt
	global_load_dwordx4 v[12:15], v192, s[14:15] offset:3072 nt
	global_load_dwordx4 v[16:19], v193, s[14:15] offset:0 nt
	global_load_dwordx4 v[20:23], v193, s[14:15] offset:1024 nt
	global_load_dwordx4 v[24:27], v193, s[14:15] offset:2048 nt
	global_load_dwordx4 v[28:31], v193, s[14:15] offset:3072 nt
	global_load_dwordx2 v[64:65], v194, s[16:17] offset:0 nt
	global_load_dwordx2 v[66:67], v194, s[16:17] offset:512 nt
	global_load_dwordx2 v[68:69], v194, s[16:17] offset:1024 nt
	global_load_dwordx2 v[70:71], v194, s[16:17] offset:1536 nt
	global_load_dwordx2 v[72:73], v194, s[16:17] offset:2048 nt
; __device__ __forceinline__ float bf_lo(unsigned w) { return __uint_as_float(w << 16); }
; __device__ __forceinline__ float bf_hi(unsigned w) { return __uint_as_float(w & 0xffff0000u); }
; __global__ void __launch_bounds__(NWAVES * 64, 2) mk_fwd(Args args) {
;     ...
;             for (int q = 0; q < 2; ++q) { const int row = row0 + q; load_row_f32(args.out + (size_t)row * DM, F.lane, v[q]);
;                 const bf16_t* yr = Y + (size_t)row * DM;
; #pragma unroll
;                 for (int j = 0; j < 8; ++j) yw[q][j] = *(const u32x2*)(yr + 4 * F.lane + 256 * j); }
; #pragma unroll
;             for (int q = 0; q < 2; ++q) { const int row = row0 + q; const int r = row / SEQ;
;                 if (r != rcur) { const float* m1 = mod + (size_t)(9 + r) * 6144; rcur = r;
; #pragma unroll
;                     for (int j = 0; j < 8; ++j) { const int col = 4 * F.lane + 256 * j; PA[j] = *(const f32x4*)(m1 + 2 * DM + col) * *(const f32x4*)(post_norm + DM + col); } }
;                 float sy = 0.f;
; #pragma unroll
;                 for (int j = 0; j < 8; ++j) { const float a = bf_lo(yw[q][j].x), b = bf_hi(yw[q][j].x), c2 = bf_lo(yw[q][j].y), d = bf_hi(yw[q][j].y); sy += (a * a + b * b) + (c2 * c2 + d * d); }
	global_load_dwordx2 v[74:75], v194, s[16:17] offset:2560 nt
	global_load_dwordx2 v[76:77], v194, s[16:17] offset:3072 nt
	global_load_dwordx2 v[78:79], v194, s[16:17] offset:3584 nt
	global_load_dwordx2 v[96:97], v194, s[22:23] offset:0 nt
	global_load_dwordx2 v[98:99], v194, s[22:23] offset:512 nt
	global_load_dwordx2 v[100:101], v194, s[22:23] offset:1024 nt
	global_load_dwordx2 v[102:103], v194, s[22:23] offset:1536 nt
	global_load_dwordx2 v[104:105], v194, s[22:23] offset:2048 nt
	global_load_dwordx2 v[106:107], v194, s[22:23] offset:2560 nt
	global_load_dwordx2 v[108:109], v194, s[22:23] offset:3072 nt
	global_load_dwordx2 v[110:111], v194, s[22:23] offset:3584 nt
	s_add_u32 s14, s14, 0x2000
	s_addc_u32 s15, s15, 0
	s_add_u32 s16, s16, 0x1000
	s_addc_u32 s17, s17, 0
	s_add_u32 s22, s22, 0x1000
	s_addc_u32 s23, s23, 0
	global_load_dwordx4 v[32:35], v192, s[14:15] offset:0 nt
	global_load_dwordx4 v[36:39], v192, s[14:15] offset:1024 nt
	global_load_dwordx4 v[40:43], v192, s[14:15] offset:2048 nt
	global_load_dwordx4 v[44:47], v192, s[14:15] offset:3072 nt
	global_load_dwordx4 v[48:51], v193, s[14:15] offset:0 nt
	global_load_dwordx4 v[52:55], v193, s[14:15] offset:1024 nt
	global_load_dwordx4 v[56:59], v193, s[14:15] offset:2048 nt
	global_load_dwordx4 v[60:63], v193, s[14:15] offset:3072 nt
	global_load_dwordx2 v[80:81], v194, s[16:17] offset:0 nt
	global_load_dwordx2 v[82:83], v194, s[16:17] offset:512 nt
	global_load_dwordx2 v[84:85], v194, s[16:17] offset:1024 nt
	global_load_dwordx2 v[86:87], v194, s[16:17] offset:1536 nt
	global_load_dwordx2 v[88:89], v194, s[16:17] offset:2048 nt
	global_load_dwordx2 v[90:91], v194, s[16:17] offset:2560 nt
	global_load_dwordx2 v[92:93], v194, s[16:17] offset:3072 nt
	global_load_dwordx2 v[94:95], v194, s[16:17] offset:3584 nt
	global_load_dwordx2 v[112:113], v194, s[22:23] offset:0 nt
	global_load_dwordx2 v[114:115], v194, s[22:23] offset:512 nt
	global_load_dwordx2 v[116:117], v194, s[22:23] offset:1024 nt
	global_load_dwordx2 v[118:119], v194, s[22:23] offset:1536 nt
	global_load_dwordx2 v[120:121], v194, s[22:23] offset:2048 nt
	global_load_dwordx2 v[122:123], v194, s[22:23] offset:2560 nt
	global_load_dwordx2 v[124:125], v194, s[22:23] offset:3072 nt
	global_load_dwordx2 v[126:127], v194, s[22:23] offset:3584 nt
	s_add_u32 s14, s14, 0x2000
	s_addc_u32 s15, s15, 0
	s_add_u32 s16, s16, 0x1000
	s_addc_u32 s17, s17, 0
	s_add_u32 s22, s22, 0x1000
	s_addc_u32 s23, s23, 0
	s_waitcnt vmcnt(24)
	v_lshlrev_b32_e32 v200, 16, v64
	v_and_b32_e32 v201, 0xffff0000, v64
	v_lshlrev_b32_e32 v202, 16, v65
	v_and_b32_e32 v203, 0xffff0000, v65
	v_mul_f32_e32 v208, v200, v200
	v_mul_f32_e32 v209, v201, v201
	v_fmac_f32_e32 v208, v202, v202
	v_fmac_f32_e32 v209, v203, v203
	v_lshlrev_b32_e32 v204, 16, v96
	v_and_b32_e32 v205, 0xffff0000, v96
	v_lshlrev_b32_e32 v206, 16, v97
	v_and_b32_e32 v207, 0xffff0000, v97
	v_mul_f32_e32 v210, v204, v204
	v_mul_f32_e32 v211, v205, v205
	v_fmac_f32_e32 v210, v206, v206
	v_fmac_f32_e32 v211, v207, v207
	v_lshlrev_b32_e32 v200, 16, v66
	v_and_b32_e32 v201, 0xffff0000, v66
	v_lshlrev_b32_e32 v202, 16, v67
	v_and_b32_e32 v203, 0xffff0000, v67
	v_fmac_f32_e32 v208, v200, v200
	v_fmac_f32_e32 v209, v201, v201
	v_fmac_f32_e32 v208, v202, v202
	v_fmac_f32_e32 v209, v203, v203
	v_lshlrev_b32_e32 v204, 16, v98
	v_and_b32_e32 v205, 0xffff0000, v98
	v_lshlrev_b32_e32 v206, 16, v99
	v_and_b32_e32 v207, 0xffff0000, v99
	v_fmac_f32_e32 v210, v204, v204
	v_fmac_f32_e32 v211, v205, v205
	v_fmac_f32_e32 v210, v206, v206
	v_fmac_f32_e32 v211, v207, v207
	v_lshlrev_b32_e32 v200, 16, v68
	v_and_b32_e32 v201, 0xffff0000, v68
	v_lshlrev_b32_e32 v202, 16, v69
	v_and_b32_e32 v203, 0xffff0000, v69
	v_fmac_f32_e32 v208, v200, v200
	v_fmac_f32_e32 v209, v201, v201
	v_fmac_f32_e32 v208, v202, v202
	v_fmac_f32_e32 v209, v203, v203
	v_lshlrev_b32_e32 v204, 16, v100
	v_and_b32_e32 v205, 0xffff0000, v100
	v_lshlrev_b32_e32 v206, 16, v101
	v_and_b32_e32 v207, 0xffff0000, v101
	v_fmac_f32_e32 v210, v204, v204
	v_fmac_f32_e32 v211, v205, v205
	v_fmac_f32_e32 v210, v206, v206
	v_fmac_f32_e32 v211, v207, v207
	v_lshlrev_b32_e32 v200, 16, v70
	v_and_b32_e32 v201, 0xffff0000, v70
	v_lshlrev_b32_e32 v202, 16, v71
	v_and_b32_e32 v203, 0xffff0000, v71
	v_fmac_f32_e32 v208, v200, v200
	v_fmac_f32_e32 v209, v201, v201
	v_fmac_f32_e32 v208, v202, v202
	v_fmac_f32_e32 v209, v203, v203
	v_lshlrev_b32_e32 v204, 16, v102
	v_and_b32_e32 v205, 0xffff0000, v102
	v_lshlrev_b32_e32 v206, 16, v103
	v_and_b32_e32 v207, 0xffff0000, v103
	v_fmac_f32_e32 v210, v204, v204
	v_fmac_f32_e32 v211, v205, v205
	v_fmac_f32_e32 v210, v206, v206
	v_fmac_f32_e32 v211, v207, v207
	v_lshlrev_b32_e32 v200, 16, v72
	v_and_b32_e32 v201, 0xffff0000, v72
	v_lshlrev_b32_e32 v202, 16, v73
	v_and_b32_e32 v203, 0xffff0000, v73
	v_fmac_f32_e32 v208, v200, v200
	v_fmac_f32_e32 v209, v201, v201
	v_fmac_f32_e32 v208, v202, v202
	v_fmac_f32_e32 v209, v203, v203
	v_lshlrev_b32_e32 v204, 16, v104
	v_and_b32_e32 v205, 0xffff0000, v104
	v_lshlrev_b32_e32 v206, 16, v105
	v_and_b32_e32 v207, 0xffff0000, v105
	v_fmac_f32_e32 v210, v204, v204
	v_fmac_f32_e32 v211, v205, v205
	v_fmac_f32_e32 v210, v206, v206
	v_fmac_f32_e32 v211, v207, v207
	v_lshlrev_b32_e32 v200, 16, v74
	v_and_b32_e32 v201, 0xffff0000, v74
	v_lshlrev_b32_e32 v202, 16, v75
	v_and_b32_e32 v203, 0xffff0000, v75
	v_fmac_f32_e32 v208, v200, v200
	v_fmac_f32_e32 v209, v201, v201
	v_fmac_f32_e32 v208, v202, v202
	v_fmac_f32_e32 v209, v203, v203
	v_lshlrev_b32_e32 v204, 16, v106
	v_and_b32_e32 v205, 0xffff0000, v106
	v_lshlrev_b32_e32 v206, 16, v107
	v_and_b32_e32 v207, 0xffff0000, v107
	v_fmac_f32_e32 v210, v204, v204
; __device__ __forceinline__ float bf_lo(unsigned w) { return __uint_as_float(w << 16); }
; __device__ __forceinline__ float bf_hi(unsigned w) { return __uint_as_float(w & 0xffff0000u); }
; __global__ void __launch_bounds__(NWAVES * 64, 2) mk_fwd(Args args) {
;     ...
;                 float sy = 0.f;
; #pragma unroll
;                 for (int j = 0; j < 8; ++j) { const float a = bf_lo(yw[q][j].x), b = bf_hi(yw[q][j].x), c2 = bf_lo(yw[q][j].y), d = bf_hi(yw[q][j].y); sy += (a * a + b * b) + (c2 * c2 + d * d); }
;                 const float rsy = __builtin_amdgcn_rsqf(wave_sum(sy) * (1.f / DM) + EPS);
; #pragma unroll
;                 for (int j = 0; j < 8; ++j) { const int col = 4 * F.lane + 256 * j;
;                     const f32x4 y4 = (f32x4){bf_lo(yw[q][j].x), bf_hi(yw[q][j].x), bf_lo(yw[q][j].y), bf_hi(yw[q][j].y)};
;                     *(f32x4*)(args.out + (size_t)row * DM + col) = v[q][j] + PA[j] * (y4 * rsy); }
	v_fmac_f32_e32 v211, v205, v205
	v_fmac_f32_e32 v210, v206, v206
	v_fmac_f32_e32 v211, v207, v207
	v_lshlrev_b32_e32 v200, 16, v76
	v_and_b32_e32 v201, 0xffff0000, v76
	v_lshlrev_b32_e32 v202, 16, v77
	v_and_b32_e32 v203, 0xffff0000, v77
	v_fmac_f32_e32 v208, v200, v200
	v_fmac_f32_e32 v209, v201, v201
	v_fmac_f32_e32 v208, v202, v202
	v_fmac_f32_e32 v209, v203, v203
	v_lshlrev_b32_e32 v204, 16, v108
	v_and_b32_e32 v205, 0xffff0000, v108
	v_lshlrev_b32_e32 v206, 16, v109
	v_and_b32_e32 v207, 0xffff0000, v109
	v_fmac_f32_e32 v210, v204, v204
	v_fmac_f32_e32 v211, v205, v205
	v_fmac_f32_e32 v210, v206, v206
	v_fmac_f32_e32 v211, v207, v207
	v_lshlrev_b32_e32 v200, 16, v78
	v_and_b32_e32 v201, 0xffff0000, v78
	v_lshlrev_b32_e32 v202, 16, v79
	v_and_b32_e32 v203, 0xffff0000, v79
	v_fmac_f32_e32 v208, v200, v200
	v_fmac_f32_e32 v209, v201, v201
	v_fmac_f32_e32 v208, v202, v202
	v_fmac_f32_e32 v209, v203, v203
	v_lshlrev_b32_e32 v204, 16, v110
	v_and_b32_e32 v205, 0xffff0000, v110
	v_lshlrev_b32_e32 v206, 16, v111
	v_and_b32_e32 v207, 0xffff0000, v111
	v_fmac_f32_e32 v210, v204, v204
	v_fmac_f32_e32 v211, v205, v205
	v_fmac_f32_e32 v210, v206, v206
	v_fmac_f32_e32 v211, v207, v207
	v_add_f32_e32 v208, v208, v209
	v_add_f32_e32 v210, v210, v211
	s_nop 0
	v_add_f32_dpp v212, v208, v208 quad_perm:[1,0,3,2] row_mask:0xf bank_mask:0xf
	v_add_f32_dpp v213, v210, v210 quad_perm:[1,0,3,2] row_mask:0xf bank_mask:0xf
	s_nop 0
	v_add_f32_dpp v212, v212, v212 quad_perm:[2,3,0,1] row_mask:0xf bank_mask:0xf
	v_add_f32_dpp v213, v213, v213 quad_perm:[2,3,0,1] row_mask:0xf bank_mask:0xf
	s_nop 0
	v_add_f32_dpp v212, v212, v212 row_half_mirror row_mask:0xf bank_mask:0xf
	v_add_f32_dpp v213, v213, v213 row_half_mirror row_mask:0xf bank_mask:0xf
	s_nop 0
	v_add_f32_dpp v212, v212, v212 row_mirror row_mask:0xf bank_mask:0xf
	v_add_f32_dpp v213, v213, v213 row_mirror row_mask:0xf bank_mask:0xf
	s_nop 0
	v_readlane_b32 s4, v212, 0
	v_readlane_b32 s5, v212, 16
	v_readlane_b32 s6, v212, 32
	v_readlane_b32 s7, v212, 48
	v_readlane_b32 s24, v213, 0
	v_readlane_b32 s25, v213, 16
	v_readlane_b32 s26, v213, 32
	v_readlane_b32 s27, v213, 48
	s_nop 1
	v_mov_b32_e32 v214, s4
	v_mov_b32_e32 v215, s24
	v_add_f32_e32 v214, s5, v214
	v_add_f32_e32 v215, s25, v215
	v_add_f32_e32 v214, s6, v214
	v_add_f32_e32 v215, s26, v215
	v_add_f32_e32 v214, s7, v214
	v_add_f32_e32 v215, s27, v215
	v_fmamk_f32 v214, v214, 0x3a000000, v195
	v_fmamk_f32 v215, v215, 0x3a000000, v195
	v_rsq_f32_e32 v214, v214
	v_rsq_f32_e32 v215, v215
	s_nop 0
	v_lshlrev_b32_e32 v200, 16, v64
	v_and_b32_e32 v201, 0xffff0000, v64
	v_lshlrev_b32_e32 v202, 16, v65
	v_and_b32_e32 v203, 0xffff0000, v65
	v_lshlrev_b32_e32 v204, 16, v96
	v_and_b32_e32 v205, 0xffff0000, v96
	v_lshlrev_b32_e32 v206, 16, v97
	v_and_b32_e32 v207, 0xffff0000, v97
	v_mul_f32_e32 v200, v214, v200
	v_mul_f32_e32 v201, v214, v201
	v_mul_f32_e32 v202, v214, v202
	v_mul_f32_e32 v203, v214, v203
	v_mul_f32_e32 v204, v215, v204
	v_mul_f32_e32 v205, v215, v205
	v_mul_f32_e32 v206, v215, v206
	v_mul_f32_e32 v207, v215, v207
	v_fmac_f32_e32 v0, v128, v200
	v_fmac_f32_e32 v1, v129, v201
	v_fmac_f32_e32 v2, v130, v202
	v_fmac_f32_e32 v3, v131, v203
	v_fmac_f32_e32 v0, v160, v204
	v_fmac_f32_e32 v1, v161, v205
	v_fmac_f32_e32 v2, v162, v206
	v_fmac_f32_e32 v3, v163, v207
	global_store_dwordx4 v192, v[0:3], s[18:19] offset:0
	v_lshlrev_b32_e32 v200, 16, v66
	v_and_b32_e32 v201, 0xffff0000, v66
	v_lshlrev_b32_e32 v202, 16, v67
	v_and_b32_e32 v203, 0xffff0000, v67
	v_lshlrev_b32_e32 v204, 16, v98
	v_and_b32_e32 v205, 0xffff0000, v98
	v_lshlrev_b32_e32 v206, 16, v99
	v_and_b32_e32 v207, 0xffff0000, v99
	v_mul_f32_e32 v200, v214, v200
	v_mul_f32_e32 v201, v214, v201
	v_mul_f32_e32 v202, v214, v202
	v_mul_f32_e32 v203, v214, v203
	v_mul_f32_e32 v204, v215, v204
	v_mul_f32_e32 v205, v215, v205
	v_mul_f32_e32 v206, v215, v206
	v_mul_f32_e32 v207, v215, v207
	v_fmac_f32_e32 v4, v132, v200
	v_fmac_f32_e32 v5, v133, v201
	v_fmac_f32_e32 v6, v134, v202
	v_fmac_f32_e32 v7, v135, v203
	v_fmac_f32_e32 v4, v164, v204
	v_fmac_f32_e32 v5, v165, v205
	v_fmac_f32_e32 v6, v166, v206
	v_fmac_f32_e32 v7, v167, v207
	global_store_dwordx4 v192, v[4:7], s[18:19] offset:1024
	v_lshlrev_b32_e32 v200, 16, v68
	v_and_b32_e32 v201, 0xffff0000, v68
	v_lshlrev_b32_e32 v202, 16, v69
	v_and_b32_e32 v203, 0xffff0000, v69
	v_lshlrev_b32_e32 v204, 16, v100
	v_and_b32_e32 v205, 0xffff0000, v100
	v_lshlrev_b32_e32 v206, 16, v101
	v_and_b32_e32 v207, 0xffff0000, v101
	v_mul_f32_e32 v200, v214, v200
	v_mul_f32_e32 v201, v214, v201
	v_mul_f32_e32 v202, v214, v202
	v_mul_f32_e32 v203, v214, v203
	v_mul_f32_e32 v204, v215, v204
	v_mul_f32_e32 v205, v215, v205
	v_mul_f32_e32 v206, v215, v206
	v_mul_f32_e32 v207, v215, v207
	v_fmac_f32_e32 v8, v136, v200
	v_fmac_f32_e32 v9, v137, v201
	v_fmac_f32_e32 v10, v138, v202
	v_fmac_f32_e32 v11, v139, v203
	v_fmac_f32_e32 v8, v168, v204
	v_fmac_f32_e32 v9, v169, v205
	v_fmac_f32_e32 v10, v170, v206
	v_fmac_f32_e32 v11, v171, v207
	global_store_dwordx4 v192, v[8:11], s[18:19] offset:2048
	v_lshlrev_b32_e32 v200, 16, v70
	v_and_b32_e32 v201, 0xffff0000, v70
	v_lshlrev_b32_e32 v202, 16, v71
	v_and_b32_e32 v203, 0xffff0000, v71
	v_lshlrev_b32_e32 v204, 16, v102
	v_and_b32_e32 v205, 0xffff0000, v102
	v_lshlrev_b32_e32 v206, 16, v103
	v_and_b32_e32 v207, 0xffff0000, v103
	v_mul_f32_e32 v200, v214, v200
	v_mul_f32_e32 v201, v214, v201
	v_mul_f32_e32 v202, v214, v202
	v_mul_f32_e32 v203, v214, v203
	v_mul_f32_e32 v204, v215, v204
	v_mul_f32_e32 v205, v215, v205
	v_mul_f32_e32 v206, v215, v206
	v_mul_f32_e32 v207, v215, v207
	v_fmac_f32_e32 v12, v140, v200
; __device__ __forceinline__ float bf_lo(unsigned w) { return __uint_as_float(w << 16); }
; __device__ __forceinline__ float bf_hi(unsigned w) { return __uint_as_float(w & 0xffff0000u); }
; __global__ void __launch_bounds__(NWAVES * 64, 2) mk_fwd(Args args) {
;     ...
;                 float sy = 0.f;
; #pragma unroll
;                 for (int j = 0; j < 8; ++j) { const float a = bf_lo(yw[q][j].x), b = bf_hi(yw[q][j].x), c2 = bf_lo(yw[q][j].y), d = bf_hi(yw[q][j].y); sy += (a * a + b * b) + (c2 * c2 + d * d); }
;                 const float rsy = __builtin_amdgcn_rsqf(wave_sum(sy) * (1.f / DM) + EPS);
; #pragma unroll
;                 for (int j = 0; j < 8; ++j) { const int col = 4 * F.lane + 256 * j;
;                     const f32x4 y4 = (f32x4){bf_lo(yw[q][j].x), bf_hi(yw[q][j].x), bf_lo(yw[q][j].y), bf_hi(yw[q][j].y)};
;                     *(f32x4*)(args.out + (size_t)row * DM + col) = v[q][j] + PA[j] * (y4 * rsy); }
	v_fmac_f32_e32 v13, v141, v201
	v_fmac_f32_e32 v14, v142, v202
	v_fmac_f32_e32 v15, v143, v203
	v_fmac_f32_e32 v12, v172, v204
	v_fmac_f32_e32 v13, v173, v205
	v_fmac_f32_e32 v14, v174, v206
	v_fmac_f32_e32 v15, v175, v207
	global_store_dwordx4 v192, v[12:15], s[18:19] offset:3072
	v_lshlrev_b32_e32 v200, 16, v72
	v_and_b32_e32 v201, 0xffff0000, v72
	v_lshlrev_b32_e32 v202, 16, v73
	v_and_b32_e32 v203, 0xffff0000, v73
	v_lshlrev_b32_e32 v204, 16, v104
	v_and_b32_e32 v205, 0xffff0000, v104
	v_lshlrev_b32_e32 v206, 16, v105
	v_and_b32_e32 v207, 0xffff0000, v105
	v_mul_f32_e32 v200, v214, v200
	v_mul_f32_e32 v201, v214, v201
	v_mul_f32_e32 v202, v214, v202
	v_mul_f32_e32 v203, v214, v203
	v_mul_f32_e32 v204, v215, v204
	v_mul_f32_e32 v205, v215, v205
	v_mul_f32_e32 v206, v215, v206
	v_mul_f32_e32 v207, v215, v207
	v_fmac_f32_e32 v16, v144, v200
	v_fmac_f32_e32 v17, v145, v201
	v_fmac_f32_e32 v18, v146, v202
	v_fmac_f32_e32 v19, v147, v203
	v_fmac_f32_e32 v16, v176, v204
	v_fmac_f32_e32 v17, v177, v205
	v_fmac_f32_e32 v18, v178, v206
	v_fmac_f32_e32 v19, v179, v207
	global_store_dwordx4 v193, v[16:19], s[18:19] offset:0
	v_lshlrev_b32_e32 v200, 16, v74
	v_and_b32_e32 v201, 0xffff0000, v74
	v_lshlrev_b32_e32 v202, 16, v75
	v_and_b32_e32 v203, 0xffff0000, v75
	v_lshlrev_b32_e32 v204, 16, v106
	v_and_b32_e32 v205, 0xffff0000, v106
	v_lshlrev_b32_e32 v206, 16, v107
	v_and_b32_e32 v207, 0xffff0000, v107
	v_mul_f32_e32 v200, v214, v200
	v_mul_f32_e32 v201, v214, v201
	v_mul_f32_e32 v202, v214, v202
	v_mul_f32_e32 v203, v214, v203
	v_mul_f32_e32 v204, v215, v204
	v_mul_f32_e32 v205, v215, v205
	v_mul_f32_e32 v206, v215, v206
	v_mul_f32_e32 v207, v215, v207
	v_fmac_f32_e32 v20, v148, v200
	v_fmac_f32_e32 v21, v149, v201
	v_fmac_f32_e32 v22, v150, v202
	v_fmac_f32_e32 v23, v151, v203
	v_fmac_f32_e32 v20, v180, v204
	v_fmac_f32_e32 v21, v181, v205
	v_fmac_f32_e32 v22, v182, v206
	v_fmac_f32_e32 v23, v183, v207
	global_store_dwordx4 v193, v[20:23], s[18:19] offset:1024
	v_lshlrev_b32_e32 v200, 16, v76
	v_and_b32_e32 v201, 0xffff0000, v76
	v_lshlrev_b32_e32 v202, 16, v77
	v_and_b32_e32 v203, 0xffff0000, v77
	v_lshlrev_b32_e32 v204, 16, v108
	v_and_b32_e32 v205, 0xffff0000, v108
	v_lshlrev_b32_e32 v206, 16, v109
	v_and_b32_e32 v207, 0xffff0000, v109
	v_mul_f32_e32 v200, v214, v200
	v_mul_f32_e32 v201, v214, v201
	v_mul_f32_e32 v202, v214, v202
	v_mul_f32_e32 v203, v214, v203
	v_mul_f32_e32 v204, v215, v204
	v_mul_f32_e32 v205, v215, v205
	v_mul_f32_e32 v206, v215, v206
	v_mul_f32_e32 v207, v215, v207
	v_fmac_f32_e32 v24, v152, v200
	v_fmac_f32_e32 v25, v153, v201
	v_fmac_f32_e32 v26, v154, v202
	v_fmac_f32_e32 v27, v155, v203
	v_fmac_f32_e32 v24, v184, v204
	v_fmac_f32_e32 v25, v185, v205
	v_fmac_f32_e32 v26, v186, v206
	v_fmac_f32_e32 v27, v187, v207
	global_store_dwordx4 v193, v[24:27], s[18:19] offset:2048
	v_lshlrev_b32_e32 v200, 16, v78
	v_and_b32_e32 v201, 0xffff0000, v78
	v_lshlrev_b32_e32 v202, 16, v79
	v_and_b32_e32 v203, 0xffff0000, v79
	v_lshlrev_b32_e32 v204, 16, v110
	v_and_b32_e32 v205, 0xffff0000, v110
	v_lshlrev_b32_e32 v206, 16, v111
	v_and_b32_e32 v207, 0xffff0000, v111
	v_mul_f32_e32 v200, v214, v200
	v_mul_f32_e32 v201, v214, v201
	v_mul_f32_e32 v202, v214, v202
	v_mul_f32_e32 v203, v214, v203
	v_mul_f32_e32 v204, v215, v204
	v_mul_f32_e32 v205, v215, v205
	v_mul_f32_e32 v206, v215, v206
	v_mul_f32_e32 v207, v215, v207
	v_fmac_f32_e32 v28, v156, v200
	v_fmac_f32_e32 v29, v157, v201
	v_fmac_f32_e32 v30, v158, v202
	v_fmac_f32_e32 v31, v159, v203
	v_fmac_f32_e32 v28, v188, v204
	v_fmac_f32_e32 v29, v189, v205
	v_fmac_f32_e32 v30, v190, v206
	v_fmac_f32_e32 v31, v191, v207
	global_store_dwordx4 v193, v[28:31], s[18:19] offset:3072
	s_add_u32 s18, s18, 0x2000
	s_addc_u32 s19, s19, 0
	global_load_dwordx4 v[0:3], v192, s[14:15] offset:0 nt
	global_load_dwordx4 v[4:7], v192, s[14:15] offset:1024 nt
	global_load_dwordx4 v[8:11], v192, s[14:15] offset:2048 nt
	global_load_dwordx4 v[12:15], v192, s[14:15] offset:3072 nt
	global_load_dwordx4 v[16:19], v193, s[14:15] offset:0 nt
	global_load_dwordx4 v[20:23], v193, s[14:15] offset:1024 nt
	global_load_dwordx4 v[24:27], v193, s[14:15] offset:2048 nt
	global_load_dwordx4 v[28:31], v193, s[14:15] offset:3072 nt
	global_load_dwordx2 v[64:65], v194, s[16:17] offset:0 nt
	global_load_dwordx2 v[66:67], v194, s[16:17] offset:512 nt
	global_load_dwordx2 v[68:69], v194, s[16:17] offset:1024 nt
	global_load_dwordx2 v[70:71], v194, s[16:17] offset:1536 nt
	global_load_dwordx2 v[72:73], v194, s[16:17] offset:2048 nt
	global_load_dwordx2 v[74:75], v194, s[16:17] offset:2560 nt
	global_load_dwordx2 v[76:77], v194, s[16:17] offset:3072 nt
	global_load_dwordx2 v[78:79], v194, s[16:17] offset:3584 nt
	global_load_dwordx2 v[96:97], v194, s[22:23] offset:0 nt
	global_load_dwordx2 v[98:99], v194, s[22:23] offset:512 nt
	global_load_dwordx2 v[100:101], v194, s[22:23] offset:1024 nt
	global_load_dwordx2 v[102:103], v194, s[22:23] offset:1536 nt
	global_load_dwordx2 v[104:105], v194, s[22:23] offset:2048 nt
	global_load_dwordx2 v[106:107], v194, s[22:23] offset:2560 nt
	global_load_dwordx2 v[108:109], v194, s[22:23] offset:3072 nt
	global_load_dwordx2 v[110:111], v194, s[22:23] offset:3584 nt
	s_add_u32 s14, s14, 0x2000
	s_addc_u32 s15, s15, 0
	s_add_u32 s16, s16, 0x1000
	s_addc_u32 s17, s17, 0
	s_add_u32 s22, s22, 0x1000
	s_addc_u32 s23, s23, 0
	s_waitcnt vmcnt(32)
; __device__ __forceinline__ float bf_lo(unsigned w) { return __uint_as_float(w << 16); }
; __device__ __forceinline__ float bf_hi(unsigned w) { return __uint_as_float(w & 0xffff0000u); }
; __global__ void __launch_bounds__(NWAVES * 64, 2) mk_fwd(Args args) {
;     ...
;                 float sy = 0.f;
; #pragma unroll
;                 for (int j = 0; j < 8; ++j) { const float a = bf_lo(yw[q][j].x), b = bf_hi(yw[q][j].x), c2 = bf_lo(yw[q][j].y), d = bf_hi(yw[q][j].y); sy += (a * a + b * b) + (c2 * c2 + d * d); }
;                 const float rsy = __builtin_amdgcn_rsqf(wave_sum(sy) * (1.f / DM) + EPS);
	v_lshlrev_b32_e32 v200, 16, v80
	v_and_b32_e32 v201, 0xffff0000, v80
	v_lshlrev_b32_e32 v202, 16, v81
	v_and_b32_e32 v203, 0xffff0000, v81
	v_mul_f32_e32 v208, v200, v200
	v_mul_f32_e32 v209, v201, v201
	v_fmac_f32_e32 v208, v202, v202
	v_fmac_f32_e32 v209, v203, v203
	v_lshlrev_b32_e32 v204, 16, v112
	v_and_b32_e32 v205, 0xffff0000, v112
	v_lshlrev_b32_e32 v206, 16, v113
	v_and_b32_e32 v207, 0xffff0000, v113
	v_mul_f32_e32 v210, v204, v204
	v_mul_f32_e32 v211, v205, v205
	v_fmac_f32_e32 v210, v206, v206
	v_fmac_f32_e32 v211, v207, v207
	v_lshlrev_b32_e32 v200, 16, v82
	v_and_b32_e32 v201, 0xffff0000, v82
	v_lshlrev_b32_e32 v202, 16, v83
	v_and_b32_e32 v203, 0xffff0000, v83
	v_fmac_f32_e32 v208, v200, v200
	v_fmac_f32_e32 v209, v201, v201
	v_fmac_f32_e32 v208, v202, v202
	v_fmac_f32_e32 v209, v203, v203
	v_lshlrev_b32_e32 v204, 16, v114
	v_and_b32_e32 v205, 0xffff0000, v114
	v_lshlrev_b32_e32 v206, 16, v115
	v_and_b32_e32 v207, 0xffff0000, v115
	v_fmac_f32_e32 v210, v204, v204
	v_fmac_f32_e32 v211, v205, v205
	v_fmac_f32_e32 v210, v206, v206
	v_fmac_f32_e32 v211, v207, v207
	v_lshlrev_b32_e32 v200, 16, v84
	v_and_b32_e32 v201, 0xffff0000, v84
	v_lshlrev_b32_e32 v202, 16, v85
	v_and_b32_e32 v203, 0xffff0000, v85
	v_fmac_f32_e32 v208, v200, v200
	v_fmac_f32_e32 v209, v201, v201
	v_fmac_f32_e32 v208, v202, v202
	v_fmac_f32_e32 v209, v203, v203
	v_lshlrev_b32_e32 v204, 16, v116
	v_and_b32_e32 v205, 0xffff0000, v116
	v_lshlrev_b32_e32 v206, 16, v117
	v_and_b32_e32 v207, 0xffff0000, v117
	v_fmac_f32_e32 v210, v204, v204
	v_fmac_f32_e32 v211, v205, v205
	v_fmac_f32_e32 v210, v206, v206
	v_fmac_f32_e32 v211, v207, v207
	v_lshlrev_b32_e32 v200, 16, v86
	v_and_b32_e32 v201, 0xffff0000, v86
	v_lshlrev_b32_e32 v202, 16, v87
	v_and_b32_e32 v203, 0xffff0000, v87
	v_fmac_f32_e32 v208, v200, v200
	v_fmac_f32_e32 v209, v201, v201
	v_fmac_f32_e32 v208, v202, v202
	v_fmac_f32_e32 v209, v203, v203
	v_lshlrev_b32_e32 v204, 16, v118
	v_and_b32_e32 v205, 0xffff0000, v118
	v_lshlrev_b32_e32 v206, 16, v119
	v_and_b32_e32 v207, 0xffff0000, v119
	v_fmac_f32_e32 v210, v204, v204
	v_fmac_f32_e32 v211, v205, v205
	v_fmac_f32_e32 v210, v206, v206
	v_fmac_f32_e32 v211, v207, v207
	v_lshlrev_b32_e32 v200, 16, v88
	v_and_b32_e32 v201, 0xffff0000, v88
	v_lshlrev_b32_e32 v202, 16, v89
	v_and_b32_e32 v203, 0xffff0000, v89
	v_fmac_f32_e32 v208, v200, v200
	v_fmac_f32_e32 v209, v201, v201
	v_fmac_f32_e32 v208, v202, v202
	v_fmac_f32_e32 v209, v203, v203
	v_lshlrev_b32_e32 v204, 16, v120
	v_and_b32_e32 v205, 0xffff0000, v120
	v_lshlrev_b32_e32 v206, 16, v121
	v_and_b32_e32 v207, 0xffff0000, v121
	v_fmac_f32_e32 v210, v204, v204
	v_fmac_f32_e32 v211, v205, v205
	v_fmac_f32_e32 v210, v206, v206
	v_fmac_f32_e32 v211, v207, v207
	v_lshlrev_b32_e32 v200, 16, v90
	v_and_b32_e32 v201, 0xffff0000, v90
	v_lshlrev_b32_e32 v202, 16, v91
	v_and_b32_e32 v203, 0xffff0000, v91
	v_fmac_f32_e32 v208, v200, v200
	v_fmac_f32_e32 v209, v201, v201
	v_fmac_f32_e32 v208, v202, v202
	v_fmac_f32_e32 v209, v203, v203
	v_lshlrev_b32_e32 v204, 16, v122
	v_and_b32_e32 v205, 0xffff0000, v122
	v_lshlrev_b32_e32 v206, 16, v123
	v_and_b32_e32 v207, 0xffff0000, v123
	v_fmac_f32_e32 v210, v204, v204
	v_fmac_f32_e32 v211, v205, v205
	v_fmac_f32_e32 v210, v206, v206
	v_fmac_f32_e32 v211, v207, v207
	v_lshlrev_b32_e32 v200, 16, v92
	v_and_b32_e32 v201, 0xffff0000, v92
	v_lshlrev_b32_e32 v202, 16, v93
	v_and_b32_e32 v203, 0xffff0000, v93
	v_fmac_f32_e32 v208, v200, v200
	v_fmac_f32_e32 v209, v201, v201
	v_fmac_f32_e32 v208, v202, v202
	v_fmac_f32_e32 v209, v203, v203
	v_lshlrev_b32_e32 v204, 16, v124
	v_and_b32_e32 v205, 0xffff0000, v124
	v_lshlrev_b32_e32 v206, 16, v125
	v_and_b32_e32 v207, 0xffff0000, v125
	v_fmac_f32_e32 v210, v204, v204
	v_fmac_f32_e32 v211, v205, v205
	v_fmac_f32_e32 v210, v206, v206
	v_fmac_f32_e32 v211, v207, v207
	v_lshlrev_b32_e32 v200, 16, v94
	v_and_b32_e32 v201, 0xffff0000, v94
	v_lshlrev_b32_e32 v202, 16, v95
	v_and_b32_e32 v203, 0xffff0000, v95
	v_fmac_f32_e32 v208, v200, v200
	v_fmac_f32_e32 v209, v201, v201
	v_fmac_f32_e32 v208, v202, v202
	v_fmac_f32_e32 v209, v203, v203
	v_lshlrev_b32_e32 v204, 16, v126
	v_and_b32_e32 v205, 0xffff0000, v126
	v_lshlrev_b32_e32 v206, 16, v127
	v_and_b32_e32 v207, 0xffff0000, v127
	v_fmac_f32_e32 v210, v204, v204
	v_fmac_f32_e32 v211, v205, v205
	v_fmac_f32_e32 v210, v206, v206
	v_fmac_f32_e32 v211, v207, v207
	v_add_f32_e32 v208, v208, v209
	v_add_f32_e32 v210, v210, v211
	s_nop 0
	v_add_f32_dpp v212, v208, v208 quad_perm:[1,0,3,2] row_mask:0xf bank_mask:0xf
	v_add_f32_dpp v213, v210, v210 quad_perm:[1,0,3,2] row_mask:0xf bank_mask:0xf
	s_nop 0
	v_add_f32_dpp v212, v212, v212 quad_perm:[2,3,0,1] row_mask:0xf bank_mask:0xf
	v_add_f32_dpp v213, v213, v213 quad_perm:[2,3,0,1] row_mask:0xf bank_mask:0xf
	s_nop 0
	v_add_f32_dpp v212, v212, v212 row_half_mirror row_mask:0xf bank_mask:0xf
	v_add_f32_dpp v213, v213, v213 row_half_mirror row_mask:0xf bank_mask:0xf
	s_nop 0
	v_add_f32_dpp v212, v212, v212 row_mirror row_mask:0xf bank_mask:0xf
	v_add_f32_dpp v213, v213, v213 row_mirror row_mask:0xf bank_mask:0xf
	s_nop 0
	v_readlane_b32 s4, v212, 0
	v_readlane_b32 s5, v212, 16
	v_readlane_b32 s6, v212, 32
	v_readlane_b32 s7, v212, 48
	v_readlane_b32 s24, v213, 0
	v_readlane_b32 s25, v213, 16
	v_readlane_b32 s26, v213, 32
	v_readlane_b32 s27, v213, 48
	s_nop 1
	v_mov_b32_e32 v214, s4
	v_mov_b32_e32 v215, s24
	v_add_f32_e32 v214, s5, v214
	v_add_f32_e32 v215, s25, v215
	v_add_f32_e32 v214, s6, v214
	v_add_f32_e32 v215, s26, v215
	v_add_f32_e32 v214, s7, v214
	v_add_f32_e32 v215, s27, v215
	v_fmamk_f32 v214, v214, 0x3a000000, v195
	v_fmamk_f32 v215, v215, 0x3a000000, v195
; __device__ __forceinline__ float bf_lo(unsigned w) { return __uint_as_float(w << 16); }
; __device__ __forceinline__ float bf_hi(unsigned w) { return __uint_as_float(w & 0xffff0000u); }
; __global__ void __launch_bounds__(NWAVES * 64, 2) mk_fwd(Args args) {
;     ...
; #pragma unroll
;                 for (int j = 0; j < 8; ++j) { const int col = 4 * F.lane + 256 * j;
;                     const f32x4 y4 = (f32x4){bf_lo(yw[q][j].x), bf_hi(yw[q][j].x), bf_lo(yw[q][j].y), bf_hi(yw[q][j].y)};
;                     *(f32x4*)(args.out + (size_t)row * DM + col) = v[q][j] + PA[j] * (y4 * rsy); }
	v_rsq_f32_e32 v214, v214
	v_rsq_f32_e32 v215, v215
	s_nop 0
	v_lshlrev_b32_e32 v200, 16, v80
	v_and_b32_e32 v201, 0xffff0000, v80
	v_lshlrev_b32_e32 v202, 16, v81
	v_and_b32_e32 v203, 0xffff0000, v81
	v_lshlrev_b32_e32 v204, 16, v112
	v_and_b32_e32 v205, 0xffff0000, v112
	v_lshlrev_b32_e32 v206, 16, v113
	v_and_b32_e32 v207, 0xffff0000, v113
	v_mul_f32_e32 v200, v214, v200
	v_mul_f32_e32 v201, v214, v201
	v_mul_f32_e32 v202, v214, v202
	v_mul_f32_e32 v203, v214, v203
	v_mul_f32_e32 v204, v215, v204
	v_mul_f32_e32 v205, v215, v205
	v_mul_f32_e32 v206, v215, v206
	v_mul_f32_e32 v207, v215, v207
	v_fmac_f32_e32 v32, v128, v200
	v_fmac_f32_e32 v33, v129, v201
	v_fmac_f32_e32 v34, v130, v202
	v_fmac_f32_e32 v35, v131, v203
	v_fmac_f32_e32 v32, v160, v204
	v_fmac_f32_e32 v33, v161, v205
	v_fmac_f32_e32 v34, v162, v206
	v_fmac_f32_e32 v35, v163, v207
	global_store_dwordx4 v192, v[32:35], s[18:19] offset:0
	v_lshlrev_b32_e32 v200, 16, v82
	v_and_b32_e32 v201, 0xffff0000, v82
	v_lshlrev_b32_e32 v202, 16, v83
	v_and_b32_e32 v203, 0xffff0000, v83
	v_lshlrev_b32_e32 v204, 16, v114
	v_and_b32_e32 v205, 0xffff0000, v114
	v_lshlrev_b32_e32 v206, 16, v115
	v_and_b32_e32 v207, 0xffff0000, v115
	v_mul_f32_e32 v200, v214, v200
	v_mul_f32_e32 v201, v214, v201
	v_mul_f32_e32 v202, v214, v202
	v_mul_f32_e32 v203, v214, v203
	v_mul_f32_e32 v204, v215, v204
	v_mul_f32_e32 v205, v215, v205
	v_mul_f32_e32 v206, v215, v206
	v_mul_f32_e32 v207, v215, v207
	v_fmac_f32_e32 v36, v132, v200
	v_fmac_f32_e32 v37, v133, v201
	v_fmac_f32_e32 v38, v134, v202
	v_fmac_f32_e32 v39, v135, v203
	v_fmac_f32_e32 v36, v164, v204
	v_fmac_f32_e32 v37, v165, v205
	v_fmac_f32_e32 v38, v166, v206
	v_fmac_f32_e32 v39, v167, v207
	global_store_dwordx4 v192, v[36:39], s[18:19] offset:1024
	v_lshlrev_b32_e32 v200, 16, v84
	v_and_b32_e32 v201, 0xffff0000, v84
	v_lshlrev_b32_e32 v202, 16, v85
	v_and_b32_e32 v203, 0xffff0000, v85
	v_lshlrev_b32_e32 v204, 16, v116
	v_and_b32_e32 v205, 0xffff0000, v116
	v_lshlrev_b32_e32 v206, 16, v117
	v_and_b32_e32 v207, 0xffff0000, v117
	v_mul_f32_e32 v200, v214, v200
	v_mul_f32_e32 v201, v214, v201
	v_mul_f32_e32 v202, v214, v202
	v_mul_f32_e32 v203, v214, v203
	v_mul_f32_e32 v204, v215, v204
	v_mul_f32_e32 v205, v215, v205
	v_mul_f32_e32 v206, v215, v206
	v_mul_f32_e32 v207, v215, v207
	v_fmac_f32_e32 v40, v136, v200
	v_fmac_f32_e32 v41, v137, v201
	v_fmac_f32_e32 v42, v138, v202
	v_fmac_f32_e32 v43, v139, v203
	v_fmac_f32_e32 v40, v168, v204
	v_fmac_f32_e32 v41, v169, v205
	v_fmac_f32_e32 v42, v170, v206
	v_fmac_f32_e32 v43, v171, v207
	global_store_dwordx4 v192, v[40:43], s[18:19] offset:2048
	v_lshlrev_b32_e32 v200, 16, v86
	v_and_b32_e32 v201, 0xffff0000, v86
	v_lshlrev_b32_e32 v202, 16, v87
	v_and_b32_e32 v203, 0xffff0000, v87
	v_lshlrev_b32_e32 v204, 16, v118
	v_and_b32_e32 v205, 0xffff0000, v118
	v_lshlrev_b32_e32 v206, 16, v119
	v_and_b32_e32 v207, 0xffff0000, v119
	v_mul_f32_e32 v200, v214, v200
	v_mul_f32_e32 v201, v214, v201
	v_mul_f32_e32 v202, v214, v202
	v_mul_f32_e32 v203, v214, v203
	v_mul_f32_e32 v204, v215, v204
	v_mul_f32_e32 v205, v215, v205
	v_mul_f32_e32 v206, v215, v206
	v_mul_f32_e32 v207, v215, v207
	v_fmac_f32_e32 v44, v140, v200
	v_fmac_f32_e32 v45, v141, v201
	v_fmac_f32_e32 v46, v142, v202
	v_fmac_f32_e32 v47, v143, v203
	v_fmac_f32_e32 v44, v172, v204
	v_fmac_f32_e32 v45, v173, v205
	v_fmac_f32_e32 v46, v174, v206
	v_fmac_f32_e32 v47, v175, v207
	global_store_dwordx4 v192, v[44:47], s[18:19] offset:3072
	v_lshlrev_b32_e32 v200, 16, v88
	v_and_b32_e32 v201, 0xffff0000, v88
	v_lshlrev_b32_e32 v202, 16, v89
	v_and_b32_e32 v203, 0xffff0000, v89
	v_lshlrev_b32_e32 v204, 16, v120
	v_and_b32_e32 v205, 0xffff0000, v120
	v_lshlrev_b32_e32 v206, 16, v121
	v_and_b32_e32 v207, 0xffff0000, v121
	v_mul_f32_e32 v200, v214, v200
	v_mul_f32_e32 v201, v214, v201
	v_mul_f32_e32 v202, v214, v202
	v_mul_f32_e32 v203, v214, v203
	v_mul_f32_e32 v204, v215, v204
	v_mul_f32_e32 v205, v215, v205
	v_mul_f32_e32 v206, v215, v206
	v_mul_f32_e32 v207, v215, v207
	v_fmac_f32_e32 v48, v144, v200
	v_fmac_f32_e32 v49, v145, v201
	v_fmac_f32_e32 v50, v146, v202
	v_fmac_f32_e32 v51, v147, v203
	v_fmac_f32_e32 v48, v176, v204
	v_fmac_f32_e32 v49, v177, v205
	v_fmac_f32_e32 v50, v178, v206
	v_fmac_f32_e32 v51, v179, v207
	global_store_dwordx4 v193, v[48:51], s[18:19] offset:0
	v_lshlrev_b32_e32 v200, 16, v90
	v_and_b32_e32 v201, 0xffff0000, v90
	v_lshlrev_b32_e32 v202, 16, v91
	v_and_b32_e32 v203, 0xffff0000, v91
	v_lshlrev_b32_e32 v204, 16, v122
	v_and_b32_e32 v205, 0xffff0000, v122
	v_lshlrev_b32_e32 v206, 16, v123
	v_and_b32_e32 v207, 0xffff0000, v123
	v_mul_f32_e32 v200, v214, v200
	v_mul_f32_e32 v201, v214, v201
	v_mul_f32_e32 v202, v214, v202
	v_mul_f32_e32 v203, v214, v203
	v_mul_f32_e32 v204, v215, v204
	v_mul_f32_e32 v205, v215, v205
	v_mul_f32_e32 v206, v215, v206
	v_mul_f32_e32 v207, v215, v207
	v_fmac_f32_e32 v52, v148, v200
	v_fmac_f32_e32 v53, v149, v201
	v_fmac_f32_e32 v54, v150, v202
	v_fmac_f32_e32 v55, v151, v203
	v_fmac_f32_e32 v52, v180, v204
	v_fmac_f32_e32 v53, v181, v205
	v_fmac_f32_e32 v54, v182, v206
	v_fmac_f32_e32 v55, v183, v207
	global_store_dwordx4 v193, v[52:55], s[18:19] offset:1024
	v_lshlrev_b32_e32 v200, 16, v92
	v_and_b32_e32 v201, 0xffff0000, v92
	v_lshlrev_b32_e32 v202, 16, v93
	v_and_b32_e32 v203, 0xffff0000, v93
	v_lshlrev_b32_e32 v204, 16, v124
	v_and_b32_e32 v205, 0xffff0000, v124
	v_lshlrev_b32_e32 v206, 16, v125
	v_and_b32_e32 v207, 0xffff0000, v125
	v_mul_f32_e32 v200, v214, v200
	v_mul_f32_e32 v201, v214, v201
	v_mul_f32_e32 v202, v214, v202
	v_mul_f32_e32 v203, v214, v203
	v_mul_f32_e32 v204, v215, v204
; __device__ __forceinline__ float bf_lo(unsigned w) { return __uint_as_float(w << 16); }
; __device__ __forceinline__ float bf_hi(unsigned w) { return __uint_as_float(w & 0xffff0000u); }
; __global__ void __launch_bounds__(NWAVES * 64, 2) mk_fwd(Args args) {
;     ...
;             for (int q = 0; q < 2; ++q) { const int row = row0 + q; load_row_f32(args.out + (size_t)row * DM, F.lane, v[q]);
;                 const bf16_t* yr = Y + (size_t)row * DM;
; #pragma unroll
;                 for (int j = 0; j < 8; ++j) yw[q][j] = *(const u32x2*)(yr + 4 * F.lane + 256 * j); }
; #pragma unroll
;             for (int q = 0; q < 2; ++q) { const int row = row0 + q; const int r = row / SEQ;
;                 if (r != rcur) { const float* m1 = mod + (size_t)(9 + r) * 6144; rcur = r;
; #pragma unroll
;                     for (int j = 0; j < 8; ++j) { const int col = 4 * F.lane + 256 * j; PA[j] = *(const f32x4*)(m1 + 2 * DM + col) * *(const f32x4*)(post_norm + DM + col); } }
;                 float sy = 0.f;
; #pragma unroll
;                 for (int j = 0; j < 8; ++j) { const float a = bf_lo(yw[q][j].x), b = bf_hi(yw[q][j].x), c2 = bf_lo(yw[q][j].y), d = bf_hi(yw[q][j].y); sy += (a * a + b * b) + (c2 * c2 + d * d); }
;     ...
; #pragma unroll
;                 for (int j = 0; j < 8; ++j) { const int col = 4 * F.lane + 256 * j;
;                     const f32x4 y4 = (f32x4){bf_lo(yw[q][j].x), bf_hi(yw[q][j].x), bf_lo(yw[q][j].y), bf_hi(yw[q][j].y)};
;                     *(f32x4*)(args.out + (size_t)row * DM + col) = v[q][j] + PA[j] * (y4 * rsy); }
	v_mul_f32_e32 v205, v215, v205
	v_mul_f32_e32 v206, v215, v206
	v_mul_f32_e32 v207, v215, v207
	v_fmac_f32_e32 v56, v152, v200
	v_fmac_f32_e32 v57, v153, v201
	v_fmac_f32_e32 v58, v154, v202
	v_fmac_f32_e32 v59, v155, v203
	v_fmac_f32_e32 v56, v184, v204
	v_fmac_f32_e32 v57, v185, v205
	v_fmac_f32_e32 v58, v186, v206
	v_fmac_f32_e32 v59, v187, v207
	global_store_dwordx4 v193, v[56:59], s[18:19] offset:2048
	v_lshlrev_b32_e32 v200, 16, v94
	v_and_b32_e32 v201, 0xffff0000, v94
	v_lshlrev_b32_e32 v202, 16, v95
	v_and_b32_e32 v203, 0xffff0000, v95
	v_lshlrev_b32_e32 v204, 16, v126
	v_and_b32_e32 v205, 0xffff0000, v126
	v_lshlrev_b32_e32 v206, 16, v127
	v_and_b32_e32 v207, 0xffff0000, v127
	v_mul_f32_e32 v200, v214, v200
	v_mul_f32_e32 v201, v214, v201
	v_mul_f32_e32 v202, v214, v202
	v_mul_f32_e32 v203, v214, v203
	v_mul_f32_e32 v204, v215, v204
	v_mul_f32_e32 v205, v215, v205
	v_mul_f32_e32 v206, v215, v206
	v_mul_f32_e32 v207, v215, v207
	v_fmac_f32_e32 v60, v156, v200
	v_fmac_f32_e32 v61, v157, v201
	v_fmac_f32_e32 v62, v158, v202
	v_fmac_f32_e32 v63, v159, v203
	v_fmac_f32_e32 v60, v188, v204
	v_fmac_f32_e32 v61, v189, v205
	v_fmac_f32_e32 v62, v190, v206
	v_fmac_f32_e32 v63, v191, v207
	global_store_dwordx4 v193, v[60:63], s[18:19] offset:3072
	s_add_u32 s18, s18, 0x2000
	s_addc_u32 s19, s19, 0
	global_load_dwordx4 v[32:35], v192, s[14:15] offset:0 nt
	global_load_dwordx4 v[36:39], v192, s[14:15] offset:1024 nt
	global_load_dwordx4 v[40:43], v192, s[14:15] offset:2048 nt
	global_load_dwordx4 v[44:47], v192, s[14:15] offset:3072 nt
	global_load_dwordx4 v[48:51], v193, s[14:15] offset:0 nt
	global_load_dwordx4 v[52:55], v193, s[14:15] offset:1024 nt
	global_load_dwordx4 v[56:59], v193, s[14:15] offset:2048 nt
	global_load_dwordx4 v[60:63], v193, s[14:15] offset:3072 nt
	global_load_dwordx2 v[80:81], v194, s[16:17] offset:0 nt
	global_load_dwordx2 v[82:83], v194, s[16:17] offset:512 nt
	global_load_dwordx2 v[84:85], v194, s[16:17] offset:1024 nt
	global_load_dwordx2 v[86:87], v194, s[16:17] offset:1536 nt
	global_load_dwordx2 v[88:89], v194, s[16:17] offset:2048 nt
	global_load_dwordx2 v[90:91], v194, s[16:17] offset:2560 nt
	global_load_dwordx2 v[92:93], v194, s[16:17] offset:3072 nt
	global_load_dwordx2 v[94:95], v194, s[16:17] offset:3584 nt
	global_load_dwordx2 v[112:113], v194, s[22:23] offset:0 nt
	global_load_dwordx2 v[114:115], v194, s[22:23] offset:512 nt
	global_load_dwordx2 v[116:117], v194, s[22:23] offset:1024 nt
	global_load_dwordx2 v[118:119], v194, s[22:23] offset:1536 nt
	global_load_dwordx2 v[120:121], v194, s[22:23] offset:2048 nt
	global_load_dwordx2 v[122:123], v194, s[22:23] offset:2560 nt
	global_load_dwordx2 v[124:125], v194, s[22:23] offset:3072 nt
	global_load_dwordx2 v[126:127], v194, s[22:23] offset:3584 nt
	s_add_u32 s14, s14, 0x2000
	s_addc_u32 s15, s15, 0
	s_add_u32 s16, s16, 0x1000
	s_addc_u32 s17, s17, 0
	s_add_u32 s22, s22, 0x1000
	s_addc_u32 s23, s23, 0
	s_waitcnt vmcnt(32)
	v_lshlrev_b32_e32 v200, 16, v64
	v_and_b32_e32 v201, 0xffff0000, v64
	v_lshlrev_b32_e32 v202, 16, v65
	v_and_b32_e32 v203, 0xffff0000, v65
	v_mul_f32_e32 v208, v200, v200
	v_mul_f32_e32 v209, v201, v201
	v_fmac_f32_e32 v208, v202, v202
	v_fmac_f32_e32 v209, v203, v203
	v_lshlrev_b32_e32 v204, 16, v96
	v_and_b32_e32 v205, 0xffff0000, v96
	v_lshlrev_b32_e32 v206, 16, v97
	v_and_b32_e32 v207, 0xffff0000, v97
	v_mul_f32_e32 v210, v204, v204
	v_mul_f32_e32 v211, v205, v205
	v_fmac_f32_e32 v210, v206, v206
	v_fmac_f32_e32 v211, v207, v207
	v_lshlrev_b32_e32 v200, 16, v66
	v_and_b32_e32 v201, 0xffff0000, v66
	v_lshlrev_b32_e32 v202, 16, v67
	v_and_b32_e32 v203, 0xffff0000, v67
	v_fmac_f32_e32 v208, v200, v200
	v_fmac_f32_e32 v209, v201, v201
	v_fmac_f32_e32 v208, v202, v202
	v_fmac_f32_e32 v209, v203, v203
	v_lshlrev_b32_e32 v204, 16, v98
	v_and_b32_e32 v205, 0xffff0000, v98
	v_lshlrev_b32_e32 v206, 16, v99
	v_and_b32_e32 v207, 0xffff0000, v99
	v_fmac_f32_e32 v210, v204, v204
	v_fmac_f32_e32 v211, v205, v205
	v_fmac_f32_e32 v210, v206, v206
	v_fmac_f32_e32 v211, v207, v207
	v_lshlrev_b32_e32 v200, 16, v68
	v_and_b32_e32 v201, 0xffff0000, v68
	v_lshlrev_b32_e32 v202, 16, v69
	v_and_b32_e32 v203, 0xffff0000, v69
	v_fmac_f32_e32 v208, v200, v200
	v_fmac_f32_e32 v209, v201, v201
	v_fmac_f32_e32 v208, v202, v202
	v_fmac_f32_e32 v209, v203, v203
	v_lshlrev_b32_e32 v204, 16, v100
	v_and_b32_e32 v205, 0xffff0000, v100
	v_lshlrev_b32_e32 v206, 16, v101
	v_and_b32_e32 v207, 0xffff0000, v101
	v_fmac_f32_e32 v210, v204, v204
	v_fmac_f32_e32 v211, v205, v205
	v_fmac_f32_e32 v210, v206, v206
	v_fmac_f32_e32 v211, v207, v207
	v_lshlrev_b32_e32 v200, 16, v70
	v_and_b32_e32 v201, 0xffff0000, v70
	v_lshlrev_b32_e32 v202, 16, v71
	v_and_b32_e32 v203, 0xffff0000, v71
	v_fmac_f32_e32 v208, v200, v200
	v_fmac_f32_e32 v209, v201, v201
	v_fmac_f32_e32 v208, v202, v202
	v_fmac_f32_e32 v209, v203, v203
	v_lshlrev_b32_e32 v204, 16, v102
	v_and_b32_e32 v205, 0xffff0000, v102
	v_lshlrev_b32_e32 v206, 16, v103
	v_and_b32_e32 v207, 0xffff0000, v103
	v_fmac_f32_e32 v210, v204, v204
	v_fmac_f32_e32 v211, v205, v205
	v_fmac_f32_e32 v210, v206, v206
	v_fmac_f32_e32 v211, v207, v207
	v_lshlrev_b32_e32 v200, 16, v72
	v_and_b32_e32 v201, 0xffff0000, v72
	v_lshlrev_b32_e32 v202, 16, v73
	v_and_b32_e32 v203, 0xffff0000, v73
	v_fmac_f32_e32 v208, v200, v200
	v_fmac_f32_e32 v209, v201, v201
	v_fmac_f32_e32 v208, v202, v202
	v_fmac_f32_e32 v209, v203, v203
	v_lshlrev_b32_e32 v204, 16, v104
	v_and_b32_e32 v205, 0xffff0000, v104
	v_lshlrev_b32_e32 v206, 16, v105
	v_and_b32_e32 v207, 0xffff0000, v105
	v_fmac_f32_e32 v210, v204, v204
	v_fmac_f32_e32 v211, v205, v205
	v_fmac_f32_e32 v210, v206, v206
; __device__ __forceinline__ float bf_lo(unsigned w) { return __uint_as_float(w << 16); }
; __device__ __forceinline__ float bf_hi(unsigned w) { return __uint_as_float(w & 0xffff0000u); }
; __global__ void __launch_bounds__(NWAVES * 64, 2) mk_fwd(Args args) {
;     ...
;                 float sy = 0.f;
; #pragma unroll
;                 for (int j = 0; j < 8; ++j) { const float a = bf_lo(yw[q][j].x), b = bf_hi(yw[q][j].x), c2 = bf_lo(yw[q][j].y), d = bf_hi(yw[q][j].y); sy += (a * a + b * b) + (c2 * c2 + d * d); }
;                 const float rsy = __builtin_amdgcn_rsqf(wave_sum(sy) * (1.f / DM) + EPS);
; #pragma unroll
;                 for (int j = 0; j < 8; ++j) { const int col = 4 * F.lane + 256 * j;
;                     const f32x4 y4 = (f32x4){bf_lo(yw[q][j].x), bf_hi(yw[q][j].x), bf_lo(yw[q][j].y), bf_hi(yw[q][j].y)};
;                     *(f32x4*)(args.out + (size_t)row * DM + col) = v[q][j] + PA[j] * (y4 * rsy); }
	v_fmac_f32_e32 v211, v207, v207
	v_lshlrev_b32_e32 v200, 16, v74
	v_and_b32_e32 v201, 0xffff0000, v74
	v_lshlrev_b32_e32 v202, 16, v75
	v_and_b32_e32 v203, 0xffff0000, v75
	v_fmac_f32_e32 v208, v200, v200
	v_fmac_f32_e32 v209, v201, v201
	v_fmac_f32_e32 v208, v202, v202
	v_fmac_f32_e32 v209, v203, v203
	v_lshlrev_b32_e32 v204, 16, v106
	v_and_b32_e32 v205, 0xffff0000, v106
	v_lshlrev_b32_e32 v206, 16, v107
	v_and_b32_e32 v207, 0xffff0000, v107
	v_fmac_f32_e32 v210, v204, v204
	v_fmac_f32_e32 v211, v205, v205
	v_fmac_f32_e32 v210, v206, v206
	v_fmac_f32_e32 v211, v207, v207
	v_lshlrev_b32_e32 v200, 16, v76
	v_and_b32_e32 v201, 0xffff0000, v76
	v_lshlrev_b32_e32 v202, 16, v77
	v_and_b32_e32 v203, 0xffff0000, v77
	v_fmac_f32_e32 v208, v200, v200
	v_fmac_f32_e32 v209, v201, v201
	v_fmac_f32_e32 v208, v202, v202
	v_fmac_f32_e32 v209, v203, v203
	v_lshlrev_b32_e32 v204, 16, v108
	v_and_b32_e32 v205, 0xffff0000, v108
	v_lshlrev_b32_e32 v206, 16, v109
	v_and_b32_e32 v207, 0xffff0000, v109
	v_fmac_f32_e32 v210, v204, v204
	v_fmac_f32_e32 v211, v205, v205
	v_fmac_f32_e32 v210, v206, v206
	v_fmac_f32_e32 v211, v207, v207
	v_lshlrev_b32_e32 v200, 16, v78
	v_and_b32_e32 v201, 0xffff0000, v78
	v_lshlrev_b32_e32 v202, 16, v79
	v_and_b32_e32 v203, 0xffff0000, v79
	v_fmac_f32_e32 v208, v200, v200
	v_fmac_f32_e32 v209, v201, v201
	v_fmac_f32_e32 v208, v202, v202
	v_fmac_f32_e32 v209, v203, v203
	v_lshlrev_b32_e32 v204, 16, v110
	v_and_b32_e32 v205, 0xffff0000, v110
	v_lshlrev_b32_e32 v206, 16, v111
	v_and_b32_e32 v207, 0xffff0000, v111
	v_fmac_f32_e32 v210, v204, v204
	v_fmac_f32_e32 v211, v205, v205
	v_fmac_f32_e32 v210, v206, v206
	v_fmac_f32_e32 v211, v207, v207
	v_add_f32_e32 v208, v208, v209
	v_add_f32_e32 v210, v210, v211
	s_nop 0
	v_add_f32_dpp v212, v208, v208 quad_perm:[1,0,3,2] row_mask:0xf bank_mask:0xf
	v_add_f32_dpp v213, v210, v210 quad_perm:[1,0,3,2] row_mask:0xf bank_mask:0xf
	s_nop 0
	v_add_f32_dpp v212, v212, v212 quad_perm:[2,3,0,1] row_mask:0xf bank_mask:0xf
	v_add_f32_dpp v213, v213, v213 quad_perm:[2,3,0,1] row_mask:0xf bank_mask:0xf
	s_nop 0
	v_add_f32_dpp v212, v212, v212 row_half_mirror row_mask:0xf bank_mask:0xf
	v_add_f32_dpp v213, v213, v213 row_half_mirror row_mask:0xf bank_mask:0xf
	s_nop 0
	v_add_f32_dpp v212, v212, v212 row_mirror row_mask:0xf bank_mask:0xf
	v_add_f32_dpp v213, v213, v213 row_mirror row_mask:0xf bank_mask:0xf
	s_nop 0
	v_readlane_b32 s4, v212, 0
	v_readlane_b32 s5, v212, 16
	v_readlane_b32 s6, v212, 32
	v_readlane_b32 s7, v212, 48
	v_readlane_b32 s24, v213, 0
	v_readlane_b32 s25, v213, 16
	v_readlane_b32 s26, v213, 32
	v_readlane_b32 s27, v213, 48
	s_nop 1
	v_mov_b32_e32 v214, s4
	v_mov_b32_e32 v215, s24
	v_add_f32_e32 v214, s5, v214
	v_add_f32_e32 v215, s25, v215
	v_add_f32_e32 v214, s6, v214
	v_add_f32_e32 v215, s26, v215
	v_add_f32_e32 v214, s7, v214
	v_add_f32_e32 v215, s27, v215
	v_fmamk_f32 v214, v214, 0x3a000000, v195
	v_fmamk_f32 v215, v215, 0x3a000000, v195
	v_rsq_f32_e32 v214, v214
	v_rsq_f32_e32 v215, v215
	s_nop 0
	v_lshlrev_b32_e32 v200, 16, v64
	v_and_b32_e32 v201, 0xffff0000, v64
	v_lshlrev_b32_e32 v202, 16, v65
	v_and_b32_e32 v203, 0xffff0000, v65
	v_lshlrev_b32_e32 v204, 16, v96
	v_and_b32_e32 v205, 0xffff0000, v96
	v_lshlrev_b32_e32 v206, 16, v97
	v_and_b32_e32 v207, 0xffff0000, v97
	v_mul_f32_e32 v200, v214, v200
	v_mul_f32_e32 v201, v214, v201
	v_mul_f32_e32 v202, v214, v202
	v_mul_f32_e32 v203, v214, v203
	v_mul_f32_e32 v204, v215, v204
	v_mul_f32_e32 v205, v215, v205
	v_mul_f32_e32 v206, v215, v206
	v_mul_f32_e32 v207, v215, v207
	v_fmac_f32_e32 v0, v128, v200
	v_fmac_f32_e32 v1, v129, v201
	v_fmac_f32_e32 v2, v130, v202
	v_fmac_f32_e32 v3, v131, v203
	v_fmac_f32_e32 v0, v160, v204
	v_fmac_f32_e32 v1, v161, v205
	v_fmac_f32_e32 v2, v162, v206
	v_fmac_f32_e32 v3, v163, v207
	global_store_dwordx4 v192, v[0:3], s[18:19] offset:0
	v_lshlrev_b32_e32 v200, 16, v66
	v_and_b32_e32 v201, 0xffff0000, v66
	v_lshlrev_b32_e32 v202, 16, v67
	v_and_b32_e32 v203, 0xffff0000, v67
	v_lshlrev_b32_e32 v204, 16, v98
	v_and_b32_e32 v205, 0xffff0000, v98
	v_lshlrev_b32_e32 v206, 16, v99
	v_and_b32_e32 v207, 0xffff0000, v99
	v_mul_f32_e32 v200, v214, v200
	v_mul_f32_e32 v201, v214, v201
	v_mul_f32_e32 v202, v214, v202
	v_mul_f32_e32 v203, v214, v203
	v_mul_f32_e32 v204, v215, v204
	v_mul_f32_e32 v205, v215, v205
	v_mul_f32_e32 v206, v215, v206
	v_mul_f32_e32 v207, v215, v207
	v_fmac_f32_e32 v4, v132, v200
	v_fmac_f32_e32 v5, v133, v201
	v_fmac_f32_e32 v6, v134, v202
	v_fmac_f32_e32 v7, v135, v203
	v_fmac_f32_e32 v4, v164, v204
	v_fmac_f32_e32 v5, v165, v205
	v_fmac_f32_e32 v6, v166, v206
	v_fmac_f32_e32 v7, v167, v207
	global_store_dwordx4 v192, v[4:7], s[18:19] offset:1024
	v_lshlrev_b32_e32 v200, 16, v68
	v_and_b32_e32 v201, 0xffff0000, v68
	v_lshlrev_b32_e32 v202, 16, v69
	v_and_b32_e32 v203, 0xffff0000, v69
	v_lshlrev_b32_e32 v204, 16, v100
	v_and_b32_e32 v205, 0xffff0000, v100
	v_lshlrev_b32_e32 v206, 16, v101
	v_and_b32_e32 v207, 0xffff0000, v101
	v_mul_f32_e32 v200, v214, v200
	v_mul_f32_e32 v201, v214, v201
	v_mul_f32_e32 v202, v214, v202
	v_mul_f32_e32 v203, v214, v203
	v_mul_f32_e32 v204, v215, v204
	v_mul_f32_e32 v205, v215, v205
	v_mul_f32_e32 v206, v215, v206
	v_mul_f32_e32 v207, v215, v207
	v_fmac_f32_e32 v8, v136, v200
	v_fmac_f32_e32 v9, v137, v201
	v_fmac_f32_e32 v10, v138, v202
	v_fmac_f32_e32 v11, v139, v203
	v_fmac_f32_e32 v8, v168, v204
	v_fmac_f32_e32 v9, v169, v205
	v_fmac_f32_e32 v10, v170, v206
	v_fmac_f32_e32 v11, v171, v207
	global_store_dwordx4 v192, v[8:11], s[18:19] offset:2048
	v_lshlrev_b32_e32 v200, 16, v70
	v_and_b32_e32 v201, 0xffff0000, v70
	v_lshlrev_b32_e32 v202, 16, v71
; __device__ __forceinline__ float bf_lo(unsigned w) { return __uint_as_float(w << 16); }
; __device__ __forceinline__ float bf_hi(unsigned w) { return __uint_as_float(w & 0xffff0000u); }
; __global__ void __launch_bounds__(NWAVES * 64, 2) mk_fwd(Args args) {
;     ...
;             for (int q = 0; q < 2; ++q) { const int row = row0 + q; load_row_f32(args.out + (size_t)row * DM, F.lane, v[q]);
;                 const bf16_t* yr = Y + (size_t)row * DM;
; #pragma unroll
;                 for (int j = 0; j < 8; ++j) yw[q][j] = *(const u32x2*)(yr + 4 * F.lane + 256 * j); }
;     ...
; #pragma unroll
;                 for (int j = 0; j < 8; ++j) { const int col = 4 * F.lane + 256 * j;
;                     const f32x4 y4 = (f32x4){bf_lo(yw[q][j].x), bf_hi(yw[q][j].x), bf_lo(yw[q][j].y), bf_hi(yw[q][j].y)};
;                     *(f32x4*)(args.out + (size_t)row * DM + col) = v[q][j] + PA[j] * (y4 * rsy); }
	v_and_b32_e32 v203, 0xffff0000, v71
	v_lshlrev_b32_e32 v204, 16, v102
	v_and_b32_e32 v205, 0xffff0000, v102
	v_lshlrev_b32_e32 v206, 16, v103
	v_and_b32_e32 v207, 0xffff0000, v103
	v_mul_f32_e32 v200, v214, v200
	v_mul_f32_e32 v201, v214, v201
	v_mul_f32_e32 v202, v214, v202
	v_mul_f32_e32 v203, v214, v203
	v_mul_f32_e32 v204, v215, v204
	v_mul_f32_e32 v205, v215, v205
	v_mul_f32_e32 v206, v215, v206
	v_mul_f32_e32 v207, v215, v207
	v_fmac_f32_e32 v12, v140, v200
	v_fmac_f32_e32 v13, v141, v201
	v_fmac_f32_e32 v14, v142, v202
	v_fmac_f32_e32 v15, v143, v203
	v_fmac_f32_e32 v12, v172, v204
	v_fmac_f32_e32 v13, v173, v205
	v_fmac_f32_e32 v14, v174, v206
	v_fmac_f32_e32 v15, v175, v207
	global_store_dwordx4 v192, v[12:15], s[18:19] offset:3072
	v_lshlrev_b32_e32 v200, 16, v72
	v_and_b32_e32 v201, 0xffff0000, v72
	v_lshlrev_b32_e32 v202, 16, v73
	v_and_b32_e32 v203, 0xffff0000, v73
	v_lshlrev_b32_e32 v204, 16, v104
	v_and_b32_e32 v205, 0xffff0000, v104
	v_lshlrev_b32_e32 v206, 16, v105
	v_and_b32_e32 v207, 0xffff0000, v105
	v_mul_f32_e32 v200, v214, v200
	v_mul_f32_e32 v201, v214, v201
	v_mul_f32_e32 v202, v214, v202
	v_mul_f32_e32 v203, v214, v203
	v_mul_f32_e32 v204, v215, v204
	v_mul_f32_e32 v205, v215, v205
	v_mul_f32_e32 v206, v215, v206
	v_mul_f32_e32 v207, v215, v207
	v_fmac_f32_e32 v16, v144, v200
	v_fmac_f32_e32 v17, v145, v201
	v_fmac_f32_e32 v18, v146, v202
	v_fmac_f32_e32 v19, v147, v203
	v_fmac_f32_e32 v16, v176, v204
	v_fmac_f32_e32 v17, v177, v205
	v_fmac_f32_e32 v18, v178, v206
	v_fmac_f32_e32 v19, v179, v207
	global_store_dwordx4 v193, v[16:19], s[18:19] offset:0
	v_lshlrev_b32_e32 v200, 16, v74
	v_and_b32_e32 v201, 0xffff0000, v74
	v_lshlrev_b32_e32 v202, 16, v75
	v_and_b32_e32 v203, 0xffff0000, v75
	v_lshlrev_b32_e32 v204, 16, v106
	v_and_b32_e32 v205, 0xffff0000, v106
	v_lshlrev_b32_e32 v206, 16, v107
	v_and_b32_e32 v207, 0xffff0000, v107
	v_mul_f32_e32 v200, v214, v200
	v_mul_f32_e32 v201, v214, v201
	v_mul_f32_e32 v202, v214, v202
	v_mul_f32_e32 v203, v214, v203
	v_mul_f32_e32 v204, v215, v204
	v_mul_f32_e32 v205, v215, v205
	v_mul_f32_e32 v206, v215, v206
	v_mul_f32_e32 v207, v215, v207
	v_fmac_f32_e32 v20, v148, v200
	v_fmac_f32_e32 v21, v149, v201
	v_fmac_f32_e32 v22, v150, v202
	v_fmac_f32_e32 v23, v151, v203
	v_fmac_f32_e32 v20, v180, v204
	v_fmac_f32_e32 v21, v181, v205
	v_fmac_f32_e32 v22, v182, v206
	v_fmac_f32_e32 v23, v183, v207
	global_store_dwordx4 v193, v[20:23], s[18:19] offset:1024
	v_lshlrev_b32_e32 v200, 16, v76
	v_and_b32_e32 v201, 0xffff0000, v76
	v_lshlrev_b32_e32 v202, 16, v77
	v_and_b32_e32 v203, 0xffff0000, v77
	v_lshlrev_b32_e32 v204, 16, v108
	v_and_b32_e32 v205, 0xffff0000, v108
	v_lshlrev_b32_e32 v206, 16, v109
	v_and_b32_e32 v207, 0xffff0000, v109
	v_mul_f32_e32 v200, v214, v200
	v_mul_f32_e32 v201, v214, v201
	v_mul_f32_e32 v202, v214, v202
	v_mul_f32_e32 v203, v214, v203
	v_mul_f32_e32 v204, v215, v204
	v_mul_f32_e32 v205, v215, v205
	v_mul_f32_e32 v206, v215, v206
	v_mul_f32_e32 v207, v215, v207
	v_fmac_f32_e32 v24, v152, v200
	v_fmac_f32_e32 v25, v153, v201
	v_fmac_f32_e32 v26, v154, v202
	v_fmac_f32_e32 v27, v155, v203
	v_fmac_f32_e32 v24, v184, v204
	v_fmac_f32_e32 v25, v185, v205
	v_fmac_f32_e32 v26, v186, v206
	v_fmac_f32_e32 v27, v187, v207
	global_store_dwordx4 v193, v[24:27], s[18:19] offset:2048
	v_lshlrev_b32_e32 v200, 16, v78
	v_and_b32_e32 v201, 0xffff0000, v78
	v_lshlrev_b32_e32 v202, 16, v79
	v_and_b32_e32 v203, 0xffff0000, v79
	v_lshlrev_b32_e32 v204, 16, v110
	v_and_b32_e32 v205, 0xffff0000, v110
	v_lshlrev_b32_e32 v206, 16, v111
	v_and_b32_e32 v207, 0xffff0000, v111
	v_mul_f32_e32 v200, v214, v200
	v_mul_f32_e32 v201, v214, v201
	v_mul_f32_e32 v202, v214, v202
	v_mul_f32_e32 v203, v214, v203
	v_mul_f32_e32 v204, v215, v204
	v_mul_f32_e32 v205, v215, v205
	v_mul_f32_e32 v206, v215, v206
	v_mul_f32_e32 v207, v215, v207
	v_fmac_f32_e32 v28, v156, v200
	v_fmac_f32_e32 v29, v157, v201
	v_fmac_f32_e32 v30, v158, v202
	v_fmac_f32_e32 v31, v159, v203
	v_fmac_f32_e32 v28, v188, v204
	v_fmac_f32_e32 v29, v189, v205
	v_fmac_f32_e32 v30, v190, v206
	v_fmac_f32_e32 v31, v191, v207
	global_store_dwordx4 v193, v[28:31], s[18:19] offset:3072
	s_add_u32 s18, s18, 0x2000
	s_addc_u32 s19, s19, 0
	global_load_dwordx4 v[0:3], v192, s[14:15] offset:0 nt
	global_load_dwordx4 v[4:7], v192, s[14:15] offset:1024 nt
	global_load_dwordx4 v[8:11], v192, s[14:15] offset:2048 nt
	global_load_dwordx4 v[12:15], v192, s[14:15] offset:3072 nt
	global_load_dwordx4 v[16:19], v193, s[14:15] offset:0 nt
	global_load_dwordx4 v[20:23], v193, s[14:15] offset:1024 nt
	global_load_dwordx4 v[24:27], v193, s[14:15] offset:2048 nt
	global_load_dwordx4 v[28:31], v193, s[14:15] offset:3072 nt
	global_load_dwordx2 v[64:65], v194, s[16:17] offset:0 nt
	global_load_dwordx2 v[66:67], v194, s[16:17] offset:512 nt
	global_load_dwordx2 v[68:69], v194, s[16:17] offset:1024 nt
	global_load_dwordx2 v[70:71], v194, s[16:17] offset:1536 nt
	global_load_dwordx2 v[72:73], v194, s[16:17] offset:2048 nt
	global_load_dwordx2 v[74:75], v194, s[16:17] offset:2560 nt
	global_load_dwordx2 v[76:77], v194, s[16:17] offset:3072 nt
	global_load_dwordx2 v[78:79], v194, s[16:17] offset:3584 nt
	global_load_dwordx2 v[96:97], v194, s[22:23] offset:0 nt
	global_load_dwordx2 v[98:99], v194, s[22:23] offset:512 nt
	global_load_dwordx2 v[100:101], v194, s[22:23] offset:1024 nt
	global_load_dwordx2 v[102:103], v194, s[22:23] offset:1536 nt
	global_load_dwordx2 v[104:105], v194, s[22:23] offset:2048 nt
	global_load_dwordx2 v[106:107], v194, s[22:23] offset:2560 nt
	global_load_dwordx2 v[108:109], v194, s[22:23] offset:3072 nt
	global_load_dwordx2 v[110:111], v194, s[22:23] offset:3584 nt
	s_add_u32 s14, s14, 0x2000
	s_addc_u32 s15, s15, 0
	s_add_u32 s16, s16, 0x1000
	s_addc_u32 s17, s17, 0
	s_add_u32 s22, s22, 0x1000
	s_addc_u32 s23, s23, 0
	s_waitcnt vmcnt(32)
; __device__ __forceinline__ float bf_lo(unsigned w) { return __uint_as_float(w << 16); }
; __device__ __forceinline__ float bf_hi(unsigned w) { return __uint_as_float(w & 0xffff0000u); }
; __global__ void __launch_bounds__(NWAVES * 64, 2) mk_fwd(Args args) {
;     ...
;                 float sy = 0.f;
; #pragma unroll
;                 for (int j = 0; j < 8; ++j) { const float a = bf_lo(yw[q][j].x), b = bf_hi(yw[q][j].x), c2 = bf_lo(yw[q][j].y), d = bf_hi(yw[q][j].y); sy += (a * a + b * b) + (c2 * c2 + d * d); }
;                 const float rsy = __builtin_amdgcn_rsqf(wave_sum(sy) * (1.f / DM) + EPS);
	v_lshlrev_b32_e32 v200, 16, v80
	v_and_b32_e32 v201, 0xffff0000, v80
	v_lshlrev_b32_e32 v202, 16, v81
	v_and_b32_e32 v203, 0xffff0000, v81
	v_mul_f32_e32 v208, v200, v200
	v_mul_f32_e32 v209, v201, v201
	v_fmac_f32_e32 v208, v202, v202
	v_fmac_f32_e32 v209, v203, v203
	v_lshlrev_b32_e32 v204, 16, v112
	v_and_b32_e32 v205, 0xffff0000, v112
	v_lshlrev_b32_e32 v206, 16, v113
	v_and_b32_e32 v207, 0xffff0000, v113
	v_mul_f32_e32 v210, v204, v204
	v_mul_f32_e32 v211, v205, v205
	v_fmac_f32_e32 v210, v206, v206
	v_fmac_f32_e32 v211, v207, v207
	v_lshlrev_b32_e32 v200, 16, v82
	v_and_b32_e32 v201, 0xffff0000, v82
	v_lshlrev_b32_e32 v202, 16, v83
	v_and_b32_e32 v203, 0xffff0000, v83
	v_fmac_f32_e32 v208, v200, v200
	v_fmac_f32_e32 v209, v201, v201
	v_fmac_f32_e32 v208, v202, v202
	v_fmac_f32_e32 v209, v203, v203
	v_lshlrev_b32_e32 v204, 16, v114
	v_and_b32_e32 v205, 0xffff0000, v114
	v_lshlrev_b32_e32 v206, 16, v115
	v_and_b32_e32 v207, 0xffff0000, v115
	v_fmac_f32_e32 v210, v204, v204
	v_fmac_f32_e32 v211, v205, v205
	v_fmac_f32_e32 v210, v206, v206
	v_fmac_f32_e32 v211, v207, v207
	v_lshlrev_b32_e32 v200, 16, v84
	v_and_b32_e32 v201, 0xffff0000, v84
	v_lshlrev_b32_e32 v202, 16, v85
	v_and_b32_e32 v203, 0xffff0000, v85
	v_fmac_f32_e32 v208, v200, v200
	v_fmac_f32_e32 v209, v201, v201
	v_fmac_f32_e32 v208, v202, v202
	v_fmac_f32_e32 v209, v203, v203
	v_lshlrev_b32_e32 v204, 16, v116
	v_and_b32_e32 v205, 0xffff0000, v116
	v_lshlrev_b32_e32 v206, 16, v117
	v_and_b32_e32 v207, 0xffff0000, v117
	v_fmac_f32_e32 v210, v204, v204
	v_fmac_f32_e32 v211, v205, v205
	v_fmac_f32_e32 v210, v206, v206
	v_fmac_f32_e32 v211, v207, v207
	v_lshlrev_b32_e32 v200, 16, v86
	v_and_b32_e32 v201, 0xffff0000, v86
	v_lshlrev_b32_e32 v202, 16, v87
	v_and_b32_e32 v203, 0xffff0000, v87
	v_fmac_f32_e32 v208, v200, v200
	v_fmac_f32_e32 v209, v201, v201
	v_fmac_f32_e32 v208, v202, v202
	v_fmac_f32_e32 v209, v203, v203
	v_lshlrev_b32_e32 v204, 16, v118
	v_and_b32_e32 v205, 0xffff0000, v118
	v_lshlrev_b32_e32 v206, 16, v119
	v_and_b32_e32 v207, 0xffff0000, v119
	v_fmac_f32_e32 v210, v204, v204
	v_fmac_f32_e32 v211, v205, v205
	v_fmac_f32_e32 v210, v206, v206
	v_fmac_f32_e32 v211, v207, v207
	v_lshlrev_b32_e32 v200, 16, v88
	v_and_b32_e32 v201, 0xffff0000, v88
	v_lshlrev_b32_e32 v202, 16, v89
	v_and_b32_e32 v203, 0xffff0000, v89
	v_fmac_f32_e32 v208, v200, v200
	v_fmac_f32_e32 v209, v201, v201
	v_fmac_f32_e32 v208, v202, v202
	v_fmac_f32_e32 v209, v203, v203
	v_lshlrev_b32_e32 v204, 16, v120
	v_and_b32_e32 v205, 0xffff0000, v120
	v_lshlrev_b32_e32 v206, 16, v121
	v_and_b32_e32 v207, 0xffff0000, v121
	v_fmac_f32_e32 v210, v204, v204
	v_fmac_f32_e32 v211, v205, v205
	v_fmac_f32_e32 v210, v206, v206
	v_fmac_f32_e32 v211, v207, v207
	v_lshlrev_b32_e32 v200, 16, v90
	v_and_b32_e32 v201, 0xffff0000, v90
	v_lshlrev_b32_e32 v202, 16, v91
	v_and_b32_e32 v203, 0xffff0000, v91
	v_fmac_f32_e32 v208, v200, v200
	v_fmac_f32_e32 v209, v201, v201
	v_fmac_f32_e32 v208, v202, v202
	v_fmac_f32_e32 v209, v203, v203
	v_lshlrev_b32_e32 v204, 16, v122
	v_and_b32_e32 v205, 0xffff0000, v122
	v_lshlrev_b32_e32 v206, 16, v123
	v_and_b32_e32 v207, 0xffff0000, v123
	v_fmac_f32_e32 v210, v204, v204
	v_fmac_f32_e32 v211, v205, v205
	v_fmac_f32_e32 v210, v206, v206
	v_fmac_f32_e32 v211, v207, v207
	v_lshlrev_b32_e32 v200, 16, v92
	v_and_b32_e32 v201, 0xffff0000, v92
	v_lshlrev_b32_e32 v202, 16, v93
	v_and_b32_e32 v203, 0xffff0000, v93
	v_fmac_f32_e32 v208, v200, v200
	v_fmac_f32_e32 v209, v201, v201
	v_fmac_f32_e32 v208, v202, v202
	v_fmac_f32_e32 v209, v203, v203
	v_lshlrev_b32_e32 v204, 16, v124
	v_and_b32_e32 v205, 0xffff0000, v124
	v_lshlrev_b32_e32 v206, 16, v125
	v_and_b32_e32 v207, 0xffff0000, v125
	v_fmac_f32_e32 v210, v204, v204
	v_fmac_f32_e32 v211, v205, v205
	v_fmac_f32_e32 v210, v206, v206
	v_fmac_f32_e32 v211, v207, v207
	v_lshlrev_b32_e32 v200, 16, v94
	v_and_b32_e32 v201, 0xffff0000, v94
	v_lshlrev_b32_e32 v202, 16, v95
	v_and_b32_e32 v203, 0xffff0000, v95
	v_fmac_f32_e32 v208, v200, v200
	v_fmac_f32_e32 v209, v201, v201
	v_fmac_f32_e32 v208, v202, v202
	v_fmac_f32_e32 v209, v203, v203
	v_lshlrev_b32_e32 v204, 16, v126
	v_and_b32_e32 v205, 0xffff0000, v126
	v_lshlrev_b32_e32 v206, 16, v127
	v_and_b32_e32 v207, 0xffff0000, v127
	v_fmac_f32_e32 v210, v204, v204
	v_fmac_f32_e32 v211, v205, v205
	v_fmac_f32_e32 v210, v206, v206
	v_fmac_f32_e32 v211, v207, v207
	v_add_f32_e32 v208, v208, v209
	v_add_f32_e32 v210, v210, v211
	s_nop 0
	v_add_f32_dpp v212, v208, v208 quad_perm:[1,0,3,2] row_mask:0xf bank_mask:0xf
	v_add_f32_dpp v213, v210, v210 quad_perm:[1,0,3,2] row_mask:0xf bank_mask:0xf
	s_nop 0
	v_add_f32_dpp v212, v212, v212 quad_perm:[2,3,0,1] row_mask:0xf bank_mask:0xf
	v_add_f32_dpp v213, v213, v213 quad_perm:[2,3,0,1] row_mask:0xf bank_mask:0xf
	s_nop 0
	v_add_f32_dpp v212, v212, v212 row_half_mirror row_mask:0xf bank_mask:0xf
	v_add_f32_dpp v213, v213, v213 row_half_mirror row_mask:0xf bank_mask:0xf
	s_nop 0
	v_add_f32_dpp v212, v212, v212 row_mirror row_mask:0xf bank_mask:0xf
	v_add_f32_dpp v213, v213, v213 row_mirror row_mask:0xf bank_mask:0xf
	s_nop 0
	v_readlane_b32 s4, v212, 0
	v_readlane_b32 s5, v212, 16
	v_readlane_b32 s6, v212, 32
	v_readlane_b32 s7, v212, 48
	v_readlane_b32 s24, v213, 0
	v_readlane_b32 s25, v213, 16
	v_readlane_b32 s26, v213, 32
	v_readlane_b32 s27, v213, 48
	s_nop 1
	v_mov_b32_e32 v214, s4
	v_mov_b32_e32 v215, s24
	v_add_f32_e32 v214, s5, v214
	v_add_f32_e32 v215, s25, v215
	v_add_f32_e32 v214, s6, v214
	v_add_f32_e32 v215, s26, v215
	v_add_f32_e32 v214, s7, v214
	v_add_f32_e32 v215, s27, v215
	v_fmamk_f32 v214, v214, 0x3a000000, v195
	v_fmamk_f32 v215, v215, 0x3a000000, v195
; __device__ __forceinline__ float bf_lo(unsigned w) { return __uint_as_float(w << 16); }
; __device__ __forceinline__ float bf_hi(unsigned w) { return __uint_as_float(w & 0xffff0000u); }
; __global__ void __launch_bounds__(NWAVES * 64, 2) mk_fwd(Args args) {
;     ...
; #pragma unroll
;                 for (int j = 0; j < 8; ++j) { const int col = 4 * F.lane + 256 * j;
;                     const f32x4 y4 = (f32x4){bf_lo(yw[q][j].x), bf_hi(yw[q][j].x), bf_lo(yw[q][j].y), bf_hi(yw[q][j].y)};
;                     *(f32x4*)(args.out + (size_t)row * DM + col) = v[q][j] + PA[j] * (y4 * rsy); }
	v_rsq_f32_e32 v214, v214
	v_rsq_f32_e32 v215, v215
	s_nop 0
	v_lshlrev_b32_e32 v200, 16, v80
	v_and_b32_e32 v201, 0xffff0000, v80
	v_lshlrev_b32_e32 v202, 16, v81
	v_and_b32_e32 v203, 0xffff0000, v81
	v_lshlrev_b32_e32 v204, 16, v112
	v_and_b32_e32 v205, 0xffff0000, v112
	v_lshlrev_b32_e32 v206, 16, v113
	v_and_b32_e32 v207, 0xffff0000, v113
	v_mul_f32_e32 v200, v214, v200
	v_mul_f32_e32 v201, v214, v201
	v_mul_f32_e32 v202, v214, v202
	v_mul_f32_e32 v203, v214, v203
	v_mul_f32_e32 v204, v215, v204
	v_mul_f32_e32 v205, v215, v205
	v_mul_f32_e32 v206, v215, v206
	v_mul_f32_e32 v207, v215, v207
	v_fmac_f32_e32 v32, v128, v200
	v_fmac_f32_e32 v33, v129, v201
	v_fmac_f32_e32 v34, v130, v202
	v_fmac_f32_e32 v35, v131, v203
	v_fmac_f32_e32 v32, v160, v204
	v_fmac_f32_e32 v33, v161, v205
	v_fmac_f32_e32 v34, v162, v206
	v_fmac_f32_e32 v35, v163, v207
	global_store_dwordx4 v192, v[32:35], s[18:19] offset:0
	v_lshlrev_b32_e32 v200, 16, v82
	v_and_b32_e32 v201, 0xffff0000, v82
	v_lshlrev_b32_e32 v202, 16, v83
	v_and_b32_e32 v203, 0xffff0000, v83
	v_lshlrev_b32_e32 v204, 16, v114
	v_and_b32_e32 v205, 0xffff0000, v114
	v_lshlrev_b32_e32 v206, 16, v115
	v_and_b32_e32 v207, 0xffff0000, v115
	v_mul_f32_e32 v200, v214, v200
	v_mul_f32_e32 v201, v214, v201
	v_mul_f32_e32 v202, v214, v202
	v_mul_f32_e32 v203, v214, v203
	v_mul_f32_e32 v204, v215, v204
	v_mul_f32_e32 v205, v215, v205
	v_mul_f32_e32 v206, v215, v206
	v_mul_f32_e32 v207, v215, v207
	v_fmac_f32_e32 v36, v132, v200
	v_fmac_f32_e32 v37, v133, v201
	v_fmac_f32_e32 v38, v134, v202
	v_fmac_f32_e32 v39, v135, v203
	v_fmac_f32_e32 v36, v164, v204
	v_fmac_f32_e32 v37, v165, v205
	v_fmac_f32_e32 v38, v166, v206
	v_fmac_f32_e32 v39, v167, v207
	global_store_dwordx4 v192, v[36:39], s[18:19] offset:1024
	v_lshlrev_b32_e32 v200, 16, v84
	v_and_b32_e32 v201, 0xffff0000, v84
	v_lshlrev_b32_e32 v202, 16, v85
	v_and_b32_e32 v203, 0xffff0000, v85
	v_lshlrev_b32_e32 v204, 16, v116
	v_and_b32_e32 v205, 0xffff0000, v116
	v_lshlrev_b32_e32 v206, 16, v117
	v_and_b32_e32 v207, 0xffff0000, v117
	v_mul_f32_e32 v200, v214, v200
	v_mul_f32_e32 v201, v214, v201
	v_mul_f32_e32 v202, v214, v202
	v_mul_f32_e32 v203, v214, v203
	v_mul_f32_e32 v204, v215, v204
	v_mul_f32_e32 v205, v215, v205
	v_mul_f32_e32 v206, v215, v206
	v_mul_f32_e32 v207, v215, v207
	v_fmac_f32_e32 v40, v136, v200
	v_fmac_f32_e32 v41, v137, v201
	v_fmac_f32_e32 v42, v138, v202
	v_fmac_f32_e32 v43, v139, v203
	v_fmac_f32_e32 v40, v168, v204
	v_fmac_f32_e32 v41, v169, v205
	v_fmac_f32_e32 v42, v170, v206
	v_fmac_f32_e32 v43, v171, v207
	global_store_dwordx4 v192, v[40:43], s[18:19] offset:2048
	v_lshlrev_b32_e32 v200, 16, v86
	v_and_b32_e32 v201, 0xffff0000, v86
	v_lshlrev_b32_e32 v202, 16, v87
	v_and_b32_e32 v203, 0xffff0000, v87
	v_lshlrev_b32_e32 v204, 16, v118
	v_and_b32_e32 v205, 0xffff0000, v118
	v_lshlrev_b32_e32 v206, 16, v119
	v_and_b32_e32 v207, 0xffff0000, v119
	v_mul_f32_e32 v200, v214, v200
	v_mul_f32_e32 v201, v214, v201
	v_mul_f32_e32 v202, v214, v202
	v_mul_f32_e32 v203, v214, v203
	v_mul_f32_e32 v204, v215, v204
	v_mul_f32_e32 v205, v215, v205
	v_mul_f32_e32 v206, v215, v206
	v_mul_f32_e32 v207, v215, v207
	v_fmac_f32_e32 v44, v140, v200
	v_fmac_f32_e32 v45, v141, v201
	v_fmac_f32_e32 v46, v142, v202
	v_fmac_f32_e32 v47, v143, v203
	v_fmac_f32_e32 v44, v172, v204
	v_fmac_f32_e32 v45, v173, v205
	v_fmac_f32_e32 v46, v174, v206
	v_fmac_f32_e32 v47, v175, v207
	global_store_dwordx4 v192, v[44:47], s[18:19] offset:3072
	v_lshlrev_b32_e32 v200, 16, v88
	v_and_b32_e32 v201, 0xffff0000, v88
	v_lshlrev_b32_e32 v202, 16, v89
	v_and_b32_e32 v203, 0xffff0000, v89
	v_lshlrev_b32_e32 v204, 16, v120
	v_and_b32_e32 v205, 0xffff0000, v120
	v_lshlrev_b32_e32 v206, 16, v121
	v_and_b32_e32 v207, 0xffff0000, v121
	v_mul_f32_e32 v200, v214, v200
	v_mul_f32_e32 v201, v214, v201
	v_mul_f32_e32 v202, v214, v202
	v_mul_f32_e32 v203, v214, v203
	v_mul_f32_e32 v204, v215, v204
	v_mul_f32_e32 v205, v215, v205
	v_mul_f32_e32 v206, v215, v206
	v_mul_f32_e32 v207, v215, v207
	v_fmac_f32_e32 v48, v144, v200
	v_fmac_f32_e32 v49, v145, v201
	v_fmac_f32_e32 v50, v146, v202
	v_fmac_f32_e32 v51, v147, v203
	v_fmac_f32_e32 v48, v176, v204
	v_fmac_f32_e32 v49, v177, v205
	v_fmac_f32_e32 v50, v178, v206
	v_fmac_f32_e32 v51, v179, v207
	global_store_dwordx4 v193, v[48:51], s[18:19] offset:0
	v_lshlrev_b32_e32 v200, 16, v90
	v_and_b32_e32 v201, 0xffff0000, v90
	v_lshlrev_b32_e32 v202, 16, v91
	v_and_b32_e32 v203, 0xffff0000, v91
	v_lshlrev_b32_e32 v204, 16, v122
	v_and_b32_e32 v205, 0xffff0000, v122
	v_lshlrev_b32_e32 v206, 16, v123
	v_and_b32_e32 v207, 0xffff0000, v123
	v_mul_f32_e32 v200, v214, v200
	v_mul_f32_e32 v201, v214, v201
	v_mul_f32_e32 v202, v214, v202
	v_mul_f32_e32 v203, v214, v203
	v_mul_f32_e32 v204, v215, v204
	v_mul_f32_e32 v205, v215, v205
	v_mul_f32_e32 v206, v215, v206
	v_mul_f32_e32 v207, v215, v207
	v_fmac_f32_e32 v52, v148, v200
	v_fmac_f32_e32 v53, v149, v201
	v_fmac_f32_e32 v54, v150, v202
	v_fmac_f32_e32 v55, v151, v203
	v_fmac_f32_e32 v52, v180, v204
	v_fmac_f32_e32 v53, v181, v205
	v_fmac_f32_e32 v54, v182, v206
	v_fmac_f32_e32 v55, v183, v207
	global_store_dwordx4 v193, v[52:55], s[18:19] offset:1024
	v_lshlrev_b32_e32 v200, 16, v92
	v_and_b32_e32 v201, 0xffff0000, v92
	v_lshlrev_b32_e32 v202, 16, v93
	v_and_b32_e32 v203, 0xffff0000, v93
	v_lshlrev_b32_e32 v204, 16, v124
	v_and_b32_e32 v205, 0xffff0000, v124
	v_lshlrev_b32_e32 v206, 16, v125
	v_and_b32_e32 v207, 0xffff0000, v125
	v_mul_f32_e32 v200, v214, v200
	v_mul_f32_e32 v201, v214, v201
	v_mul_f32_e32 v202, v214, v202
	v_mul_f32_e32 v203, v214, v203
	v_mul_f32_e32 v204, v215, v204
; __device__ __forceinline__ float bf_lo(unsigned w) { return __uint_as_float(w << 16); }
; __device__ __forceinline__ float bf_hi(unsigned w) { return __uint_as_float(w & 0xffff0000u); }
; __global__ void __launch_bounds__(NWAVES * 64, 2) mk_fwd(Args args) {
;     ...
;             for (int q = 0; q < 2; ++q) { const int row = row0 + q; load_row_f32(args.out + (size_t)row * DM, F.lane, v[q]);
;                 const bf16_t* yr = Y + (size_t)row * DM;
; #pragma unroll
;                 for (int j = 0; j < 8; ++j) yw[q][j] = *(const u32x2*)(yr + 4 * F.lane + 256 * j); }
; #pragma unroll
;             for (int q = 0; q < 2; ++q) { const int row = row0 + q; const int r = row / SEQ;
;                 if (r != rcur) { const float* m1 = mod + (size_t)(9 + r) * 6144; rcur = r;
; #pragma unroll
;                     for (int j = 0; j < 8; ++j) { const int col = 4 * F.lane + 256 * j; PA[j] = *(const f32x4*)(m1 + 2 * DM + col) * *(const f32x4*)(post_norm + DM + col); } }
;                 float sy = 0.f;
; #pragma unroll
;                 for (int j = 0; j < 8; ++j) { const float a = bf_lo(yw[q][j].x), b = bf_hi(yw[q][j].x), c2 = bf_lo(yw[q][j].y), d = bf_hi(yw[q][j].y); sy += (a * a + b * b) + (c2 * c2 + d * d); }
;     ...
; #pragma unroll
;                 for (int j = 0; j < 8; ++j) { const int col = 4 * F.lane + 256 * j;
;                     const f32x4 y4 = (f32x4){bf_lo(yw[q][j].x), bf_hi(yw[q][j].x), bf_lo(yw[q][j].y), bf_hi(yw[q][j].y)};
;                     *(f32x4*)(args.out + (size_t)row * DM + col) = v[q][j] + PA[j] * (y4 * rsy); }
	v_mul_f32_e32 v205, v215, v205
	v_mul_f32_e32 v206, v215, v206
	v_mul_f32_e32 v207, v215, v207
	v_fmac_f32_e32 v56, v152, v200
	v_fmac_f32_e32 v57, v153, v201
	v_fmac_f32_e32 v58, v154, v202
	v_fmac_f32_e32 v59, v155, v203
	v_fmac_f32_e32 v56, v184, v204
	v_fmac_f32_e32 v57, v185, v205
	v_fmac_f32_e32 v58, v186, v206
	v_fmac_f32_e32 v59, v187, v207
	global_store_dwordx4 v193, v[56:59], s[18:19] offset:2048
	v_lshlrev_b32_e32 v200, 16, v94
	v_and_b32_e32 v201, 0xffff0000, v94
	v_lshlrev_b32_e32 v202, 16, v95
	v_and_b32_e32 v203, 0xffff0000, v95
	v_lshlrev_b32_e32 v204, 16, v126
	v_and_b32_e32 v205, 0xffff0000, v126
	v_lshlrev_b32_e32 v206, 16, v127
	v_and_b32_e32 v207, 0xffff0000, v127
	v_mul_f32_e32 v200, v214, v200
	v_mul_f32_e32 v201, v214, v201
	v_mul_f32_e32 v202, v214, v202
	v_mul_f32_e32 v203, v214, v203
	v_mul_f32_e32 v204, v215, v204
	v_mul_f32_e32 v205, v215, v205
	v_mul_f32_e32 v206, v215, v206
	v_mul_f32_e32 v207, v215, v207
	v_fmac_f32_e32 v60, v156, v200
	v_fmac_f32_e32 v61, v157, v201
	v_fmac_f32_e32 v62, v158, v202
	v_fmac_f32_e32 v63, v159, v203
	v_fmac_f32_e32 v60, v188, v204
	v_fmac_f32_e32 v61, v189, v205
	v_fmac_f32_e32 v62, v190, v206
	v_fmac_f32_e32 v63, v191, v207
	global_store_dwordx4 v193, v[60:63], s[18:19] offset:3072
	s_add_u32 s18, s18, 0x2000
	s_addc_u32 s19, s19, 0
	global_load_dwordx4 v[32:35], v192, s[14:15] offset:0 nt
	global_load_dwordx4 v[36:39], v192, s[14:15] offset:1024 nt
	global_load_dwordx4 v[40:43], v192, s[14:15] offset:2048 nt
	global_load_dwordx4 v[44:47], v192, s[14:15] offset:3072 nt
	global_load_dwordx4 v[48:51], v193, s[14:15] offset:0 nt
	global_load_dwordx4 v[52:55], v193, s[14:15] offset:1024 nt
	global_load_dwordx4 v[56:59], v193, s[14:15] offset:2048 nt
	global_load_dwordx4 v[60:63], v193, s[14:15] offset:3072 nt
	global_load_dwordx2 v[80:81], v194, s[16:17] offset:0 nt
	global_load_dwordx2 v[82:83], v194, s[16:17] offset:512 nt
	global_load_dwordx2 v[84:85], v194, s[16:17] offset:1024 nt
	global_load_dwordx2 v[86:87], v194, s[16:17] offset:1536 nt
	global_load_dwordx2 v[88:89], v194, s[16:17] offset:2048 nt
	global_load_dwordx2 v[90:91], v194, s[16:17] offset:2560 nt
	global_load_dwordx2 v[92:93], v194, s[16:17] offset:3072 nt
	global_load_dwordx2 v[94:95], v194, s[16:17] offset:3584 nt
	global_load_dwordx2 v[112:113], v194, s[22:23] offset:0 nt
	global_load_dwordx2 v[114:115], v194, s[22:23] offset:512 nt
	global_load_dwordx2 v[116:117], v194, s[22:23] offset:1024 nt
	global_load_dwordx2 v[118:119], v194, s[22:23] offset:1536 nt
	global_load_dwordx2 v[120:121], v194, s[22:23] offset:2048 nt
	global_load_dwordx2 v[122:123], v194, s[22:23] offset:2560 nt
	global_load_dwordx2 v[124:125], v194, s[22:23] offset:3072 nt
	global_load_dwordx2 v[126:127], v194, s[22:23] offset:3584 nt
	s_add_u32 s14, s14, 0x2000
	s_addc_u32 s15, s15, 0
	s_add_u32 s16, s16, 0x1000
	s_addc_u32 s17, s17, 0
	s_add_u32 s22, s22, 0x1000
	s_addc_u32 s23, s23, 0
	s_waitcnt vmcnt(32)
	v_lshlrev_b32_e32 v200, 16, v64
	v_and_b32_e32 v201, 0xffff0000, v64
	v_lshlrev_b32_e32 v202, 16, v65
	v_and_b32_e32 v203, 0xffff0000, v65
	v_mul_f32_e32 v208, v200, v200
	v_mul_f32_e32 v209, v201, v201
	v_fmac_f32_e32 v208, v202, v202
	v_fmac_f32_e32 v209, v203, v203
	v_lshlrev_b32_e32 v204, 16, v96
	v_and_b32_e32 v205, 0xffff0000, v96
	v_lshlrev_b32_e32 v206, 16, v97
	v_and_b32_e32 v207, 0xffff0000, v97
	v_mul_f32_e32 v210, v204, v204
	v_mul_f32_e32 v211, v205, v205
	v_fmac_f32_e32 v210, v206, v206
	v_fmac_f32_e32 v211, v207, v207
	v_lshlrev_b32_e32 v200, 16, v66
	v_and_b32_e32 v201, 0xffff0000, v66
	v_lshlrev_b32_e32 v202, 16, v67
	v_and_b32_e32 v203, 0xffff0000, v67
	v_fmac_f32_e32 v208, v200, v200
	v_fmac_f32_e32 v209, v201, v201
	v_fmac_f32_e32 v208, v202, v202
	v_fmac_f32_e32 v209, v203, v203
	v_lshlrev_b32_e32 v204, 16, v98
	v_and_b32_e32 v205, 0xffff0000, v98
	v_lshlrev_b32_e32 v206, 16, v99
	v_and_b32_e32 v207, 0xffff0000, v99
	v_fmac_f32_e32 v210, v204, v204
	v_fmac_f32_e32 v211, v205, v205
	v_fmac_f32_e32 v210, v206, v206
	v_fmac_f32_e32 v211, v207, v207
	v_lshlrev_b32_e32 v200, 16, v68
	v_and_b32_e32 v201, 0xffff0000, v68
	v_lshlrev_b32_e32 v202, 16, v69
	v_and_b32_e32 v203, 0xffff0000, v69
	v_fmac_f32_e32 v208, v200, v200
	v_fmac_f32_e32 v209, v201, v201
	v_fmac_f32_e32 v208, v202, v202
	v_fmac_f32_e32 v209, v203, v203
	v_lshlrev_b32_e32 v204, 16, v100
	v_and_b32_e32 v205, 0xffff0000, v100
	v_lshlrev_b32_e32 v206, 16, v101
	v_and_b32_e32 v207, 0xffff0000, v101
	v_fmac_f32_e32 v210, v204, v204
	v_fmac_f32_e32 v211, v205, v205
	v_fmac_f32_e32 v210, v206, v206
	v_fmac_f32_e32 v211, v207, v207
	v_lshlrev_b32_e32 v200, 16, v70
	v_and_b32_e32 v201, 0xffff0000, v70
	v_lshlrev_b32_e32 v202, 16, v71
	v_and_b32_e32 v203, 0xffff0000, v71
	v_fmac_f32_e32 v208, v200, v200
	v_fmac_f32_e32 v209, v201, v201
	v_fmac_f32_e32 v208, v202, v202
	v_fmac_f32_e32 v209, v203, v203
	v_lshlrev_b32_e32 v204, 16, v102
	v_and_b32_e32 v205, 0xffff0000, v102
	v_lshlrev_b32_e32 v206, 16, v103
	v_and_b32_e32 v207, 0xffff0000, v103
	v_fmac_f32_e32 v210, v204, v204
	v_fmac_f32_e32 v211, v205, v205
	v_fmac_f32_e32 v210, v206, v206
	v_fmac_f32_e32 v211, v207, v207
	v_lshlrev_b32_e32 v200, 16, v72
	v_and_b32_e32 v201, 0xffff0000, v72
	v_lshlrev_b32_e32 v202, 16, v73
	v_and_b32_e32 v203, 0xffff0000, v73
	v_fmac_f32_e32 v208, v200, v200
	v_fmac_f32_e32 v209, v201, v201
	v_fmac_f32_e32 v208, v202, v202
	v_fmac_f32_e32 v209, v203, v203
	v_lshlrev_b32_e32 v204, 16, v104
	v_and_b32_e32 v205, 0xffff0000, v104
	v_lshlrev_b32_e32 v206, 16, v105
	v_and_b32_e32 v207, 0xffff0000, v105
	v_fmac_f32_e32 v210, v204, v204
	v_fmac_f32_e32 v211, v205, v205
	v_fmac_f32_e32 v210, v206, v206
; __device__ __forceinline__ float bf_lo(unsigned w) { return __uint_as_float(w << 16); }
; __device__ __forceinline__ float bf_hi(unsigned w) { return __uint_as_float(w & 0xffff0000u); }
; __global__ void __launch_bounds__(NWAVES * 64, 2) mk_fwd(Args args) {
;     ...
;                 float sy = 0.f;
; #pragma unroll
;                 for (int j = 0; j < 8; ++j) { const float a = bf_lo(yw[q][j].x), b = bf_hi(yw[q][j].x), c2 = bf_lo(yw[q][j].y), d = bf_hi(yw[q][j].y); sy += (a * a + b * b) + (c2 * c2 + d * d); }
;                 const float rsy = __builtin_amdgcn_rsqf(wave_sum(sy) * (1.f / DM) + EPS);
; #pragma unroll
;                 for (int j = 0; j < 8; ++j) { const int col = 4 * F.lane + 256 * j;
;                     const f32x4 y4 = (f32x4){bf_lo(yw[q][j].x), bf_hi(yw[q][j].x), bf_lo(yw[q][j].y), bf_hi(yw[q][j].y)};
;                     *(f32x4*)(args.out + (size_t)row * DM + col) = v[q][j] + PA[j] * (y4 * rsy); }
	v_fmac_f32_e32 v211, v207, v207
	v_lshlrev_b32_e32 v200, 16, v74
	v_and_b32_e32 v201, 0xffff0000, v74
	v_lshlrev_b32_e32 v202, 16, v75
	v_and_b32_e32 v203, 0xffff0000, v75
	v_fmac_f32_e32 v208, v200, v200
	v_fmac_f32_e32 v209, v201, v201
	v_fmac_f32_e32 v208, v202, v202
	v_fmac_f32_e32 v209, v203, v203
	v_lshlrev_b32_e32 v204, 16, v106
	v_and_b32_e32 v205, 0xffff0000, v106
	v_lshlrev_b32_e32 v206, 16, v107
	v_and_b32_e32 v207, 0xffff0000, v107
	v_fmac_f32_e32 v210, v204, v204
	v_fmac_f32_e32 v211, v205, v205
	v_fmac_f32_e32 v210, v206, v206
	v_fmac_f32_e32 v211, v207, v207
	v_lshlrev_b32_e32 v200, 16, v76
	v_and_b32_e32 v201, 0xffff0000, v76
	v_lshlrev_b32_e32 v202, 16, v77
	v_and_b32_e32 v203, 0xffff0000, v77
	v_fmac_f32_e32 v208, v200, v200
	v_fmac_f32_e32 v209, v201, v201
	v_fmac_f32_e32 v208, v202, v202
	v_fmac_f32_e32 v209, v203, v203
	v_lshlrev_b32_e32 v204, 16, v108
	v_and_b32_e32 v205, 0xffff0000, v108
	v_lshlrev_b32_e32 v206, 16, v109
	v_and_b32_e32 v207, 0xffff0000, v109
	v_fmac_f32_e32 v210, v204, v204
	v_fmac_f32_e32 v211, v205, v205
	v_fmac_f32_e32 v210, v206, v206
	v_fmac_f32_e32 v211, v207, v207
	v_lshlrev_b32_e32 v200, 16, v78
	v_and_b32_e32 v201, 0xffff0000, v78
	v_lshlrev_b32_e32 v202, 16, v79
	v_and_b32_e32 v203, 0xffff0000, v79
	v_fmac_f32_e32 v208, v200, v200
	v_fmac_f32_e32 v209, v201, v201
	v_fmac_f32_e32 v208, v202, v202
	v_fmac_f32_e32 v209, v203, v203
	v_lshlrev_b32_e32 v204, 16, v110
	v_and_b32_e32 v205, 0xffff0000, v110
	v_lshlrev_b32_e32 v206, 16, v111
	v_and_b32_e32 v207, 0xffff0000, v111
	v_fmac_f32_e32 v210, v204, v204
	v_fmac_f32_e32 v211, v205, v205
	v_fmac_f32_e32 v210, v206, v206
	v_fmac_f32_e32 v211, v207, v207
	v_add_f32_e32 v208, v208, v209
	v_add_f32_e32 v210, v210, v211
	s_nop 0
	v_add_f32_dpp v212, v208, v208 quad_perm:[1,0,3,2] row_mask:0xf bank_mask:0xf
	v_add_f32_dpp v213, v210, v210 quad_perm:[1,0,3,2] row_mask:0xf bank_mask:0xf
	s_nop 0
	v_add_f32_dpp v212, v212, v212 quad_perm:[2,3,0,1] row_mask:0xf bank_mask:0xf
	v_add_f32_dpp v213, v213, v213 quad_perm:[2,3,0,1] row_mask:0xf bank_mask:0xf
	s_nop 0
	v_add_f32_dpp v212, v212, v212 row_half_mirror row_mask:0xf bank_mask:0xf
	v_add_f32_dpp v213, v213, v213 row_half_mirror row_mask:0xf bank_mask:0xf
	s_nop 0
	v_add_f32_dpp v212, v212, v212 row_mirror row_mask:0xf bank_mask:0xf
	v_add_f32_dpp v213, v213, v213 row_mirror row_mask:0xf bank_mask:0xf
	s_nop 0
	v_readlane_b32 s4, v212, 0
	v_readlane_b32 s5, v212, 16
	v_readlane_b32 s6, v212, 32
	v_readlane_b32 s7, v212, 48
	v_readlane_b32 s24, v213, 0
	v_readlane_b32 s25, v213, 16
	v_readlane_b32 s26, v213, 32
	v_readlane_b32 s27, v213, 48
	s_nop 1
	v_mov_b32_e32 v214, s4
	v_mov_b32_e32 v215, s24
	v_add_f32_e32 v214, s5, v214
	v_add_f32_e32 v215, s25, v215
	v_add_f32_e32 v214, s6, v214
	v_add_f32_e32 v215, s26, v215
	v_add_f32_e32 v214, s7, v214
	v_add_f32_e32 v215, s27, v215
	v_fmamk_f32 v214, v214, 0x3a000000, v195
	v_fmamk_f32 v215, v215, 0x3a000000, v195
	v_rsq_f32_e32 v214, v214
	v_rsq_f32_e32 v215, v215
	s_nop 0
	v_lshlrev_b32_e32 v200, 16, v64
	v_and_b32_e32 v201, 0xffff0000, v64
	v_lshlrev_b32_e32 v202, 16, v65
	v_and_b32_e32 v203, 0xffff0000, v65
	v_lshlrev_b32_e32 v204, 16, v96
	v_and_b32_e32 v205, 0xffff0000, v96
	v_lshlrev_b32_e32 v206, 16, v97
	v_and_b32_e32 v207, 0xffff0000, v97
	v_mul_f32_e32 v200, v214, v200
	v_mul_f32_e32 v201, v214, v201
	v_mul_f32_e32 v202, v214, v202
	v_mul_f32_e32 v203, v214, v203
	v_mul_f32_e32 v204, v215, v204
	v_mul_f32_e32 v205, v215, v205
	v_mul_f32_e32 v206, v215, v206
	v_mul_f32_e32 v207, v215, v207
	v_fmac_f32_e32 v0, v128, v200
	v_fmac_f32_e32 v1, v129, v201
	v_fmac_f32_e32 v2, v130, v202
	v_fmac_f32_e32 v3, v131, v203
	v_fmac_f32_e32 v0, v160, v204
	v_fmac_f32_e32 v1, v161, v205
	v_fmac_f32_e32 v2, v162, v206
	v_fmac_f32_e32 v3, v163, v207
	global_store_dwordx4 v192, v[0:3], s[18:19] offset:0
	v_lshlrev_b32_e32 v200, 16, v66
	v_and_b32_e32 v201, 0xffff0000, v66
	v_lshlrev_b32_e32 v202, 16, v67
	v_and_b32_e32 v203, 0xffff0000, v67
	v_lshlrev_b32_e32 v204, 16, v98
	v_and_b32_e32 v205, 0xffff0000, v98
	v_lshlrev_b32_e32 v206, 16, v99
	v_and_b32_e32 v207, 0xffff0000, v99
	v_mul_f32_e32 v200, v214, v200
	v_mul_f32_e32 v201, v214, v201
	v_mul_f32_e32 v202, v214, v202
	v_mul_f32_e32 v203, v214, v203
	v_mul_f32_e32 v204, v215, v204
	v_mul_f32_e32 v205, v215, v205
	v_mul_f32_e32 v206, v215, v206
	v_mul_f32_e32 v207, v215, v207
	v_fmac_f32_e32 v4, v132, v200
	v_fmac_f32_e32 v5, v133, v201
	v_fmac_f32_e32 v6, v134, v202
	v_fmac_f32_e32 v7, v135, v203
	v_fmac_f32_e32 v4, v164, v204
	v_fmac_f32_e32 v5, v165, v205
	v_fmac_f32_e32 v6, v166, v206
	v_fmac_f32_e32 v7, v167, v207
	global_store_dwordx4 v192, v[4:7], s[18:19] offset:1024
	v_lshlrev_b32_e32 v200, 16, v68
	v_and_b32_e32 v201, 0xffff0000, v68
	v_lshlrev_b32_e32 v202, 16, v69
	v_and_b32_e32 v203, 0xffff0000, v69
	v_lshlrev_b32_e32 v204, 16, v100
	v_and_b32_e32 v205, 0xffff0000, v100
	v_lshlrev_b32_e32 v206, 16, v101
	v_and_b32_e32 v207, 0xffff0000, v101
	v_mul_f32_e32 v200, v214, v200
	v_mul_f32_e32 v201, v214, v201
	v_mul_f32_e32 v202, v214, v202
	v_mul_f32_e32 v203, v214, v203
	v_mul_f32_e32 v204, v215, v204
	v_mul_f32_e32 v205, v215, v205
	v_mul_f32_e32 v206, v215, v206
	v_mul_f32_e32 v207, v215, v207
	v_fmac_f32_e32 v8, v136, v200
	v_fmac_f32_e32 v9, v137, v201
	v_fmac_f32_e32 v10, v138, v202
	v_fmac_f32_e32 v11, v139, v203
	v_fmac_f32_e32 v8, v168, v204
	v_fmac_f32_e32 v9, v169, v205
	v_fmac_f32_e32 v10, v170, v206
	v_fmac_f32_e32 v11, v171, v207
	global_store_dwordx4 v192, v[8:11], s[18:19] offset:2048
	v_lshlrev_b32_e32 v200, 16, v70
	v_and_b32_e32 v201, 0xffff0000, v70
	v_lshlrev_b32_e32 v202, 16, v71
; __device__ __forceinline__ float bf_lo(unsigned w) { return __uint_as_float(w << 16); }
; __device__ __forceinline__ float bf_hi(unsigned w) { return __uint_as_float(w & 0xffff0000u); }
; __global__ void __launch_bounds__(NWAVES * 64, 2) mk_fwd(Args args) {
;     ...
;         for (int row0 = rbeg; row0 < rbeg + per2 && row0 < ML; row0 += 2) {
;             f32x4 v[2][8]; u32x2 yw[2][8];
; #pragma unroll
;             for (int q = 0; q < 2; ++q) { const int row = row0 + q; load_row_f32(args.out + (size_t)row * DM, F.lane, v[q]);
;                 const bf16_t* yr = Y + (size_t)row * DM;
; #pragma unroll
;                 for (int j = 0; j < 8; ++j) yw[q][j] = *(const u32x2*)(yr + 4 * F.lane + 256 * j); }
;     ...
; #pragma unroll
;                 for (int j = 0; j < 8; ++j) { const int col = 4 * F.lane + 256 * j;
;                     const f32x4 y4 = (f32x4){bf_lo(yw[q][j].x), bf_hi(yw[q][j].x), bf_lo(yw[q][j].y), bf_hi(yw[q][j].y)};
;                     *(f32x4*)(args.out + (size_t)row * DM + col) = v[q][j] + PA[j] * (y4 * rsy); }
	v_and_b32_e32 v203, 0xffff0000, v71
	v_lshlrev_b32_e32 v204, 16, v102
	v_and_b32_e32 v205, 0xffff0000, v102
	v_lshlrev_b32_e32 v206, 16, v103
	v_and_b32_e32 v207, 0xffff0000, v103
	v_mul_f32_e32 v200, v214, v200
	v_mul_f32_e32 v201, v214, v201
	v_mul_f32_e32 v202, v214, v202
	v_mul_f32_e32 v203, v214, v203
	v_mul_f32_e32 v204, v215, v204
	v_mul_f32_e32 v205, v215, v205
	v_mul_f32_e32 v206, v215, v206
	v_mul_f32_e32 v207, v215, v207
	v_fmac_f32_e32 v12, v140, v200
	v_fmac_f32_e32 v13, v141, v201
	v_fmac_f32_e32 v14, v142, v202
	v_fmac_f32_e32 v15, v143, v203
	v_fmac_f32_e32 v12, v172, v204
	v_fmac_f32_e32 v13, v173, v205
	v_fmac_f32_e32 v14, v174, v206
	v_fmac_f32_e32 v15, v175, v207
	global_store_dwordx4 v192, v[12:15], s[18:19] offset:3072
	v_lshlrev_b32_e32 v200, 16, v72
	v_and_b32_e32 v201, 0xffff0000, v72
	v_lshlrev_b32_e32 v202, 16, v73
	v_and_b32_e32 v203, 0xffff0000, v73
	v_lshlrev_b32_e32 v204, 16, v104
	v_and_b32_e32 v205, 0xffff0000, v104
	v_lshlrev_b32_e32 v206, 16, v105
	v_and_b32_e32 v207, 0xffff0000, v105
	v_mul_f32_e32 v200, v214, v200
	v_mul_f32_e32 v201, v214, v201
	v_mul_f32_e32 v202, v214, v202
	v_mul_f32_e32 v203, v214, v203
	v_mul_f32_e32 v204, v215, v204
	v_mul_f32_e32 v205, v215, v205
	v_mul_f32_e32 v206, v215, v206
	v_mul_f32_e32 v207, v215, v207
	v_fmac_f32_e32 v16, v144, v200
	v_fmac_f32_e32 v17, v145, v201
	v_fmac_f32_e32 v18, v146, v202
	v_fmac_f32_e32 v19, v147, v203
	v_fmac_f32_e32 v16, v176, v204
	v_fmac_f32_e32 v17, v177, v205
	v_fmac_f32_e32 v18, v178, v206
	v_fmac_f32_e32 v19, v179, v207
	global_store_dwordx4 v193, v[16:19], s[18:19] offset:0
	v_lshlrev_b32_e32 v200, 16, v74
	v_and_b32_e32 v201, 0xffff0000, v74
	v_lshlrev_b32_e32 v202, 16, v75
	v_and_b32_e32 v203, 0xffff0000, v75
	v_lshlrev_b32_e32 v204, 16, v106
	v_and_b32_e32 v205, 0xffff0000, v106
	v_lshlrev_b32_e32 v206, 16, v107
	v_and_b32_e32 v207, 0xffff0000, v107
	v_mul_f32_e32 v200, v214, v200
	v_mul_f32_e32 v201, v214, v201
	v_mul_f32_e32 v202, v214, v202
	v_mul_f32_e32 v203, v214, v203
	v_mul_f32_e32 v204, v215, v204
	v_mul_f32_e32 v205, v215, v205
	v_mul_f32_e32 v206, v215, v206
	v_mul_f32_e32 v207, v215, v207
	v_fmac_f32_e32 v20, v148, v200
	v_fmac_f32_e32 v21, v149, v201
	v_fmac_f32_e32 v22, v150, v202
	v_fmac_f32_e32 v23, v151, v203
	v_fmac_f32_e32 v20, v180, v204
	v_fmac_f32_e32 v21, v181, v205
	v_fmac_f32_e32 v22, v182, v206
	v_fmac_f32_e32 v23, v183, v207
	global_store_dwordx4 v193, v[20:23], s[18:19] offset:1024
	v_lshlrev_b32_e32 v200, 16, v76
	v_and_b32_e32 v201, 0xffff0000, v76
	v_lshlrev_b32_e32 v202, 16, v77
	v_and_b32_e32 v203, 0xffff0000, v77
	v_lshlrev_b32_e32 v204, 16, v108
	v_and_b32_e32 v205, 0xffff0000, v108
	v_lshlrev_b32_e32 v206, 16, v109
	v_and_b32_e32 v207, 0xffff0000, v109
	v_mul_f32_e32 v200, v214, v200
	v_mul_f32_e32 v201, v214, v201
	v_mul_f32_e32 v202, v214, v202
	v_mul_f32_e32 v203, v214, v203
	v_mul_f32_e32 v204, v215, v204
	v_mul_f32_e32 v205, v215, v205
	v_mul_f32_e32 v206, v215, v206
	v_mul_f32_e32 v207, v215, v207
	v_fmac_f32_e32 v24, v152, v200
	v_fmac_f32_e32 v25, v153, v201
	v_fmac_f32_e32 v26, v154, v202
	v_fmac_f32_e32 v27, v155, v203
	v_fmac_f32_e32 v24, v184, v204
	v_fmac_f32_e32 v25, v185, v205
	v_fmac_f32_e32 v26, v186, v206
	v_fmac_f32_e32 v27, v187, v207
	global_store_dwordx4 v193, v[24:27], s[18:19] offset:2048
	v_lshlrev_b32_e32 v200, 16, v78
	v_and_b32_e32 v201, 0xffff0000, v78
	v_lshlrev_b32_e32 v202, 16, v79
	v_and_b32_e32 v203, 0xffff0000, v79
	v_lshlrev_b32_e32 v204, 16, v110
	v_and_b32_e32 v205, 0xffff0000, v110
	v_lshlrev_b32_e32 v206, 16, v111
	v_and_b32_e32 v207, 0xffff0000, v111
	v_mul_f32_e32 v200, v214, v200
	v_mul_f32_e32 v201, v214, v201
	v_mul_f32_e32 v202, v214, v202
	v_mul_f32_e32 v203, v214, v203
	v_mul_f32_e32 v204, v215, v204
	v_mul_f32_e32 v205, v215, v205
	v_mul_f32_e32 v206, v215, v206
	v_mul_f32_e32 v207, v215, v207
	v_fmac_f32_e32 v28, v156, v200
	v_fmac_f32_e32 v29, v157, v201
	v_fmac_f32_e32 v30, v158, v202
	v_fmac_f32_e32 v31, v159, v203
	v_fmac_f32_e32 v28, v188, v204
	v_fmac_f32_e32 v29, v189, v205
	v_fmac_f32_e32 v30, v190, v206
	v_fmac_f32_e32 v31, v191, v207
	global_store_dwordx4 v193, v[28:31], s[18:19] offset:3072
	s_add_u32 s18, s18, 0x2000
	s_addc_u32 s19, s19, 0
	global_load_dwordx4 v[0:3], v192, s[14:15] offset:0 nt
	global_load_dwordx4 v[4:7], v192, s[14:15] offset:1024 nt
	global_load_dwordx4 v[8:11], v192, s[14:15] offset:2048 nt
	global_load_dwordx4 v[12:15], v192, s[14:15] offset:3072 nt
	global_load_dwordx4 v[16:19], v193, s[14:15] offset:0 nt
	global_load_dwordx4 v[20:23], v193, s[14:15] offset:1024 nt
	global_load_dwordx4 v[24:27], v193, s[14:15] offset:2048 nt
	global_load_dwordx4 v[28:31], v193, s[14:15] offset:3072 nt
	global_load_dwordx2 v[64:65], v194, s[16:17] offset:0 nt
	global_load_dwordx2 v[66:67], v194, s[16:17] offset:512 nt
	global_load_dwordx2 v[68:69], v194, s[16:17] offset:1024 nt
	global_load_dwordx2 v[70:71], v194, s[16:17] offset:1536 nt
	global_load_dwordx2 v[72:73], v194, s[16:17] offset:2048 nt
	global_load_dwordx2 v[74:75], v194, s[16:17] offset:2560 nt
	global_load_dwordx2 v[76:77], v194, s[16:17] offset:3072 nt
	global_load_dwordx2 v[78:79], v194, s[16:17] offset:3584 nt
	global_load_dwordx2 v[96:97], v194, s[22:23] offset:0 nt
	global_load_dwordx2 v[98:99], v194, s[22:23] offset:512 nt
	global_load_dwordx2 v[100:101], v194, s[22:23] offset:1024 nt
	global_load_dwordx2 v[102:103], v194, s[22:23] offset:1536 nt
	global_load_dwordx2 v[104:105], v194, s[22:23] offset:2048 nt
	global_load_dwordx2 v[106:107], v194, s[22:23] offset:2560 nt
	global_load_dwordx2 v[108:109], v194, s[22:23] offset:3072 nt
	global_load_dwordx2 v[110:111], v194, s[22:23] offset:3584 nt
	s_add_u32 s14, s14, 0x2000
	s_addc_u32 s15, s15, 0
	s_add_u32 s16, s16, 0x1000
	s_addc_u32 s17, s17, 0
	s_add_u32 s22, s22, 0x1000
	s_addc_u32 s23, s23, 0
	s_waitcnt vmcnt(32)
; __device__ __forceinline__ float bf_lo(unsigned w) { return __uint_as_float(w << 16); }
; __device__ __forceinline__ float bf_hi(unsigned w) { return __uint_as_float(w & 0xffff0000u); }
; __global__ void __launch_bounds__(NWAVES * 64, 2) mk_fwd(Args args) {
;     ...
;                 float sy = 0.f;
; #pragma unroll
;                 for (int j = 0; j < 8; ++j) { const float a = bf_lo(yw[q][j].x), b = bf_hi(yw[q][j].x), c2 = bf_lo(yw[q][j].y), d = bf_hi(yw[q][j].y); sy += (a * a + b * b) + (c2 * c2 + d * d); }
;                 const float rsy = __builtin_amdgcn_rsqf(wave_sum(sy) * (1.f / DM) + EPS);
	v_lshlrev_b32_e32 v200, 16, v80
	v_and_b32_e32 v201, 0xffff0000, v80
	v_lshlrev_b32_e32 v202, 16, v81
	v_and_b32_e32 v203, 0xffff0000, v81
	v_mul_f32_e32 v208, v200, v200
	v_mul_f32_e32 v209, v201, v201
	v_fmac_f32_e32 v208, v202, v202
	v_fmac_f32_e32 v209, v203, v203
	v_lshlrev_b32_e32 v204, 16, v112
	v_and_b32_e32 v205, 0xffff0000, v112
	v_lshlrev_b32_e32 v206, 16, v113
	v_and_b32_e32 v207, 0xffff0000, v113
	v_mul_f32_e32 v210, v204, v204
	v_mul_f32_e32 v211, v205, v205
	v_fmac_f32_e32 v210, v206, v206
	v_fmac_f32_e32 v211, v207, v207
	v_lshlrev_b32_e32 v200, 16, v82
	v_and_b32_e32 v201, 0xffff0000, v82
	v_lshlrev_b32_e32 v202, 16, v83
	v_and_b32_e32 v203, 0xffff0000, v83
	v_fmac_f32_e32 v208, v200, v200
	v_fmac_f32_e32 v209, v201, v201
	v_fmac_f32_e32 v208, v202, v202
	v_fmac_f32_e32 v209, v203, v203
	v_lshlrev_b32_e32 v204, 16, v114
	v_and_b32_e32 v205, 0xffff0000, v114
	v_lshlrev_b32_e32 v206, 16, v115
	v_and_b32_e32 v207, 0xffff0000, v115
	v_fmac_f32_e32 v210, v204, v204
	v_fmac_f32_e32 v211, v205, v205
	v_fmac_f32_e32 v210, v206, v206
	v_fmac_f32_e32 v211, v207, v207
	v_lshlrev_b32_e32 v200, 16, v84
	v_and_b32_e32 v201, 0xffff0000, v84
	v_lshlrev_b32_e32 v202, 16, v85
	v_and_b32_e32 v203, 0xffff0000, v85
	v_fmac_f32_e32 v208, v200, v200
	v_fmac_f32_e32 v209, v201, v201
	v_fmac_f32_e32 v208, v202, v202
	v_fmac_f32_e32 v209, v203, v203
	v_lshlrev_b32_e32 v204, 16, v116
	v_and_b32_e32 v205, 0xffff0000, v116
	v_lshlrev_b32_e32 v206, 16, v117
	v_and_b32_e32 v207, 0xffff0000, v117
	v_fmac_f32_e32 v210, v204, v204
	v_fmac_f32_e32 v211, v205, v205
	v_fmac_f32_e32 v210, v206, v206
	v_fmac_f32_e32 v211, v207, v207
	v_lshlrev_b32_e32 v200, 16, v86
	v_and_b32_e32 v201, 0xffff0000, v86
	v_lshlrev_b32_e32 v202, 16, v87
	v_and_b32_e32 v203, 0xffff0000, v87
	v_fmac_f32_e32 v208, v200, v200
	v_fmac_f32_e32 v209, v201, v201
	v_fmac_f32_e32 v208, v202, v202
	v_fmac_f32_e32 v209, v203, v203
	v_lshlrev_b32_e32 v204, 16, v118
	v_and_b32_e32 v205, 0xffff0000, v118
	v_lshlrev_b32_e32 v206, 16, v119
	v_and_b32_e32 v207, 0xffff0000, v119
	v_fmac_f32_e32 v210, v204, v204
	v_fmac_f32_e32 v211, v205, v205
	v_fmac_f32_e32 v210, v206, v206
	v_fmac_f32_e32 v211, v207, v207
	v_lshlrev_b32_e32 v200, 16, v88
	v_and_b32_e32 v201, 0xffff0000, v88
	v_lshlrev_b32_e32 v202, 16, v89
	v_and_b32_e32 v203, 0xffff0000, v89
	v_fmac_f32_e32 v208, v200, v200
	v_fmac_f32_e32 v209, v201, v201
	v_fmac_f32_e32 v208, v202, v202
	v_fmac_f32_e32 v209, v203, v203
	v_lshlrev_b32_e32 v204, 16, v120
	v_and_b32_e32 v205, 0xffff0000, v120
	v_lshlrev_b32_e32 v206, 16, v121
	v_and_b32_e32 v207, 0xffff0000, v121
	v_fmac_f32_e32 v210, v204, v204
	v_fmac_f32_e32 v211, v205, v205
	v_fmac_f32_e32 v210, v206, v206
	v_fmac_f32_e32 v211, v207, v207
	v_lshlrev_b32_e32 v200, 16, v90
	v_and_b32_e32 v201, 0xffff0000, v90
	v_lshlrev_b32_e32 v202, 16, v91
	v_and_b32_e32 v203, 0xffff0000, v91
	v_fmac_f32_e32 v208, v200, v200
	v_fmac_f32_e32 v209, v201, v201
	v_fmac_f32_e32 v208, v202, v202
	v_fmac_f32_e32 v209, v203, v203
	v_lshlrev_b32_e32 v204, 16, v122
	v_and_b32_e32 v205, 0xffff0000, v122
	v_lshlrev_b32_e32 v206, 16, v123
	v_and_b32_e32 v207, 0xffff0000, v123
	v_fmac_f32_e32 v210, v204, v204
	v_fmac_f32_e32 v211, v205, v205
	v_fmac_f32_e32 v210, v206, v206
	v_fmac_f32_e32 v211, v207, v207
	v_lshlrev_b32_e32 v200, 16, v92
	v_and_b32_e32 v201, 0xffff0000, v92
	v_lshlrev_b32_e32 v202, 16, v93
	v_and_b32_e32 v203, 0xffff0000, v93
	v_fmac_f32_e32 v208, v200, v200
	v_fmac_f32_e32 v209, v201, v201
	v_fmac_f32_e32 v208, v202, v202
	v_fmac_f32_e32 v209, v203, v203
	v_lshlrev_b32_e32 v204, 16, v124
	v_and_b32_e32 v205, 0xffff0000, v124
	v_lshlrev_b32_e32 v206, 16, v125
	v_and_b32_e32 v207, 0xffff0000, v125
	v_fmac_f32_e32 v210, v204, v204
	v_fmac_f32_e32 v211, v205, v205
	v_fmac_f32_e32 v210, v206, v206
	v_fmac_f32_e32 v211, v207, v207
	v_lshlrev_b32_e32 v200, 16, v94
	v_and_b32_e32 v201, 0xffff0000, v94
	v_lshlrev_b32_e32 v202, 16, v95
	v_and_b32_e32 v203, 0xffff0000, v95
	v_fmac_f32_e32 v208, v200, v200
	v_fmac_f32_e32 v209, v201, v201
	v_fmac_f32_e32 v208, v202, v202
	v_fmac_f32_e32 v209, v203, v203
	v_lshlrev_b32_e32 v204, 16, v126
	v_and_b32_e32 v205, 0xffff0000, v126
	v_lshlrev_b32_e32 v206, 16, v127
	v_and_b32_e32 v207, 0xffff0000, v127
	v_fmac_f32_e32 v210, v204, v204
	v_fmac_f32_e32 v211, v205, v205
	v_fmac_f32_e32 v210, v206, v206
	v_fmac_f32_e32 v211, v207, v207
	v_add_f32_e32 v208, v208, v209
	v_add_f32_e32 v210, v210, v211
	s_nop 0
	v_add_f32_dpp v212, v208, v208 quad_perm:[1,0,3,2] row_mask:0xf bank_mask:0xf
	v_add_f32_dpp v213, v210, v210 quad_perm:[1,0,3,2] row_mask:0xf bank_mask:0xf
	s_nop 0
	v_add_f32_dpp v212, v212, v212 quad_perm:[2,3,0,1] row_mask:0xf bank_mask:0xf
	v_add_f32_dpp v213, v213, v213 quad_perm:[2,3,0,1] row_mask:0xf bank_mask:0xf
	s_nop 0
	v_add_f32_dpp v212, v212, v212 row_half_mirror row_mask:0xf bank_mask:0xf
	v_add_f32_dpp v213, v213, v213 row_half_mirror row_mask:0xf bank_mask:0xf
	s_nop 0
	v_add_f32_dpp v212, v212, v212 row_mirror row_mask:0xf bank_mask:0xf
	v_add_f32_dpp v213, v213, v213 row_mirror row_mask:0xf bank_mask:0xf
	s_nop 0
	v_readlane_b32 s4, v212, 0
	v_readlane_b32 s5, v212, 16
	v_readlane_b32 s6, v212, 32
	v_readlane_b32 s7, v212, 48
	v_readlane_b32 s24, v213, 0
	v_readlane_b32 s25, v213, 16
	v_readlane_b32 s26, v213, 32
	v_readlane_b32 s27, v213, 48
	s_nop 1
	v_mov_b32_e32 v214, s4
	v_mov_b32_e32 v215, s24
	v_add_f32_e32 v214, s5, v214
	v_add_f32_e32 v215, s25, v215
	v_add_f32_e32 v214, s6, v214
	v_add_f32_e32 v215, s26, v215
	v_add_f32_e32 v214, s7, v214
	v_add_f32_e32 v215, s27, v215
	v_fmamk_f32 v214, v214, 0x3a000000, v195
	v_fmamk_f32 v215, v215, 0x3a000000, v195
; __device__ __forceinline__ float bf_lo(unsigned w) { return __uint_as_float(w << 16); }
; __device__ __forceinline__ float bf_hi(unsigned w) { return __uint_as_float(w & 0xffff0000u); }
; __global__ void __launch_bounds__(NWAVES * 64, 2) mk_fwd(Args args) {
;     ...
;                 const float rsy = __builtin_amdgcn_rsqf(wave_sum(sy) * (1.f / DM) + EPS);
; #pragma unroll
;                 for (int j = 0; j < 8; ++j) { const int col = 4 * F.lane + 256 * j;
;                     const f32x4 y4 = (f32x4){bf_lo(yw[q][j].x), bf_hi(yw[q][j].x), bf_lo(yw[q][j].y), bf_hi(yw[q][j].y)};
;                     *(f32x4*)(args.out + (size_t)row * DM + col) = v[q][j] + PA[j] * (y4 * rsy); }
	v_rsq_f32_e32 v214, v214
	v_rsq_f32_e32 v215, v215
	s_nop 0
	v_lshlrev_b32_e32 v200, 16, v80
	v_and_b32_e32 v201, 0xffff0000, v80
	v_lshlrev_b32_e32 v202, 16, v81
	v_and_b32_e32 v203, 0xffff0000, v81
	v_lshlrev_b32_e32 v204, 16, v112
	v_and_b32_e32 v205, 0xffff0000, v112
	v_lshlrev_b32_e32 v206, 16, v113
	v_and_b32_e32 v207, 0xffff0000, v113
	v_mul_f32_e32 v200, v214, v200
	v_mul_f32_e32 v201, v214, v201
	v_mul_f32_e32 v202, v214, v202
	v_mul_f32_e32 v203, v214, v203
	v_mul_f32_e32 v204, v215, v204
	v_mul_f32_e32 v205, v215, v205
	v_mul_f32_e32 v206, v215, v206
	v_mul_f32_e32 v207, v215, v207
	v_fmac_f32_e32 v32, v128, v200
	v_fmac_f32_e32 v33, v129, v201
	v_fmac_f32_e32 v34, v130, v202
	v_fmac_f32_e32 v35, v131, v203
	v_fmac_f32_e32 v32, v160, v204
	v_fmac_f32_e32 v33, v161, v205
	v_fmac_f32_e32 v34, v162, v206
	v_fmac_f32_e32 v35, v163, v207
	global_store_dwordx4 v192, v[32:35], s[18:19] offset:0
	v_lshlrev_b32_e32 v200, 16, v82
	v_and_b32_e32 v201, 0xffff0000, v82
	v_lshlrev_b32_e32 v202, 16, v83
	v_and_b32_e32 v203, 0xffff0000, v83
	v_lshlrev_b32_e32 v204, 16, v114
	v_and_b32_e32 v205, 0xffff0000, v114
	v_lshlrev_b32_e32 v206, 16, v115
	v_and_b32_e32 v207, 0xffff0000, v115
	v_mul_f32_e32 v200, v214, v200
	v_mul_f32_e32 v201, v214, v201
	v_mul_f32_e32 v202, v214, v202
	v_mul_f32_e32 v203, v214, v203
	v_mul_f32_e32 v204, v215, v204
	v_mul_f32_e32 v205, v215, v205
	v_mul_f32_e32 v206, v215, v206
	v_mul_f32_e32 v207, v215, v207
	v_fmac_f32_e32 v36, v132, v200
	v_fmac_f32_e32 v37, v133, v201
	v_fmac_f32_e32 v38, v134, v202
	v_fmac_f32_e32 v39, v135, v203
	v_fmac_f32_e32 v36, v164, v204
	v_fmac_f32_e32 v37, v165, v205
	v_fmac_f32_e32 v38, v166, v206
	v_fmac_f32_e32 v39, v167, v207
	global_store_dwordx4 v192, v[36:39], s[18:19] offset:1024
	v_lshlrev_b32_e32 v200, 16, v84
	v_and_b32_e32 v201, 0xffff0000, v84
	v_lshlrev_b32_e32 v202, 16, v85
	v_and_b32_e32 v203, 0xffff0000, v85
	v_lshlrev_b32_e32 v204, 16, v116
	v_and_b32_e32 v205, 0xffff0000, v116
	v_lshlrev_b32_e32 v206, 16, v117
	v_and_b32_e32 v207, 0xffff0000, v117
	v_mul_f32_e32 v200, v214, v200
	v_mul_f32_e32 v201, v214, v201
	v_mul_f32_e32 v202, v214, v202
	v_mul_f32_e32 v203, v214, v203
	v_mul_f32_e32 v204, v215, v204
	v_mul_f32_e32 v205, v215, v205
	v_mul_f32_e32 v206, v215, v206
	v_mul_f32_e32 v207, v215, v207
	v_fmac_f32_e32 v40, v136, v200
	v_fmac_f32_e32 v41, v137, v201
	v_fmac_f32_e32 v42, v138, v202
	v_fmac_f32_e32 v43, v139, v203
	v_fmac_f32_e32 v40, v168, v204
	v_fmac_f32_e32 v41, v169, v205
	v_fmac_f32_e32 v42, v170, v206
	v_fmac_f32_e32 v43, v171, v207
	global_store_dwordx4 v192, v[40:43], s[18:19] offset:2048
	v_lshlrev_b32_e32 v200, 16, v86
	v_and_b32_e32 v201, 0xffff0000, v86
	v_lshlrev_b32_e32 v202, 16, v87
	v_and_b32_e32 v203, 0xffff0000, v87
	v_lshlrev_b32_e32 v204, 16, v118
	v_and_b32_e32 v205, 0xffff0000, v118
	v_lshlrev_b32_e32 v206, 16, v119
	v_and_b32_e32 v207, 0xffff0000, v119
	v_mul_f32_e32 v200, v214, v200
	v_mul_f32_e32 v201, v214, v201
	v_mul_f32_e32 v202, v214, v202
	v_mul_f32_e32 v203, v214, v203
	v_mul_f32_e32 v204, v215, v204
	v_mul_f32_e32 v205, v215, v205
	v_mul_f32_e32 v206, v215, v206
	v_mul_f32_e32 v207, v215, v207
	v_fmac_f32_e32 v44, v140, v200
	v_fmac_f32_e32 v45, v141, v201
	v_fmac_f32_e32 v46, v142, v202
	v_fmac_f32_e32 v47, v143, v203
	v_fmac_f32_e32 v44, v172, v204
	v_fmac_f32_e32 v45, v173, v205
	v_fmac_f32_e32 v46, v174, v206
	v_fmac_f32_e32 v47, v175, v207
	global_store_dwordx4 v192, v[44:47], s[18:19] offset:3072
	v_lshlrev_b32_e32 v200, 16, v88
	v_and_b32_e32 v201, 0xffff0000, v88
	v_lshlrev_b32_e32 v202, 16, v89
	v_and_b32_e32 v203, 0xffff0000, v89
	v_lshlrev_b32_e32 v204, 16, v120
	v_and_b32_e32 v205, 0xffff0000, v120
	v_lshlrev_b32_e32 v206, 16, v121
	v_and_b32_e32 v207, 0xffff0000, v121
	v_mul_f32_e32 v200, v214, v200
	v_mul_f32_e32 v201, v214, v201
	v_mul_f32_e32 v202, v214, v202
	v_mul_f32_e32 v203, v214, v203
	v_mul_f32_e32 v204, v215, v204
	v_mul_f32_e32 v205, v215, v205
	v_mul_f32_e32 v206, v215, v206
	v_mul_f32_e32 v207, v215, v207
	v_fmac_f32_e32 v48, v144, v200
	v_fmac_f32_e32 v49, v145, v201
	v_fmac_f32_e32 v50, v146, v202
	v_fmac_f32_e32 v51, v147, v203
	v_fmac_f32_e32 v48, v176, v204
	v_fmac_f32_e32 v49, v177, v205
	v_fmac_f32_e32 v50, v178, v206
	v_fmac_f32_e32 v51, v179, v207
	global_store_dwordx4 v193, v[48:51], s[18:19] offset:0
	v_lshlrev_b32_e32 v200, 16, v90
	v_and_b32_e32 v201, 0xffff0000, v90
	v_lshlrev_b32_e32 v202, 16, v91
	v_and_b32_e32 v203, 0xffff0000, v91
	v_lshlrev_b32_e32 v204, 16, v122
	v_and_b32_e32 v205, 0xffff0000, v122
	v_lshlrev_b32_e32 v206, 16, v123
	v_and_b32_e32 v207, 0xffff0000, v123
	v_mul_f32_e32 v200, v214, v200
	v_mul_f32_e32 v201, v214, v201
	v_mul_f32_e32 v202, v214, v202
	v_mul_f32_e32 v203, v214, v203
	v_mul_f32_e32 v204, v215, v204
	v_mul_f32_e32 v205, v215, v205
	v_mul_f32_e32 v206, v215, v206
	v_mul_f32_e32 v207, v215, v207
	v_fmac_f32_e32 v52, v148, v200
	v_fmac_f32_e32 v53, v149, v201
	v_fmac_f32_e32 v54, v150, v202
	v_fmac_f32_e32 v55, v151, v203
	v_fmac_f32_e32 v52, v180, v204
	v_fmac_f32_e32 v53, v181, v205
	v_fmac_f32_e32 v54, v182, v206
	v_fmac_f32_e32 v55, v183, v207
	global_store_dwordx4 v193, v[52:55], s[18:19] offset:1024
	v_lshlrev_b32_e32 v200, 16, v92
	v_and_b32_e32 v201, 0xffff0000, v92
	v_lshlrev_b32_e32 v202, 16, v93
	v_and_b32_e32 v203, 0xffff0000, v93
	v_lshlrev_b32_e32 v204, 16, v124
	v_and_b32_e32 v205, 0xffff0000, v124
	v_lshlrev_b32_e32 v206, 16, v125
	v_and_b32_e32 v207, 0xffff0000, v125
	v_mul_f32_e32 v200, v214, v200
	v_mul_f32_e32 v201, v214, v201
	v_mul_f32_e32 v202, v214, v202
	v_mul_f32_e32 v203, v214, v203
	v_mul_f32_e32 v204, v215, v204
; __device__ __forceinline__ float bf_lo(unsigned w) { return __uint_as_float(w << 16); }
; __device__ __forceinline__ float bf_hi(unsigned w) { return __uint_as_float(w & 0xffff0000u); }
; __global__ void __launch_bounds__(NWAVES * 64, 2) mk_fwd(Args args) {
;     ...
;         for (int row0 = rbeg; row0 < rbeg + per2 && row0 < ML; row0 += 2) {
;             f32x4 v[2][8]; u32x2 yw[2][8];
; #pragma unroll
;             for (int q = 0; q < 2; ++q) { const int row = row0 + q; load_row_f32(args.out + (size_t)row * DM, F.lane, v[q]);
;                 const bf16_t* yr = Y + (size_t)row * DM;
; #pragma unroll
;                 for (int j = 0; j < 8; ++j) yw[q][j] = *(const u32x2*)(yr + 4 * F.lane + 256 * j); }
;     ...
;                 float sy = 0.f;
; #pragma unroll
;                 for (int j = 0; j < 8; ++j) { const float a = bf_lo(yw[q][j].x), b = bf_hi(yw[q][j].x), c2 = bf_lo(yw[q][j].y), d = bf_hi(yw[q][j].y); sy += (a * a + b * b) + (c2 * c2 + d * d); }
;     ...
; #pragma unroll
;                 for (int j = 0; j < 8; ++j) { const int col = 4 * F.lane + 256 * j;
;                     const f32x4 y4 = (f32x4){bf_lo(yw[q][j].x), bf_hi(yw[q][j].x), bf_lo(yw[q][j].y), bf_hi(yw[q][j].y)};
;                     *(f32x4*)(args.out + (size_t)row * DM + col) = v[q][j] + PA[j] * (y4 * rsy); }
	v_mul_f32_e32 v205, v215, v205
	v_mul_f32_e32 v206, v215, v206
	v_mul_f32_e32 v207, v215, v207
	v_fmac_f32_e32 v56, v152, v200
	v_fmac_f32_e32 v57, v153, v201
	v_fmac_f32_e32 v58, v154, v202
	v_fmac_f32_e32 v59, v155, v203
	v_fmac_f32_e32 v56, v184, v204
	v_fmac_f32_e32 v57, v185, v205
	v_fmac_f32_e32 v58, v186, v206
	v_fmac_f32_e32 v59, v187, v207
	global_store_dwordx4 v193, v[56:59], s[18:19] offset:2048
	v_lshlrev_b32_e32 v200, 16, v94
	v_and_b32_e32 v201, 0xffff0000, v94
	v_lshlrev_b32_e32 v202, 16, v95
	v_and_b32_e32 v203, 0xffff0000, v95
	v_lshlrev_b32_e32 v204, 16, v126
	v_and_b32_e32 v205, 0xffff0000, v126
	v_lshlrev_b32_e32 v206, 16, v127
	v_and_b32_e32 v207, 0xffff0000, v127
	v_mul_f32_e32 v200, v214, v200
	v_mul_f32_e32 v201, v214, v201
	v_mul_f32_e32 v202, v214, v202
	v_mul_f32_e32 v203, v214, v203
	v_mul_f32_e32 v204, v215, v204
	v_mul_f32_e32 v205, v215, v205
	v_mul_f32_e32 v206, v215, v206
	v_mul_f32_e32 v207, v215, v207
	v_fmac_f32_e32 v60, v156, v200
	v_fmac_f32_e32 v61, v157, v201
	v_fmac_f32_e32 v62, v158, v202
	v_fmac_f32_e32 v63, v159, v203
	v_fmac_f32_e32 v60, v188, v204
	v_fmac_f32_e32 v61, v189, v205
	v_fmac_f32_e32 v62, v190, v206
	v_fmac_f32_e32 v63, v191, v207
	global_store_dwordx4 v193, v[60:63], s[18:19] offset:3072
	s_add_u32 s18, s18, 0x2000
	s_addc_u32 s19, s19, 0
	global_load_dwordx4 v[32:35], v192, s[14:15] offset:0 nt
	global_load_dwordx4 v[36:39], v192, s[14:15] offset:1024 nt
	global_load_dwordx4 v[40:43], v192, s[14:15] offset:2048 nt
	global_load_dwordx4 v[44:47], v192, s[14:15] offset:3072 nt
	global_load_dwordx4 v[48:51], v193, s[14:15] offset:0 nt
	global_load_dwordx4 v[52:55], v193, s[14:15] offset:1024 nt
	global_load_dwordx4 v[56:59], v193, s[14:15] offset:2048 nt
	global_load_dwordx4 v[60:63], v193, s[14:15] offset:3072 nt
	global_load_dwordx2 v[80:81], v194, s[16:17] offset:0 nt
	global_load_dwordx2 v[82:83], v194, s[16:17] offset:512 nt
	global_load_dwordx2 v[84:85], v194, s[16:17] offset:1024 nt
	global_load_dwordx2 v[86:87], v194, s[16:17] offset:1536 nt
	global_load_dwordx2 v[88:89], v194, s[16:17] offset:2048 nt
	global_load_dwordx2 v[90:91], v194, s[16:17] offset:2560 nt
	global_load_dwordx2 v[92:93], v194, s[16:17] offset:3072 nt
	global_load_dwordx2 v[94:95], v194, s[16:17] offset:3584 nt
	global_load_dwordx2 v[112:113], v194, s[22:23] offset:0 nt
	global_load_dwordx2 v[114:115], v194, s[22:23] offset:512 nt
	global_load_dwordx2 v[116:117], v194, s[22:23] offset:1024 nt
	global_load_dwordx2 v[118:119], v194, s[22:23] offset:1536 nt
	global_load_dwordx2 v[120:121], v194, s[22:23] offset:2048 nt
	global_load_dwordx2 v[122:123], v194, s[22:23] offset:2560 nt
	global_load_dwordx2 v[124:125], v194, s[22:23] offset:3072 nt
	global_load_dwordx2 v[126:127], v194, s[22:23] offset:3584 nt
	s_add_u32 s14, s14, 0x2000
	s_addc_u32 s15, s15, 0
	s_add_u32 s16, s16, 0x1000
	s_addc_u32 s17, s17, 0
	s_add_u32 s22, s22, 0x1000
	s_addc_u32 s23, s23, 0
	s_waitcnt vmcnt(32)
	v_lshlrev_b32_e32 v200, 16, v64
	v_and_b32_e32 v201, 0xffff0000, v64
	v_lshlrev_b32_e32 v202, 16, v65
	v_and_b32_e32 v203, 0xffff0000, v65
	v_mul_f32_e32 v208, v200, v200
	v_mul_f32_e32 v209, v201, v201
	v_fmac_f32_e32 v208, v202, v202
	v_fmac_f32_e32 v209, v203, v203
	v_lshlrev_b32_e32 v204, 16, v96
	v_and_b32_e32 v205, 0xffff0000, v96
	v_lshlrev_b32_e32 v206, 16, v97
	v_and_b32_e32 v207, 0xffff0000, v97
	v_mul_f32_e32 v210, v204, v204
	v_mul_f32_e32 v211, v205, v205
	v_fmac_f32_e32 v210, v206, v206
	v_fmac_f32_e32 v211, v207, v207
	v_lshlrev_b32_e32 v200, 16, v66
	v_and_b32_e32 v201, 0xffff0000, v66
	v_lshlrev_b32_e32 v202, 16, v67
	v_and_b32_e32 v203, 0xffff0000, v67
	v_fmac_f32_e32 v208, v200, v200
	v_fmac_f32_e32 v209, v201, v201
	v_fmac_f32_e32 v208, v202, v202
	v_fmac_f32_e32 v209, v203, v203
	v_lshlrev_b32_e32 v204, 16, v98
	v_and_b32_e32 v205, 0xffff0000, v98
	v_lshlrev_b32_e32 v206, 16, v99
	v_and_b32_e32 v207, 0xffff0000, v99
	v_fmac_f32_e32 v210, v204, v204
	v_fmac_f32_e32 v211, v205, v205
	v_fmac_f32_e32 v210, v206, v206
	v_fmac_f32_e32 v211, v207, v207
	v_lshlrev_b32_e32 v200, 16, v68
	v_and_b32_e32 v201, 0xffff0000, v68
	v_lshlrev_b32_e32 v202, 16, v69
	v_and_b32_e32 v203, 0xffff0000, v69
	v_fmac_f32_e32 v208, v200, v200
	v_fmac_f32_e32 v209, v201, v201
	v_fmac_f32_e32 v208, v202, v202
	v_fmac_f32_e32 v209, v203, v203
	v_lshlrev_b32_e32 v204, 16, v100
	v_and_b32_e32 v205, 0xffff0000, v100
	v_lshlrev_b32_e32 v206, 16, v101
	v_and_b32_e32 v207, 0xffff0000, v101
	v_fmac_f32_e32 v210, v204, v204
	v_fmac_f32_e32 v211, v205, v205
	v_fmac_f32_e32 v210, v206, v206
	v_fmac_f32_e32 v211, v207, v207
	v_lshlrev_b32_e32 v200, 16, v70
	v_and_b32_e32 v201, 0xffff0000, v70
	v_lshlrev_b32_e32 v202, 16, v71
	v_and_b32_e32 v203, 0xffff0000, v71
	v_fmac_f32_e32 v208, v200, v200
	v_fmac_f32_e32 v209, v201, v201
	v_fmac_f32_e32 v208, v202, v202
	v_fmac_f32_e32 v209, v203, v203
	v_lshlrev_b32_e32 v204, 16, v102
	v_and_b32_e32 v205, 0xffff0000, v102
	v_lshlrev_b32_e32 v206, 16, v103
	v_and_b32_e32 v207, 0xffff0000, v103
	v_fmac_f32_e32 v210, v204, v204
	v_fmac_f32_e32 v211, v205, v205
	v_fmac_f32_e32 v210, v206, v206
	v_fmac_f32_e32 v211, v207, v207
	v_lshlrev_b32_e32 v200, 16, v72
	v_and_b32_e32 v201, 0xffff0000, v72
	v_lshlrev_b32_e32 v202, 16, v73
	v_and_b32_e32 v203, 0xffff0000, v73
	v_fmac_f32_e32 v208, v200, v200
	v_fmac_f32_e32 v209, v201, v201
	v_fmac_f32_e32 v208, v202, v202
	v_fmac_f32_e32 v209, v203, v203
	v_lshlrev_b32_e32 v204, 16, v104
	v_and_b32_e32 v205, 0xffff0000, v104
	v_lshlrev_b32_e32 v206, 16, v105
	v_and_b32_e32 v207, 0xffff0000, v105
	v_fmac_f32_e32 v210, v204, v204
	v_fmac_f32_e32 v211, v205, v205
	v_fmac_f32_e32 v210, v206, v206
; __device__ __forceinline__ float bf_lo(unsigned w) { return __uint_as_float(w << 16); }
; __device__ __forceinline__ float bf_hi(unsigned w) { return __uint_as_float(w & 0xffff0000u); }
; __global__ void __launch_bounds__(NWAVES * 64, 2) mk_fwd(Args args) {
;     ...
;                 float sy = 0.f;
; #pragma unroll
;                 for (int j = 0; j < 8; ++j) { const float a = bf_lo(yw[q][j].x), b = bf_hi(yw[q][j].x), c2 = bf_lo(yw[q][j].y), d = bf_hi(yw[q][j].y); sy += (a * a + b * b) + (c2 * c2 + d * d); }
;                 const float rsy = __builtin_amdgcn_rsqf(wave_sum(sy) * (1.f / DM) + EPS);
; #pragma unroll
;                 for (int j = 0; j < 8; ++j) { const int col = 4 * F.lane + 256 * j;
;                     const f32x4 y4 = (f32x4){bf_lo(yw[q][j].x), bf_hi(yw[q][j].x), bf_lo(yw[q][j].y), bf_hi(yw[q][j].y)};
;                     *(f32x4*)(args.out + (size_t)row * DM + col) = v[q][j] + PA[j] * (y4 * rsy); }
	v_fmac_f32_e32 v211, v207, v207
	v_lshlrev_b32_e32 v200, 16, v74
	v_and_b32_e32 v201, 0xffff0000, v74
	v_lshlrev_b32_e32 v202, 16, v75
	v_and_b32_e32 v203, 0xffff0000, v75
	v_fmac_f32_e32 v208, v200, v200
	v_fmac_f32_e32 v209, v201, v201
	v_fmac_f32_e32 v208, v202, v202
	v_fmac_f32_e32 v209, v203, v203
	v_lshlrev_b32_e32 v204, 16, v106
	v_and_b32_e32 v205, 0xffff0000, v106
	v_lshlrev_b32_e32 v206, 16, v107
	v_and_b32_e32 v207, 0xffff0000, v107
	v_fmac_f32_e32 v210, v204, v204
	v_fmac_f32_e32 v211, v205, v205
	v_fmac_f32_e32 v210, v206, v206
	v_fmac_f32_e32 v211, v207, v207
	v_lshlrev_b32_e32 v200, 16, v76
	v_and_b32_e32 v201, 0xffff0000, v76
	v_lshlrev_b32_e32 v202, 16, v77
	v_and_b32_e32 v203, 0xffff0000, v77
	v_fmac_f32_e32 v208, v200, v200
	v_fmac_f32_e32 v209, v201, v201
	v_fmac_f32_e32 v208, v202, v202
	v_fmac_f32_e32 v209, v203, v203
	v_lshlrev_b32_e32 v204, 16, v108
	v_and_b32_e32 v205, 0xffff0000, v108
	v_lshlrev_b32_e32 v206, 16, v109
	v_and_b32_e32 v207, 0xffff0000, v109
	v_fmac_f32_e32 v210, v204, v204
	v_fmac_f32_e32 v211, v205, v205
	v_fmac_f32_e32 v210, v206, v206
	v_fmac_f32_e32 v211, v207, v207
	v_lshlrev_b32_e32 v200, 16, v78
	v_and_b32_e32 v201, 0xffff0000, v78
	v_lshlrev_b32_e32 v202, 16, v79
	v_and_b32_e32 v203, 0xffff0000, v79
	v_fmac_f32_e32 v208, v200, v200
	v_fmac_f32_e32 v209, v201, v201
	v_fmac_f32_e32 v208, v202, v202
	v_fmac_f32_e32 v209, v203, v203
	v_lshlrev_b32_e32 v204, 16, v110
	v_and_b32_e32 v205, 0xffff0000, v110
	v_lshlrev_b32_e32 v206, 16, v111
	v_and_b32_e32 v207, 0xffff0000, v111
	v_fmac_f32_e32 v210, v204, v204
	v_fmac_f32_e32 v211, v205, v205
	v_fmac_f32_e32 v210, v206, v206
	v_fmac_f32_e32 v211, v207, v207
	v_add_f32_e32 v208, v208, v209
	v_add_f32_e32 v210, v210, v211
	s_nop 0
	v_add_f32_dpp v212, v208, v208 quad_perm:[1,0,3,2] row_mask:0xf bank_mask:0xf
	v_add_f32_dpp v213, v210, v210 quad_perm:[1,0,3,2] row_mask:0xf bank_mask:0xf
	s_nop 0
	v_add_f32_dpp v212, v212, v212 quad_perm:[2,3,0,1] row_mask:0xf bank_mask:0xf
	v_add_f32_dpp v213, v213, v213 quad_perm:[2,3,0,1] row_mask:0xf bank_mask:0xf
	s_nop 0
	v_add_f32_dpp v212, v212, v212 row_half_mirror row_mask:0xf bank_mask:0xf
	v_add_f32_dpp v213, v213, v213 row_half_mirror row_mask:0xf bank_mask:0xf
	s_nop 0
	v_add_f32_dpp v212, v212, v212 row_mirror row_mask:0xf bank_mask:0xf
	v_add_f32_dpp v213, v213, v213 row_mirror row_mask:0xf bank_mask:0xf
	s_nop 0
	v_readlane_b32 s4, v212, 0
	v_readlane_b32 s5, v212, 16
	v_readlane_b32 s6, v212, 32
	v_readlane_b32 s7, v212, 48
	v_readlane_b32 s24, v213, 0
	v_readlane_b32 s25, v213, 16
	v_readlane_b32 s26, v213, 32
	v_readlane_b32 s27, v213, 48
	s_nop 1
	v_mov_b32_e32 v214, s4
	v_mov_b32_e32 v215, s24
	v_add_f32_e32 v214, s5, v214
	v_add_f32_e32 v215, s25, v215
	v_add_f32_e32 v214, s6, v214
	v_add_f32_e32 v215, s26, v215
	v_add_f32_e32 v214, s7, v214
	v_add_f32_e32 v215, s27, v215
	v_fmamk_f32 v214, v214, 0x3a000000, v195
	v_fmamk_f32 v215, v215, 0x3a000000, v195
	v_rsq_f32_e32 v214, v214
	v_rsq_f32_e32 v215, v215
	s_nop 0
	v_lshlrev_b32_e32 v200, 16, v64
	v_and_b32_e32 v201, 0xffff0000, v64
	v_lshlrev_b32_e32 v202, 16, v65
	v_and_b32_e32 v203, 0xffff0000, v65
	v_lshlrev_b32_e32 v204, 16, v96
	v_and_b32_e32 v205, 0xffff0000, v96
	v_lshlrev_b32_e32 v206, 16, v97
	v_and_b32_e32 v207, 0xffff0000, v97
	v_mul_f32_e32 v200, v214, v200
	v_mul_f32_e32 v201, v214, v201
	v_mul_f32_e32 v202, v214, v202
	v_mul_f32_e32 v203, v214, v203
	v_mul_f32_e32 v204, v215, v204
	v_mul_f32_e32 v205, v215, v205
	v_mul_f32_e32 v206, v215, v206
	v_mul_f32_e32 v207, v215, v207
	v_fmac_f32_e32 v0, v128, v200
	v_fmac_f32_e32 v1, v129, v201
	v_fmac_f32_e32 v2, v130, v202
	v_fmac_f32_e32 v3, v131, v203
	v_fmac_f32_e32 v0, v160, v204
	v_fmac_f32_e32 v1, v161, v205
	v_fmac_f32_e32 v2, v162, v206
	v_fmac_f32_e32 v3, v163, v207
	global_store_dwordx4 v192, v[0:3], s[18:19] offset:0
	v_lshlrev_b32_e32 v200, 16, v66
	v_and_b32_e32 v201, 0xffff0000, v66
	v_lshlrev_b32_e32 v202, 16, v67
	v_and_b32_e32 v203, 0xffff0000, v67
	v_lshlrev_b32_e32 v204, 16, v98
	v_and_b32_e32 v205, 0xffff0000, v98
	v_lshlrev_b32_e32 v206, 16, v99
	v_and_b32_e32 v207, 0xffff0000, v99
	v_mul_f32_e32 v200, v214, v200
	v_mul_f32_e32 v201, v214, v201
	v_mul_f32_e32 v202, v214, v202
	v_mul_f32_e32 v203, v214, v203
	v_mul_f32_e32 v204, v215, v204
	v_mul_f32_e32 v205, v215, v205
	v_mul_f32_e32 v206, v215, v206
	v_mul_f32_e32 v207, v215, v207
	v_fmac_f32_e32 v4, v132, v200
	v_fmac_f32_e32 v5, v133, v201
	v_fmac_f32_e32 v6, v134, v202
	v_fmac_f32_e32 v7, v135, v203
	v_fmac_f32_e32 v4, v164, v204
	v_fmac_f32_e32 v5, v165, v205
	v_fmac_f32_e32 v6, v166, v206
	v_fmac_f32_e32 v7, v167, v207
	global_store_dwordx4 v192, v[4:7], s[18:19] offset:1024
	v_lshlrev_b32_e32 v200, 16, v68
	v_and_b32_e32 v201, 0xffff0000, v68
	v_lshlrev_b32_e32 v202, 16, v69
	v_and_b32_e32 v203, 0xffff0000, v69
	v_lshlrev_b32_e32 v204, 16, v100
	v_and_b32_e32 v205, 0xffff0000, v100
	v_lshlrev_b32_e32 v206, 16, v101
	v_and_b32_e32 v207, 0xffff0000, v101
	v_mul_f32_e32 v200, v214, v200
	v_mul_f32_e32 v201, v214, v201
	v_mul_f32_e32 v202, v214, v202
	v_mul_f32_e32 v203, v214, v203
	v_mul_f32_e32 v204, v215, v204
	v_mul_f32_e32 v205, v215, v205
	v_mul_f32_e32 v206, v215, v206
	v_mul_f32_e32 v207, v215, v207
	v_fmac_f32_e32 v8, v136, v200
	v_fmac_f32_e32 v9, v137, v201
	v_fmac_f32_e32 v10, v138, v202
	v_fmac_f32_e32 v11, v139, v203
	v_fmac_f32_e32 v8, v168, v204
	v_fmac_f32_e32 v9, v169, v205
	v_fmac_f32_e32 v10, v170, v206
	v_fmac_f32_e32 v11, v171, v207
	global_store_dwordx4 v192, v[8:11], s[18:19] offset:2048
	v_lshlrev_b32_e32 v200, 16, v70
	v_and_b32_e32 v201, 0xffff0000, v70
	v_lshlrev_b32_e32 v202, 16, v71
; __device__ __forceinline__ float bf_lo(unsigned w) { return __uint_as_float(w << 16); }
; __device__ __forceinline__ float bf_hi(unsigned w) { return __uint_as_float(w & 0xffff0000u); }
; __global__ void __launch_bounds__(NWAVES * 64, 2) mk_fwd(Args args) {
;     ...
; #pragma unroll
;                 for (int j = 0; j < 8; ++j) { const int col = 4 * F.lane + 256 * j;
;                     const f32x4 y4 = (f32x4){bf_lo(yw[q][j].x), bf_hi(yw[q][j].x), bf_lo(yw[q][j].y), bf_hi(yw[q][j].y)};
;                     *(f32x4*)(args.out + (size_t)row * DM + col) = v[q][j] + PA[j] * (y4 * rsy); }
	v_and_b32_e32 v203, 0xffff0000, v71
	v_lshlrev_b32_e32 v204, 16, v102
	v_and_b32_e32 v205, 0xffff0000, v102
	v_lshlrev_b32_e32 v206, 16, v103
	v_and_b32_e32 v207, 0xffff0000, v103
	v_mul_f32_e32 v200, v214, v200
	v_mul_f32_e32 v201, v214, v201
	v_mul_f32_e32 v202, v214, v202
	v_mul_f32_e32 v203, v214, v203
	v_mul_f32_e32 v204, v215, v204
	v_mul_f32_e32 v205, v215, v205
	v_mul_f32_e32 v206, v215, v206
	v_mul_f32_e32 v207, v215, v207
	v_fmac_f32_e32 v12, v140, v200
	v_fmac_f32_e32 v13, v141, v201
	v_fmac_f32_e32 v14, v142, v202
	v_fmac_f32_e32 v15, v143, v203
	v_fmac_f32_e32 v12, v172, v204
	v_fmac_f32_e32 v13, v173, v205
	v_fmac_f32_e32 v14, v174, v206
	v_fmac_f32_e32 v15, v175, v207
	global_store_dwordx4 v192, v[12:15], s[18:19] offset:3072
	v_lshlrev_b32_e32 v200, 16, v72
	v_and_b32_e32 v201, 0xffff0000, v72
	v_lshlrev_b32_e32 v202, 16, v73
	v_and_b32_e32 v203, 0xffff0000, v73
	v_lshlrev_b32_e32 v204, 16, v104
	v_and_b32_e32 v205, 0xffff0000, v104
	v_lshlrev_b32_e32 v206, 16, v105
	v_and_b32_e32 v207, 0xffff0000, v105
	v_mul_f32_e32 v200, v214, v200
	v_mul_f32_e32 v201, v214, v201
	v_mul_f32_e32 v202, v214, v202
	v_mul_f32_e32 v203, v214, v203
	v_mul_f32_e32 v204, v215, v204
	v_mul_f32_e32 v205, v215, v205
	v_mul_f32_e32 v206, v215, v206
	v_mul_f32_e32 v207, v215, v207
	v_fmac_f32_e32 v16, v144, v200
	v_fmac_f32_e32 v17, v145, v201
	v_fmac_f32_e32 v18, v146, v202
	v_fmac_f32_e32 v19, v147, v203
	v_fmac_f32_e32 v16, v176, v204
	v_fmac_f32_e32 v17, v177, v205
	v_fmac_f32_e32 v18, v178, v206
	v_fmac_f32_e32 v19, v179, v207
	global_store_dwordx4 v193, v[16:19], s[18:19] offset:0
	v_lshlrev_b32_e32 v200, 16, v74
	v_and_b32_e32 v201, 0xffff0000, v74
	v_lshlrev_b32_e32 v202, 16, v75
	v_and_b32_e32 v203, 0xffff0000, v75
	v_lshlrev_b32_e32 v204, 16, v106
	v_and_b32_e32 v205, 0xffff0000, v106
	v_lshlrev_b32_e32 v206, 16, v107
	v_and_b32_e32 v207, 0xffff0000, v107
	v_mul_f32_e32 v200, v214, v200
	v_mul_f32_e32 v201, v214, v201
	v_mul_f32_e32 v202, v214, v202
	v_mul_f32_e32 v203, v214, v203
	v_mul_f32_e32 v204, v215, v204
	v_mul_f32_e32 v205, v215, v205
	v_mul_f32_e32 v206, v215, v206
	v_mul_f32_e32 v207, v215, v207
	v_fmac_f32_e32 v20, v148, v200
	v_fmac_f32_e32 v21, v149, v201
	v_fmac_f32_e32 v22, v150, v202
	v_fmac_f32_e32 v23, v151, v203
	v_fmac_f32_e32 v20, v180, v204
	v_fmac_f32_e32 v21, v181, v205
	v_fmac_f32_e32 v22, v182, v206
	v_fmac_f32_e32 v23, v183, v207
	global_store_dwordx4 v193, v[20:23], s[18:19] offset:1024
	v_lshlrev_b32_e32 v200, 16, v76
	v_and_b32_e32 v201, 0xffff0000, v76
	v_lshlrev_b32_e32 v202, 16, v77
	v_and_b32_e32 v203, 0xffff0000, v77
	v_lshlrev_b32_e32 v204, 16, v108
	v_and_b32_e32 v205, 0xffff0000, v108
	v_lshlrev_b32_e32 v206, 16, v109
	v_and_b32_e32 v207, 0xffff0000, v109
	v_mul_f32_e32 v200, v214, v200
	v_mul_f32_e32 v201, v214, v201
	v_mul_f32_e32 v202, v214, v202
	v_mul_f32_e32 v203, v214, v203
	v_mul_f32_e32 v204, v215, v204
	v_mul_f32_e32 v205, v215, v205
	v_mul_f32_e32 v206, v215, v206
	v_mul_f32_e32 v207, v215, v207
	v_fmac_f32_e32 v24, v152, v200
	v_fmac_f32_e32 v25, v153, v201
	v_fmac_f32_e32 v26, v154, v202
	v_fmac_f32_e32 v27, v155, v203
	v_fmac_f32_e32 v24, v184, v204
	v_fmac_f32_e32 v25, v185, v205
	v_fmac_f32_e32 v26, v186, v206
	v_fmac_f32_e32 v27, v187, v207
	global_store_dwordx4 v193, v[24:27], s[18:19] offset:2048
	v_lshlrev_b32_e32 v200, 16, v78
	v_and_b32_e32 v201, 0xffff0000, v78
	v_lshlrev_b32_e32 v202, 16, v79
	v_and_b32_e32 v203, 0xffff0000, v79
	v_lshlrev_b32_e32 v204, 16, v110
	v_and_b32_e32 v205, 0xffff0000, v110
	v_lshlrev_b32_e32 v206, 16, v111
	v_and_b32_e32 v207, 0xffff0000, v111
	v_mul_f32_e32 v200, v214, v200
	v_mul_f32_e32 v201, v214, v201
	v_mul_f32_e32 v202, v214, v202
	v_mul_f32_e32 v203, v214, v203
	v_mul_f32_e32 v204, v215, v204
	v_mul_f32_e32 v205, v215, v205
	v_mul_f32_e32 v206, v215, v206
	v_mul_f32_e32 v207, v215, v207
	v_fmac_f32_e32 v28, v156, v200
	v_fmac_f32_e32 v29, v157, v201
	v_fmac_f32_e32 v30, v158, v202
	v_fmac_f32_e32 v31, v159, v203
	v_fmac_f32_e32 v28, v188, v204
	v_fmac_f32_e32 v29, v189, v205
	v_fmac_f32_e32 v30, v190, v206
	v_fmac_f32_e32 v31, v191, v207
	global_store_dwordx4 v193, v[28:31], s[18:19] offset:3072
	s_add_u32 s18, s18, 0x2000
	s_addc_u32 s19, s19, 0
	s_waitcnt vmcnt(8)
; __device__ __forceinline__ float bf_lo(unsigned w) { return __uint_as_float(w << 16); }
; __device__ __forceinline__ float bf_hi(unsigned w) { return __uint_as_float(w & 0xffff0000u); }
; __global__ void __launch_bounds__(NWAVES * 64, 2) mk_fwd(Args args) {
;     ...
;                 float sy = 0.f;
; #pragma unroll
;                 for (int j = 0; j < 8; ++j) { const float a = bf_lo(yw[q][j].x), b = bf_hi(yw[q][j].x), c2 = bf_lo(yw[q][j].y), d = bf_hi(yw[q][j].y); sy += (a * a + b * b) + (c2 * c2 + d * d); }
;                 const float rsy = __builtin_amdgcn_rsqf(wave_sum(sy) * (1.f / DM) + EPS);
	v_lshlrev_b32_e32 v200, 16, v80
	v_and_b32_e32 v201, 0xffff0000, v80
	v_lshlrev_b32_e32 v202, 16, v81
	v_and_b32_e32 v203, 0xffff0000, v81
	v_mul_f32_e32 v208, v200, v200
	v_mul_f32_e32 v209, v201, v201
	v_fmac_f32_e32 v208, v202, v202
	v_fmac_f32_e32 v209, v203, v203
	v_lshlrev_b32_e32 v204, 16, v112
	v_and_b32_e32 v205, 0xffff0000, v112
	v_lshlrev_b32_e32 v206, 16, v113
	v_and_b32_e32 v207, 0xffff0000, v113
	v_mul_f32_e32 v210, v204, v204
	v_mul_f32_e32 v211, v205, v205
	v_fmac_f32_e32 v210, v206, v206
	v_fmac_f32_e32 v211, v207, v207
	v_lshlrev_b32_e32 v200, 16, v82
	v_and_b32_e32 v201, 0xffff0000, v82
	v_lshlrev_b32_e32 v202, 16, v83
	v_and_b32_e32 v203, 0xffff0000, v83
	v_fmac_f32_e32 v208, v200, v200
	v_fmac_f32_e32 v209, v201, v201
	v_fmac_f32_e32 v208, v202, v202
	v_fmac_f32_e32 v209, v203, v203
	v_lshlrev_b32_e32 v204, 16, v114
	v_and_b32_e32 v205, 0xffff0000, v114
	v_lshlrev_b32_e32 v206, 16, v115
	v_and_b32_e32 v207, 0xffff0000, v115
	v_fmac_f32_e32 v210, v204, v204
	v_fmac_f32_e32 v211, v205, v205
	v_fmac_f32_e32 v210, v206, v206
	v_fmac_f32_e32 v211, v207, v207
	v_lshlrev_b32_e32 v200, 16, v84
	v_and_b32_e32 v201, 0xffff0000, v84
	v_lshlrev_b32_e32 v202, 16, v85
	v_and_b32_e32 v203, 0xffff0000, v85
	v_fmac_f32_e32 v208, v200, v200
	v_fmac_f32_e32 v209, v201, v201
	v_fmac_f32_e32 v208, v202, v202
	v_fmac_f32_e32 v209, v203, v203
	v_lshlrev_b32_e32 v204, 16, v116
	v_and_b32_e32 v205, 0xffff0000, v116
	v_lshlrev_b32_e32 v206, 16, v117
	v_and_b32_e32 v207, 0xffff0000, v117
	v_fmac_f32_e32 v210, v204, v204
	v_fmac_f32_e32 v211, v205, v205
	v_fmac_f32_e32 v210, v206, v206
	v_fmac_f32_e32 v211, v207, v207
	v_lshlrev_b32_e32 v200, 16, v86
	v_and_b32_e32 v201, 0xffff0000, v86
	v_lshlrev_b32_e32 v202, 16, v87
	v_and_b32_e32 v203, 0xffff0000, v87
	v_fmac_f32_e32 v208, v200, v200
	v_fmac_f32_e32 v209, v201, v201
	v_fmac_f32_e32 v208, v202, v202
	v_fmac_f32_e32 v209, v203, v203
	v_lshlrev_b32_e32 v204, 16, v118
	v_and_b32_e32 v205, 0xffff0000, v118
	v_lshlrev_b32_e32 v206, 16, v119
	v_and_b32_e32 v207, 0xffff0000, v119
	v_fmac_f32_e32 v210, v204, v204
	v_fmac_f32_e32 v211, v205, v205
	v_fmac_f32_e32 v210, v206, v206
	v_fmac_f32_e32 v211, v207, v207
	v_lshlrev_b32_e32 v200, 16, v88
	v_and_b32_e32 v201, 0xffff0000, v88
	v_lshlrev_b32_e32 v202, 16, v89
	v_and_b32_e32 v203, 0xffff0000, v89
	v_fmac_f32_e32 v208, v200, v200
	v_fmac_f32_e32 v209, v201, v201
	v_fmac_f32_e32 v208, v202, v202
	v_fmac_f32_e32 v209, v203, v203
	v_lshlrev_b32_e32 v204, 16, v120
	v_and_b32_e32 v205, 0xffff0000, v120
	v_lshlrev_b32_e32 v206, 16, v121
	v_and_b32_e32 v207, 0xffff0000, v121
	v_fmac_f32_e32 v210, v204, v204
	v_fmac_f32_e32 v211, v205, v205
	v_fmac_f32_e32 v210, v206, v206
	v_fmac_f32_e32 v211, v207, v207
	v_lshlrev_b32_e32 v200, 16, v90
	v_and_b32_e32 v201, 0xffff0000, v90
	v_lshlrev_b32_e32 v202, 16, v91
	v_and_b32_e32 v203, 0xffff0000, v91
	v_fmac_f32_e32 v208, v200, v200
	v_fmac_f32_e32 v209, v201, v201
	v_fmac_f32_e32 v208, v202, v202
	v_fmac_f32_e32 v209, v203, v203
	v_lshlrev_b32_e32 v204, 16, v122
	v_and_b32_e32 v205, 0xffff0000, v122
	v_lshlrev_b32_e32 v206, 16, v123
	v_and_b32_e32 v207, 0xffff0000, v123
	v_fmac_f32_e32 v210, v204, v204
	v_fmac_f32_e32 v211, v205, v205
	v_fmac_f32_e32 v210, v206, v206
	v_fmac_f32_e32 v211, v207, v207
	v_lshlrev_b32_e32 v200, 16, v92
	v_and_b32_e32 v201, 0xffff0000, v92
	v_lshlrev_b32_e32 v202, 16, v93
	v_and_b32_e32 v203, 0xffff0000, v93
	v_fmac_f32_e32 v208, v200, v200
	v_fmac_f32_e32 v209, v201, v201
	v_fmac_f32_e32 v208, v202, v202
	v_fmac_f32_e32 v209, v203, v203
	v_lshlrev_b32_e32 v204, 16, v124
	v_and_b32_e32 v205, 0xffff0000, v124
	v_lshlrev_b32_e32 v206, 16, v125
	v_and_b32_e32 v207, 0xffff0000, v125
	v_fmac_f32_e32 v210, v204, v204
	v_fmac_f32_e32 v211, v205, v205
	v_fmac_f32_e32 v210, v206, v206
	v_fmac_f32_e32 v211, v207, v207
	v_lshlrev_b32_e32 v200, 16, v94
	v_and_b32_e32 v201, 0xffff0000, v94
	v_lshlrev_b32_e32 v202, 16, v95
	v_and_b32_e32 v203, 0xffff0000, v95
	v_fmac_f32_e32 v208, v200, v200
	v_fmac_f32_e32 v209, v201, v201
	v_fmac_f32_e32 v208, v202, v202
	v_fmac_f32_e32 v209, v203, v203
	v_lshlrev_b32_e32 v204, 16, v126
	v_and_b32_e32 v205, 0xffff0000, v126
	v_lshlrev_b32_e32 v206, 16, v127
	v_and_b32_e32 v207, 0xffff0000, v127
	v_fmac_f32_e32 v210, v204, v204
	v_fmac_f32_e32 v211, v205, v205
	v_fmac_f32_e32 v210, v206, v206
	v_fmac_f32_e32 v211, v207, v207
	v_add_f32_e32 v208, v208, v209
	v_add_f32_e32 v210, v210, v211
	s_nop 0
	v_add_f32_dpp v212, v208, v208 quad_perm:[1,0,3,2] row_mask:0xf bank_mask:0xf
	v_add_f32_dpp v213, v210, v210 quad_perm:[1,0,3,2] row_mask:0xf bank_mask:0xf
	s_nop 0
	v_add_f32_dpp v212, v212, v212 quad_perm:[2,3,0,1] row_mask:0xf bank_mask:0xf
	v_add_f32_dpp v213, v213, v213 quad_perm:[2,3,0,1] row_mask:0xf bank_mask:0xf
	s_nop 0
	v_add_f32_dpp v212, v212, v212 row_half_mirror row_mask:0xf bank_mask:0xf
	v_add_f32_dpp v213, v213, v213 row_half_mirror row_mask:0xf bank_mask:0xf
	s_nop 0
	v_add_f32_dpp v212, v212, v212 row_mirror row_mask:0xf bank_mask:0xf
	v_add_f32_dpp v213, v213, v213 row_mirror row_mask:0xf bank_mask:0xf
	s_nop 0
	v_readlane_b32 s4, v212, 0
	v_readlane_b32 s5, v212, 16
	v_readlane_b32 s6, v212, 32
	v_readlane_b32 s7, v212, 48
	v_readlane_b32 s24, v213, 0
	v_readlane_b32 s25, v213, 16
	v_readlane_b32 s26, v213, 32
	v_readlane_b32 s27, v213, 48
	s_nop 1
	v_mov_b32_e32 v214, s4
	v_mov_b32_e32 v215, s24
	v_add_f32_e32 v214, s5, v214
	v_add_f32_e32 v215, s25, v215
	v_add_f32_e32 v214, s6, v214
	v_add_f32_e32 v215, s26, v215
	v_add_f32_e32 v214, s7, v214
	v_add_f32_e32 v215, s27, v215
	v_fmamk_f32 v214, v214, 0x3a000000, v195
	v_fmamk_f32 v215, v215, 0x3a000000, v195
; __device__ __forceinline__ float bf_lo(unsigned w) { return __uint_as_float(w << 16); }
; __device__ __forceinline__ float bf_hi(unsigned w) { return __uint_as_float(w & 0xffff0000u); }
; __global__ void __launch_bounds__(NWAVES * 64, 2) mk_fwd(Args args) {
;     ...
;                 const float rsy = __builtin_amdgcn_rsqf(wave_sum(sy) * (1.f / DM) + EPS);
; #pragma unroll
;                 for (int j = 0; j < 8; ++j) { const int col = 4 * F.lane + 256 * j;
;                     const f32x4 y4 = (f32x4){bf_lo(yw[q][j].x), bf_hi(yw[q][j].x), bf_lo(yw[q][j].y), bf_hi(yw[q][j].y)};
;                     *(f32x4*)(args.out + (size_t)row * DM + col) = v[q][j] + PA[j] * (y4 * rsy); }
	v_rsq_f32_e32 v214, v214
	v_rsq_f32_e32 v215, v215
	s_nop 0
	v_lshlrev_b32_e32 v200, 16, v80
	v_and_b32_e32 v201, 0xffff0000, v80
	v_lshlrev_b32_e32 v202, 16, v81
	v_and_b32_e32 v203, 0xffff0000, v81
	v_lshlrev_b32_e32 v204, 16, v112
	v_and_b32_e32 v205, 0xffff0000, v112
	v_lshlrev_b32_e32 v206, 16, v113
	v_and_b32_e32 v207, 0xffff0000, v113
	v_mul_f32_e32 v200, v214, v200
	v_mul_f32_e32 v201, v214, v201
	v_mul_f32_e32 v202, v214, v202
	v_mul_f32_e32 v203, v214, v203
	v_mul_f32_e32 v204, v215, v204
	v_mul_f32_e32 v205, v215, v205
	v_mul_f32_e32 v206, v215, v206
	v_mul_f32_e32 v207, v215, v207
	v_fmac_f32_e32 v32, v128, v200
	v_fmac_f32_e32 v33, v129, v201
	v_fmac_f32_e32 v34, v130, v202
	v_fmac_f32_e32 v35, v131, v203
	v_fmac_f32_e32 v32, v160, v204
	v_fmac_f32_e32 v33, v161, v205
	v_fmac_f32_e32 v34, v162, v206
	v_fmac_f32_e32 v35, v163, v207
	global_store_dwordx4 v192, v[32:35], s[18:19] offset:0
	v_lshlrev_b32_e32 v200, 16, v82
	v_and_b32_e32 v201, 0xffff0000, v82
	v_lshlrev_b32_e32 v202, 16, v83
	v_and_b32_e32 v203, 0xffff0000, v83
	v_lshlrev_b32_e32 v204, 16, v114
	v_and_b32_e32 v205, 0xffff0000, v114
	v_lshlrev_b32_e32 v206, 16, v115
	v_and_b32_e32 v207, 0xffff0000, v115
	v_mul_f32_e32 v200, v214, v200
	v_mul_f32_e32 v201, v214, v201
	v_mul_f32_e32 v202, v214, v202
	v_mul_f32_e32 v203, v214, v203
	v_mul_f32_e32 v204, v215, v204
	v_mul_f32_e32 v205, v215, v205
	v_mul_f32_e32 v206, v215, v206
	v_mul_f32_e32 v207, v215, v207
	v_fmac_f32_e32 v36, v132, v200
	v_fmac_f32_e32 v37, v133, v201
	v_fmac_f32_e32 v38, v134, v202
	v_fmac_f32_e32 v39, v135, v203
	v_fmac_f32_e32 v36, v164, v204
	v_fmac_f32_e32 v37, v165, v205
	v_fmac_f32_e32 v38, v166, v206
	v_fmac_f32_e32 v39, v167, v207
	global_store_dwordx4 v192, v[36:39], s[18:19] offset:1024
	v_lshlrev_b32_e32 v200, 16, v84
	v_and_b32_e32 v201, 0xffff0000, v84
	v_lshlrev_b32_e32 v202, 16, v85
	v_and_b32_e32 v203, 0xffff0000, v85
	v_lshlrev_b32_e32 v204, 16, v116
	v_and_b32_e32 v205, 0xffff0000, v116
	v_lshlrev_b32_e32 v206, 16, v117
	v_and_b32_e32 v207, 0xffff0000, v117
	v_mul_f32_e32 v200, v214, v200
	v_mul_f32_e32 v201, v214, v201
	v_mul_f32_e32 v202, v214, v202
	v_mul_f32_e32 v203, v214, v203
	v_mul_f32_e32 v204, v215, v204
	v_mul_f32_e32 v205, v215, v205
	v_mul_f32_e32 v206, v215, v206
	v_mul_f32_e32 v207, v215, v207
	v_fmac_f32_e32 v40, v136, v200
	v_fmac_f32_e32 v41, v137, v201
	v_fmac_f32_e32 v42, v138, v202
	v_fmac_f32_e32 v43, v139, v203
	v_fmac_f32_e32 v40, v168, v204
	v_fmac_f32_e32 v41, v169, v205
	v_fmac_f32_e32 v42, v170, v206
	v_fmac_f32_e32 v43, v171, v207
	global_store_dwordx4 v192, v[40:43], s[18:19] offset:2048
	v_lshlrev_b32_e32 v200, 16, v86
	v_and_b32_e32 v201, 0xffff0000, v86
	v_lshlrev_b32_e32 v202, 16, v87
	v_and_b32_e32 v203, 0xffff0000, v87
	v_lshlrev_b32_e32 v204, 16, v118
	v_and_b32_e32 v205, 0xffff0000, v118
	v_lshlrev_b32_e32 v206, 16, v119
	v_and_b32_e32 v207, 0xffff0000, v119
	v_mul_f32_e32 v200, v214, v200
	v_mul_f32_e32 v201, v214, v201
	v_mul_f32_e32 v202, v214, v202
	v_mul_f32_e32 v203, v214, v203
	v_mul_f32_e32 v204, v215, v204
	v_mul_f32_e32 v205, v215, v205
	v_mul_f32_e32 v206, v215, v206
	v_mul_f32_e32 v207, v215, v207
	v_fmac_f32_e32 v44, v140, v200
	v_fmac_f32_e32 v45, v141, v201
	v_fmac_f32_e32 v46, v142, v202
	v_fmac_f32_e32 v47, v143, v203
	v_fmac_f32_e32 v44, v172, v204
	v_fmac_f32_e32 v45, v173, v205
	v_fmac_f32_e32 v46, v174, v206
	v_fmac_f32_e32 v47, v175, v207
	global_store_dwordx4 v192, v[44:47], s[18:19] offset:3072
	v_lshlrev_b32_e32 v200, 16, v88
	v_and_b32_e32 v201, 0xffff0000, v88
	v_lshlrev_b32_e32 v202, 16, v89
	v_and_b32_e32 v203, 0xffff0000, v89
	v_lshlrev_b32_e32 v204, 16, v120
	v_and_b32_e32 v205, 0xffff0000, v120
	v_lshlrev_b32_e32 v206, 16, v121
	v_and_b32_e32 v207, 0xffff0000, v121
	v_mul_f32_e32 v200, v214, v200
	v_mul_f32_e32 v201, v214, v201
	v_mul_f32_e32 v202, v214, v202
	v_mul_f32_e32 v203, v214, v203
	v_mul_f32_e32 v204, v215, v204
	v_mul_f32_e32 v205, v215, v205
	v_mul_f32_e32 v206, v215, v206
	v_mul_f32_e32 v207, v215, v207
	v_fmac_f32_e32 v48, v144, v200
	v_fmac_f32_e32 v49, v145, v201
	v_fmac_f32_e32 v50, v146, v202
	v_fmac_f32_e32 v51, v147, v203
	v_fmac_f32_e32 v48, v176, v204
	v_fmac_f32_e32 v49, v177, v205
	v_fmac_f32_e32 v50, v178, v206
	v_fmac_f32_e32 v51, v179, v207
	global_store_dwordx4 v193, v[48:51], s[18:19] offset:0
	v_lshlrev_b32_e32 v200, 16, v90
	v_and_b32_e32 v201, 0xffff0000, v90
	v_lshlrev_b32_e32 v202, 16, v91
	v_and_b32_e32 v203, 0xffff0000, v91
	v_lshlrev_b32_e32 v204, 16, v122
	v_and_b32_e32 v205, 0xffff0000, v122
	v_lshlrev_b32_e32 v206, 16, v123
	v_and_b32_e32 v207, 0xffff0000, v123
	v_mul_f32_e32 v200, v214, v200
	v_mul_f32_e32 v201, v214, v201
	v_mul_f32_e32 v202, v214, v202
	v_mul_f32_e32 v203, v214, v203
	v_mul_f32_e32 v204, v215, v204
	v_mul_f32_e32 v205, v215, v205
	v_mul_f32_e32 v206, v215, v206
	v_mul_f32_e32 v207, v215, v207
	v_fmac_f32_e32 v52, v148, v200
	v_fmac_f32_e32 v53, v149, v201
	v_fmac_f32_e32 v54, v150, v202
	v_fmac_f32_e32 v55, v151, v203
	v_fmac_f32_e32 v52, v180, v204
	v_fmac_f32_e32 v53, v181, v205
	v_fmac_f32_e32 v54, v182, v206
	v_fmac_f32_e32 v55, v183, v207
	global_store_dwordx4 v193, v[52:55], s[18:19] offset:1024
	v_lshlrev_b32_e32 v200, 16, v92
	v_and_b32_e32 v201, 0xffff0000, v92
	v_lshlrev_b32_e32 v202, 16, v93
	v_and_b32_e32 v203, 0xffff0000, v93
	v_lshlrev_b32_e32 v204, 16, v124
	v_and_b32_e32 v205, 0xffff0000, v124
	v_lshlrev_b32_e32 v206, 16, v125
	v_and_b32_e32 v207, 0xffff0000, v125
	v_mul_f32_e32 v200, v214, v200
	v_mul_f32_e32 v201, v214, v201
	v_mul_f32_e32 v202, v214, v202
	v_mul_f32_e32 v203, v214, v203
	v_mul_f32_e32 v204, v215, v204
	v_mul_f32_e32 v205, v215, v205
	v_mul_f32_e32 v206, v215, v206
	v_mul_f32_e32 v207, v215, v207
	v_fmac_f32_e32 v56, v152, v200
	v_fmac_f32_e32 v57, v153, v201
	v_fmac_f32_e32 v58, v154, v202
	v_fmac_f32_e32 v59, v155, v203
	v_fmac_f32_e32 v56, v184, v204
	v_fmac_f32_e32 v57, v185, v205
	v_fmac_f32_e32 v58, v186, v206
	v_fmac_f32_e32 v59, v187, v207
	global_store_dwordx4 v193, v[56:59], s[18:19] offset:2048
	v_lshlrev_b32_e32 v200, 16, v94
	v_and_b32_e32 v201, 0xffff0000, v94
	v_lshlrev_b32_e32 v202, 16, v95
	v_and_b32_e32 v203, 0xffff0000, v95
	v_lshlrev_b32_e32 v204, 16, v126
	v_and_b32_e32 v205, 0xffff0000, v126
	v_lshlrev_b32_e32 v206, 16, v127
	v_and_b32_e32 v207, 0xffff0000, v127
	v_mul_f32_e32 v200, v214, v200
	v_mul_f32_e32 v201, v214, v201
	v_mul_f32_e32 v202, v214, v202
	v_mul_f32_e32 v203, v214, v203
	v_mul_f32_e32 v204, v215, v204
	v_mul_f32_e32 v205, v215, v205
	v_mul_f32_e32 v206, v215, v206
	v_mul_f32_e32 v207, v215, v207
	v_fmac_f32_e32 v60, v156, v200
	v_fmac_f32_e32 v61, v157, v201
	v_fmac_f32_e32 v62, v158, v202
	v_fmac_f32_e32 v63, v159, v203
	v_fmac_f32_e32 v60, v188, v204
	v_fmac_f32_e32 v61, v189, v205
	v_fmac_f32_e32 v62, v190, v206
	v_fmac_f32_e32 v63, v191, v207
	global_store_dwordx4 v193, v[60:63], s[18:19] offset:3072
	s_add_u32 s18, s18, 0x2000
	s_addc_u32 s19, s19, 0
	s_branch .LBB0_1296
